# v7 + peeled first K-loop iteration with srcC=0 MFMAs in 9 GEMM loops; per-unit accumulator zeroing removed
# speedup vs baseline: 1.0057x; 1.0013x over previous
; #define PG8_STAGE(bufoff, gbase, voff) do { _Pragma("unroll") for (int _i = 0; _i < 2; ++_i) \
;         __builtin_amdgcn_global_load_lds((const unsigned*)((const char*)(gbase) + (voff)[_i]), (PG8_LAS unsigned*)(lds + (bufoff) + ldsw + _i * 8192), 16, 0, 0); } while (0)
; #define PG8_LDA(dst, b, h) do { _Pragma("unroll") for (int m = 0; m < 4; ++m) _Pragma("unroll") for (int k = 0; k < 2; ++k) dst[m][k] = *(const PG8_LAS bf16x8*)(lds + PG8_SA(b, h) + aoff + m * 2048 + k * 1024); } while (0)
; #define PG8_LDB(dst, b, h) do { _Pragma("unroll") for (int n = 0; n < 2; ++n) _Pragma("unroll") for (int k = 0; k < 2; ++k) dst[n][k] = *(const PG8_LAS bf16x8*)(lds + PG8_SB(b, h) + boff + n * 2048 + k * 1024); } while (0)
; #define PG8_MMA(ai, bj, At, Bt) do { __builtin_amdgcn_s_setprio(1); _Pragma("unroll") for (int m = 0; m < 4; ++m) _Pragma("unroll") for (int n = 0; n < 2; ++n) _Pragma("unroll") for (int k = 0; k < 2; ++k) \
;         acc[ai][bj][m][n] = __builtin_amdgcn_mfma_f32_16x16x32_bf16(Bt[n][k], At[m][k], acc[ai][bj][m][n], 0, 0, 0); __builtin_amdgcn_s_setprio(0); } while (0)
; #define PG8_WAIT_V(n) asm volatile("s_waitcnt vmcnt(" #n ")" ::: "memory")
; #define PG8_WAIT_L(n) asm volatile("s_waitcnt lgkmcnt(" #n ")" ::: "memory")
; template <class Epi>
; __device__ __forceinline__ void gemm_phase(PG8_LAS unsigned char* lds, PG8_LAS unsigned char* xl, const Gemm g, const Sched& S, const Epi& E, const int wid) {
;     ...
;             const char* a1 = cA + (size_t)(t + 1) * kstep + j1;
;             const char* a2 = last ? nA : cA + (size_t)(t + 2) * kstep + ja2; const char* b2 = last ? nB : cB + (size_t)(t + 2) * kstep + jb2;
;             const char* a3 = a2 + kstep; const char* b3 = b2 + kstep;
;             PG8_LDB(B0, 0, 0); PG8_LDB(B1, 0, 1); PG8_SCHED; PG8_LDA(At, 0, 0); PG8_STAGE(PG8_SA(1, 1), a1 + hstepA, voffA);
;             PG8_WAIT_V(8); PG8_WAIT_L(0); PG8_BAR; if (do0) { PG8_MMA(0, 0, At, B0); PG8_MMA(0, 1, At, B1); } PG8_BAR; PG8_SCHED;
;             PG8_LDA(At, 0, 1); PG8_STAGE(PG8_SB(0, 0), b2, voffB); PG8_STAGE(PG8_SB(0, 1), b2 + hstepB, voffB); PG8_STAGE(PG8_SA(0, 0), a2, voffA);
;     ...
;         for (int a = 0; a < 2; ++a)
; #pragma unroll
;             for (int b = 0; b < 2; ++b)
; #pragma unroll
;                 for (int m = 0; m < 4; ++m)
; #pragma unroll
;                     for (int n = 0; n < 2; ++n) acc[a][b][m][n] = (f32x4){0.f, 0.f, 0.f, 0.f};
.LBB0_219:
	s_ashr_i32 s21, s20, 31
	s_lshl_b64 s[8:9], s[20:21], 20
	s_add_u32 s30, s60, s8
	s_addc_u32 s31, s61, s9
	s_and_b64 s[8:9], s[40:41], exec
	s_cselect_b32 s8, s31, s51
	s_cselect_b32 s9, s30, s50
	s_ashr_i32 s13, s12, 31
	s_lshl_b64 s[10:11], s[12:13], 20
	s_add_u32 s48, s62, s10
	s_addc_u32 s49, s66, s11
	s_and_b64 s[10:11], s[40:41], exec
	s_cselect_b32 s10, s49, s53
	s_cselect_b32 s11, s48, s52
	s_add_u32 s13, s52, 0x100
	s_addc_u32 s21, s53, 0
	s_mov_b32 s43, -2
	s_cmp_lg_u32 s100, 1
	s_cbranch_scc1 .Ldefbar_skip_0
	s_mov_b32 s100, 0
	s_barrier
.Ldefbar_skip_0:
	v_add_u32_e32 v141, s22, v128
	v_add_u32_e32 v226, s22, v130
	v_add_u32_e32 v227, s22, v132
	v_add_u32_e32 v228, s22, v134
	v_add_u32_e32 v229, 0x10000, v142
	s_add_u32 s52, s50, 0x100
	s_addc_u32 s53, s51, 0
	s_add_i32 s54, 0, 0x10000
	s_cmp_eq_u32 s43, 28
	s_cselect_b32 s59, s8, s53
	s_cselect_b32 s58, s9, s52
	s_cselect_b32 s57, s10, s21
	s_cselect_b32 s56, s11, s13
	s_add_i32 s55, 0, 0x14000
	ds_read_b128 v[144:147], v229 offset:0
	ds_read_b128 v[148:151], v229 offset:1024
	ds_read_b128 v[152:155], v229 offset:2048
	ds_read_b128 v[156:159], v229 offset:3072
	ds_read_b128 v[160:163], v229 offset:16384
	ds_read_b128 v[164:167], v229 offset:17408
	ds_read_b128 v[168:171], v229 offset:18432
	ds_read_b128 v[172:175], v229 offset:19456
	s_add_i32 m0, s37, 0xc000
	ds_read_b128 v[176:179], v143
	ds_read_b128 v[180:183], v143 offset:1024
	ds_read_b128 v[184:187], v143 offset:2048
	ds_read_b128 v[188:191], v143 offset:3072
	ds_read_b128 v[210:213], v143 offset:4096
	ds_read_b128 v[214:217], v143 offset:5120
	ds_read_b128 v[218:221], v143 offset:6144
	ds_read_b128 v[222:225], v143 offset:7168
	global_load_lds_dwordx4 v136, s[50:51]
	s_add_i32 m0, s37, 0xe000
	s_nop 0
	global_load_lds_dwordx4 v138, s[50:51]
	s_waitcnt vmcnt(8)
	s_waitcnt lgkmcnt(0)
	s_setprio 1
	s_barrier
	v_mfma_f32_16x16x32_bf16 v[124:127], v[144:147], v[176:179], 0
	v_mfma_f32_16x16x32_bf16 v[120:123], v[152:155], v[176:179], 0
	v_mfma_f32_16x16x32_bf16 v[116:119], v[144:147], v[184:187], 0
	v_mfma_f32_16x16x32_bf16 v[108:111], v[152:155], v[184:187], 0
	v_mfma_f32_16x16x32_bf16 v[100:103], v[144:147], v[210:213], 0
	v_mfma_f32_16x16x32_bf16 v[92:95], v[152:155], v[210:213], 0
	v_mfma_f32_16x16x32_bf16 v[84:87], v[144:147], v[218:221], 0
	v_mfma_f32_16x16x32_bf16 v[76:79], v[152:155], v[218:221], 0
	v_mfma_f32_16x16x32_bf16 v[124:127], v[148:151], v[180:183], v[124:127]
	v_mfma_f32_16x16x32_bf16 v[120:123], v[156:159], v[180:183], v[120:123]
	v_mfma_f32_16x16x32_bf16 v[116:119], v[148:151], v[188:191], v[116:119]
	v_mfma_f32_16x16x32_bf16 v[108:111], v[156:159], v[188:191], v[108:111]
	v_mfma_f32_16x16x32_bf16 v[100:103], v[148:151], v[214:217], v[100:103]
	v_mfma_f32_16x16x32_bf16 v[92:95], v[156:159], v[214:217], v[92:95]
	v_mfma_f32_16x16x32_bf16 v[84:87], v[148:151], v[222:225], v[84:87]
	v_mfma_f32_16x16x32_bf16 v[76:79], v[156:159], v[222:225], v[76:79]
	s_setprio 0
	s_setprio 1
	v_mfma_f32_16x16x32_bf16 v[112:115], v[160:163], v[176:179], 0
	v_mfma_f32_16x16x32_bf16 v[104:107], v[168:171], v[176:179], 0
	v_mfma_f32_16x16x32_bf16 v[96:99], v[160:163], v[184:187], 0
	v_mfma_f32_16x16x32_bf16 v[88:91], v[168:171], v[184:187], 0
	v_mfma_f32_16x16x32_bf16 v[80:83], v[160:163], v[210:213], 0
	v_mfma_f32_16x16x32_bf16 v[72:75], v[168:171], v[210:213], 0
	v_mfma_f32_16x16x32_bf16 v[68:71], v[160:163], v[218:221], 0
	v_mfma_f32_16x16x32_bf16 v[64:67], v[168:171], v[218:221], 0
	v_mfma_f32_16x16x32_bf16 v[112:115], v[164:167], v[180:183], v[112:115]
	v_mfma_f32_16x16x32_bf16 v[104:107], v[172:175], v[180:183], v[104:107]
	v_mfma_f32_16x16x32_bf16 v[96:99], v[164:167], v[188:191], v[96:99]
	v_mfma_f32_16x16x32_bf16 v[88:91], v[172:175], v[188:191], v[88:91]
	v_mfma_f32_16x16x32_bf16 v[80:83], v[164:167], v[214:217], v[80:83]
	v_mfma_f32_16x16x32_bf16 v[72:75], v[172:175], v[214:217], v[72:75]
	v_mfma_f32_16x16x32_bf16 v[68:71], v[164:167], v[222:225], v[68:71]
	v_mfma_f32_16x16x32_bf16 v[64:67], v[172:175], v[222:225], v[64:67]
	s_barrier
	s_setprio 0
	s_add_i32 s50, s54, s29
	s_mov_b32 m0, s50
	ds_read_b128 v[176:179], v143 offset:16384
	ds_read_b128 v[180:183], v143 offset:17408
	ds_read_b128 v[184:187], v143 offset:18432
	ds_read_b128 v[188:191], v143 offset:19456
	ds_read_b128 v[210:213], v143 offset:20480
	ds_read_b128 v[214:217], v143 offset:21504
	ds_read_b128 v[218:221], v143 offset:22528
	ds_read_b128 v[222:225], v143 offset:23552
	global_load_lds_dwordx4 v132, s[56:57]
	s_add_i32 m0, s50, 0x2000
	s_add_u32 s50, s56, 0x80000
	s_addc_u32 s51, s57, 0
	s_add_i32 s54, s55, s29
	global_load_lds_dwordx4 v128, s[56:57]
	s_mov_b32 m0, s54
	s_nop 0
	global_load_lds_dwordx4 v132, s[50:51]
	s_add_i32 m0, s54, 0x2000
	s_nop 0
	global_load_lds_dwordx4 v128, s[50:51]
	s_mov_b32 m0, s37
	s_nop 0
	global_load_lds_dwordx4 v134, s[58:59]
	s_mov_b32 m0, s68
	s_nop 0
	global_load_lds_dwordx4 v130, s[58:59]
	s_waitcnt vmcnt(8)
	s_waitcnt lgkmcnt(0)
	s_setprio 1
	s_barrier
; #define PG8_STAGE(bufoff, gbase, voff) do { _Pragma("unroll") for (int _i = 0; _i < 2; ++_i) \
;         __builtin_amdgcn_global_load_lds((const unsigned*)((const char*)(gbase) + (voff)[_i]), (PG8_LAS unsigned*)(lds + (bufoff) + ldsw + _i * 8192), 16, 0, 0); } while (0)
; #define PG8_LDA(dst, b, h) do { _Pragma("unroll") for (int m = 0; m < 4; ++m) _Pragma("unroll") for (int k = 0; k < 2; ++k) dst[m][k] = *(const PG8_LAS bf16x8*)(lds + PG8_SA(b, h) + aoff + m * 2048 + k * 1024); } while (0)
; #define PG8_LDB(dst, b, h) do { _Pragma("unroll") for (int n = 0; n < 2; ++n) _Pragma("unroll") for (int k = 0; k < 2; ++k) dst[n][k] = *(const PG8_LAS bf16x8*)(lds + PG8_SB(b, h) + boff + n * 2048 + k * 1024); } while (0)
; #define PG8_MMA(ai, bj, At, Bt) do { __builtin_amdgcn_s_setprio(1); _Pragma("unroll") for (int m = 0; m < 4; ++m) _Pragma("unroll") for (int n = 0; n < 2; ++n) _Pragma("unroll") for (int k = 0; k < 2; ++k) \
;         acc[ai][bj][m][n] = __builtin_amdgcn_mfma_f32_16x16x32_bf16(Bt[n][k], At[m][k], acc[ai][bj][m][n], 0, 0, 0); __builtin_amdgcn_s_setprio(0); } while (0)
; #define PG8_WAIT_V(n) asm volatile("s_waitcnt vmcnt(" #n ")" ::: "memory")
; #define PG8_WAIT_L(n) asm volatile("s_waitcnt lgkmcnt(" #n ")" ::: "memory")
; #define PG8_BAR __builtin_amdgcn_s_barrier()
; #define PG8_SCHED __builtin_amdgcn_sched_barrier(0)
; template <class Epi>
; __device__ __forceinline__ void gemm_phase(PG8_LAS unsigned char* lds, PG8_LAS unsigned char* xl, const Gemm g, const Sched& S, const Epi& E, const int wid) {
;     ...
;             PG8_WAIT_V(8); PG8_WAIT_L(0); PG8_BAR; if (do1) { PG8_MMA(1, 0, At, B0); PG8_MMA(1, 1, At, B1); } PG8_BAR; PG8_SCHED;
;             PG8_LDB(B0, 1, 0); PG8_LDB(B1, 1, 1); PG8_SCHED; PG8_LDA(At, 1, 0); PG8_STAGE(PG8_SA(0, 1), a2 + hstepA, voffA);
;             PG8_WAIT_V(8); PG8_WAIT_L(0); PG8_BAR; if (do0) { PG8_MMA(0, 0, At, B0); PG8_MMA(0, 1, At, B1); } PG8_BAR; PG8_SCHED;
	v_mfma_f32_16x16x32_bf16 v[60:63], v[144:147], v[176:179], 0
	v_mfma_f32_16x16x32_bf16 v[56:59], v[152:155], v[176:179], 0
	v_mfma_f32_16x16x32_bf16 v[52:55], v[144:147], v[184:187], 0
	v_mfma_f32_16x16x32_bf16 v[44:47], v[152:155], v[184:187], 0
	v_mfma_f32_16x16x32_bf16 v[36:39], v[144:147], v[210:213], 0
	v_mfma_f32_16x16x32_bf16 v[28:31], v[152:155], v[210:213], 0
	v_mfma_f32_16x16x32_bf16 v[20:23], v[144:147], v[218:221], 0
	v_mfma_f32_16x16x32_bf16 v[12:15], v[152:155], v[218:221], 0
	v_mfma_f32_16x16x32_bf16 v[60:63], v[148:151], v[180:183], v[60:63]
	v_mfma_f32_16x16x32_bf16 v[56:59], v[156:159], v[180:183], v[56:59]
	v_mfma_f32_16x16x32_bf16 v[52:55], v[148:151], v[188:191], v[52:55]
	v_mfma_f32_16x16x32_bf16 v[44:47], v[156:159], v[188:191], v[44:47]
	v_mfma_f32_16x16x32_bf16 v[36:39], v[148:151], v[214:217], v[36:39]
	v_mfma_f32_16x16x32_bf16 v[28:31], v[156:159], v[214:217], v[28:31]
	v_mfma_f32_16x16x32_bf16 v[20:23], v[148:151], v[222:225], v[20:23]
	v_mfma_f32_16x16x32_bf16 v[12:15], v[156:159], v[222:225], v[12:15]
	s_setprio 0
	s_setprio 1
	v_mfma_f32_16x16x32_bf16 v[48:51], v[160:163], v[176:179], 0
	v_mfma_f32_16x16x32_bf16 v[40:43], v[168:171], v[176:179], 0
	v_mfma_f32_16x16x32_bf16 v[32:35], v[160:163], v[184:187], 0
	v_mfma_f32_16x16x32_bf16 v[24:27], v[168:171], v[184:187], 0
	v_mfma_f32_16x16x32_bf16 v[16:19], v[160:163], v[210:213], 0
	v_mfma_f32_16x16x32_bf16 v[8:11], v[168:171], v[210:213], 0
	v_mfma_f32_16x16x32_bf16 v[4:7], v[160:163], v[218:221], 0
	v_mfma_f32_16x16x32_bf16 v[0:3], v[168:171], v[218:221], 0
	v_mfma_f32_16x16x32_bf16 v[48:51], v[164:167], v[180:183], v[48:51]
	v_mfma_f32_16x16x32_bf16 v[40:43], v[172:175], v[180:183], v[40:43]
	v_mfma_f32_16x16x32_bf16 v[32:35], v[164:167], v[188:191], v[32:35]
	v_mfma_f32_16x16x32_bf16 v[24:27], v[172:175], v[188:191], v[24:27]
	v_mfma_f32_16x16x32_bf16 v[16:19], v[164:167], v[214:217], v[16:19]
	v_mfma_f32_16x16x32_bf16 v[8:11], v[172:175], v[214:217], v[8:11]
	v_mfma_f32_16x16x32_bf16 v[4:7], v[164:167], v[222:225], v[4:7]
	v_mfma_f32_16x16x32_bf16 v[0:3], v[172:175], v[222:225], v[0:3]
	s_barrier
	s_setprio 0
	s_add_i32 s54, 0, 0x18000
	s_add_i32 s55, 0, 0x1c000
	ds_read_b128 v[144:147], v229 offset:32768
	ds_read_b128 v[148:151], v229 offset:33792
	ds_read_b128 v[152:155], v229 offset:34816
	ds_read_b128 v[156:159], v229 offset:35840
	ds_read_b128 v[160:163], v229 offset:49152
	ds_read_b128 v[164:167], v229 offset:50176
	ds_read_b128 v[168:171], v229 offset:51200
	ds_read_b128 v[172:175], v229 offset:52224
	s_add_u32 s50, s58, 0x80000
	s_addc_u32 s51, s59, 0
	s_mov_b32 m0, s69
	ds_read_b128 v[176:179], v143 offset:32768
	ds_read_b128 v[180:183], v143 offset:33792
	ds_read_b128 v[184:187], v143 offset:34816
	ds_read_b128 v[188:191], v143 offset:35840
	ds_read_b128 v[210:213], v143 offset:36864
	ds_read_b128 v[214:217], v143 offset:37888
	ds_read_b128 v[218:221], v143 offset:38912
	ds_read_b128 v[222:225], v143 offset:39936
	global_load_lds_dwordx4 v134, s[50:51]
	s_mov_b32 m0, s70
	s_nop 0
	global_load_lds_dwordx4 v130, s[50:51]
	s_waitcnt vmcnt(8)
	s_waitcnt lgkmcnt(0)
	s_setprio 1
	s_barrier
	v_mfma_f32_16x16x32_bf16 v[124:127], v[144:147], v[176:179], v[124:127]
	v_mfma_f32_16x16x32_bf16 v[120:123], v[152:155], v[176:179], v[120:123]
	v_mfma_f32_16x16x32_bf16 v[116:119], v[144:147], v[184:187], v[116:119]
	v_mfma_f32_16x16x32_bf16 v[108:111], v[152:155], v[184:187], v[108:111]
	v_mfma_f32_16x16x32_bf16 v[100:103], v[144:147], v[210:213], v[100:103]
	v_mfma_f32_16x16x32_bf16 v[92:95], v[152:155], v[210:213], v[92:95]
	v_mfma_f32_16x16x32_bf16 v[84:87], v[144:147], v[218:221], v[84:87]
	v_mfma_f32_16x16x32_bf16 v[76:79], v[152:155], v[218:221], v[76:79]
	v_mfma_f32_16x16x32_bf16 v[124:127], v[148:151], v[180:183], v[124:127]
	v_mfma_f32_16x16x32_bf16 v[120:123], v[156:159], v[180:183], v[120:123]
	v_mfma_f32_16x16x32_bf16 v[116:119], v[148:151], v[188:191], v[116:119]
	v_mfma_f32_16x16x32_bf16 v[108:111], v[156:159], v[188:191], v[108:111]
	v_mfma_f32_16x16x32_bf16 v[100:103], v[148:151], v[214:217], v[100:103]
	v_mfma_f32_16x16x32_bf16 v[92:95], v[156:159], v[214:217], v[92:95]
	v_mfma_f32_16x16x32_bf16 v[84:87], v[148:151], v[222:225], v[84:87]
	v_mfma_f32_16x16x32_bf16 v[76:79], v[156:159], v[222:225], v[76:79]
	s_setprio 0
	s_setprio 1
	v_mfma_f32_16x16x32_bf16 v[112:115], v[160:163], v[176:179], v[112:115]
	v_mfma_f32_16x16x32_bf16 v[104:107], v[168:171], v[176:179], v[104:107]
	v_mfma_f32_16x16x32_bf16 v[96:99], v[160:163], v[184:187], v[96:99]
	v_mfma_f32_16x16x32_bf16 v[88:91], v[168:171], v[184:187], v[88:91]
	v_mfma_f32_16x16x32_bf16 v[80:83], v[160:163], v[210:213], v[80:83]
	v_mfma_f32_16x16x32_bf16 v[72:75], v[168:171], v[210:213], v[72:75]
	v_mfma_f32_16x16x32_bf16 v[68:71], v[160:163], v[218:221], v[68:71]
	v_mfma_f32_16x16x32_bf16 v[64:67], v[168:171], v[218:221], v[64:67]
	v_mfma_f32_16x16x32_bf16 v[112:115], v[164:167], v[180:183], v[112:115]
	v_mfma_f32_16x16x32_bf16 v[104:107], v[172:175], v[180:183], v[104:107]
	v_mfma_f32_16x16x32_bf16 v[96:99], v[164:167], v[188:191], v[96:99]
	v_mfma_f32_16x16x32_bf16 v[88:91], v[172:175], v[188:191], v[88:91]
	v_mfma_f32_16x16x32_bf16 v[80:83], v[164:167], v[214:217], v[80:83]
	v_mfma_f32_16x16x32_bf16 v[72:75], v[172:175], v[214:217], v[72:75]
	v_mfma_f32_16x16x32_bf16 v[68:71], v[164:167], v[222:225], v[68:71]
	v_mfma_f32_16x16x32_bf16 v[64:67], v[172:175], v[222:225], v[64:67]
	s_barrier
; #define PG8_STAGE(bufoff, gbase, voff) do { _Pragma("unroll") for (int _i = 0; _i < 2; ++_i) \
;         __builtin_amdgcn_global_load_lds((const unsigned*)((const char*)(gbase) + (voff)[_i]), (PG8_LAS unsigned*)(lds + (bufoff) + ldsw + _i * 8192), 16, 0, 0); } while (0)
; #define PG8_LDA(dst, b, h) do { _Pragma("unroll") for (int m = 0; m < 4; ++m) _Pragma("unroll") for (int k = 0; k < 2; ++k) dst[m][k] = *(const PG8_LAS bf16x8*)(lds + PG8_SA(b, h) + aoff + m * 2048 + k * 1024); } while (0)
; #define PG8_MMA(ai, bj, At, Bt) do { __builtin_amdgcn_s_setprio(1); _Pragma("unroll") for (int m = 0; m < 4; ++m) _Pragma("unroll") for (int n = 0; n < 2; ++n) _Pragma("unroll") for (int k = 0; k < 2; ++k) \
;         acc[ai][bj][m][n] = __builtin_amdgcn_mfma_f32_16x16x32_bf16(Bt[n][k], At[m][k], acc[ai][bj][m][n], 0, 0, 0); __builtin_amdgcn_s_setprio(0); } while (0)
; #define PG8_WAIT_V(n) asm volatile("s_waitcnt vmcnt(" #n ")" ::: "memory")
; #define PG8_WAIT_L(n) asm volatile("s_waitcnt lgkmcnt(" #n ")" ::: "memory")
; #define PG8_BAR __builtin_amdgcn_s_barrier()
; #define PG8_SCHED __builtin_amdgcn_sched_barrier(0)
; template <class Epi>
; __device__ __forceinline__ void gemm_phase(PG8_LAS unsigned char* lds, PG8_LAS unsigned char* xl, const Gemm g, const Sched& S, const Epi& E, const int wid) {
;     ...
;             PG8_LDA(At, 1, 1); PG8_STAGE(PG8_SB(1, 0), b3, voffB); PG8_STAGE(PG8_SB(1, 1), b3 + hstepB, voffB); PG8_STAGE(PG8_SA(1, 0), a3, voffA);
;             PG8_WAIT_V(8); PG8_WAIT_L(0); PG8_BAR; if (do1) { PG8_MMA(1, 0, At, B0); PG8_MMA(1, 1, At, B1); } PG8_BAR; PG8_SCHED;
;         }
	s_setprio 0
	s_add_i32 s50, s54, s29
	s_mov_b32 m0, s50
	ds_read_b128 v[176:179], v143 offset:49152
	ds_read_b128 v[180:183], v143 offset:50176
	ds_read_b128 v[184:187], v143 offset:51200
	ds_read_b128 v[188:191], v143 offset:52224
	ds_read_b128 v[210:213], v143 offset:53248
	ds_read_b128 v[214:217], v143 offset:54272
	ds_read_b128 v[218:221], v143 offset:55296
	ds_read_b128 v[222:225], v143 offset:56320
	global_load_lds_dwordx4 v227, s[56:57]
	s_add_i32 m0, s50, 0x2000
	s_add_u32 s50, s56, 0x80080
	global_load_lds_dwordx4 v141, s[56:57]
	s_addc_u32 s51, s57, 0
	s_add_i32 s54, s55, s29
	s_mov_b32 m0, s54
	s_nop 0
	global_load_lds_dwordx4 v132, s[50:51]
	s_add_i32 m0, s54, 0x2000
	s_nop 0
	global_load_lds_dwordx4 v128, s[50:51]
	s_mov_b32 m0, s77
	s_nop 0
	global_load_lds_dwordx4 v228, s[58:59]
	s_mov_b32 m0, s87
	s_nop 0
	global_load_lds_dwordx4 v226, s[58:59]
	s_waitcnt vmcnt(8)
	s_waitcnt lgkmcnt(0)
	s_setprio 1
	s_barrier
	v_mfma_f32_16x16x32_bf16 v[60:63], v[144:147], v[176:179], v[60:63]
	v_mfma_f32_16x16x32_bf16 v[56:59], v[152:155], v[176:179], v[56:59]
	v_mfma_f32_16x16x32_bf16 v[52:55], v[144:147], v[184:187], v[52:55]
	v_mfma_f32_16x16x32_bf16 v[44:47], v[152:155], v[184:187], v[44:47]
	v_mfma_f32_16x16x32_bf16 v[36:39], v[144:147], v[210:213], v[36:39]
	v_mfma_f32_16x16x32_bf16 v[28:31], v[152:155], v[210:213], v[28:31]
	v_mfma_f32_16x16x32_bf16 v[20:23], v[144:147], v[218:221], v[20:23]
	v_mfma_f32_16x16x32_bf16 v[12:15], v[152:155], v[218:221], v[12:15]
	v_mfma_f32_16x16x32_bf16 v[60:63], v[148:151], v[180:183], v[60:63]
	v_mfma_f32_16x16x32_bf16 v[56:59], v[156:159], v[180:183], v[56:59]
	v_mfma_f32_16x16x32_bf16 v[52:55], v[148:151], v[188:191], v[52:55]
	v_mfma_f32_16x16x32_bf16 v[44:47], v[156:159], v[188:191], v[44:47]
	v_mfma_f32_16x16x32_bf16 v[36:39], v[148:151], v[214:217], v[36:39]
	v_mfma_f32_16x16x32_bf16 v[28:31], v[156:159], v[214:217], v[28:31]
	v_mfma_f32_16x16x32_bf16 v[20:23], v[148:151], v[222:225], v[20:23]
	v_mfma_f32_16x16x32_bf16 v[12:15], v[156:159], v[222:225], v[12:15]
	s_setprio 0
	s_setprio 1
	v_mfma_f32_16x16x32_bf16 v[48:51], v[160:163], v[176:179], v[48:51]
	v_mfma_f32_16x16x32_bf16 v[40:43], v[168:171], v[176:179], v[40:43]
	v_mfma_f32_16x16x32_bf16 v[32:35], v[160:163], v[184:187], v[32:35]
	v_mfma_f32_16x16x32_bf16 v[24:27], v[168:171], v[184:187], v[24:27]
	v_mfma_f32_16x16x32_bf16 v[16:19], v[160:163], v[210:213], v[16:19]
	v_mfma_f32_16x16x32_bf16 v[8:11], v[168:171], v[210:213], v[8:11]
	v_mfma_f32_16x16x32_bf16 v[4:7], v[160:163], v[218:221], v[4:7]
	v_mfma_f32_16x16x32_bf16 v[0:3], v[168:171], v[218:221], v[0:3]
	v_mfma_f32_16x16x32_bf16 v[48:51], v[164:167], v[180:183], v[48:51]
	v_mfma_f32_16x16x32_bf16 v[40:43], v[172:175], v[180:183], v[40:43]
	v_mfma_f32_16x16x32_bf16 v[32:35], v[164:167], v[188:191], v[32:35]
	v_mfma_f32_16x16x32_bf16 v[24:27], v[172:175], v[188:191], v[24:27]
	v_mfma_f32_16x16x32_bf16 v[16:19], v[164:167], v[214:217], v[16:19]
	v_mfma_f32_16x16x32_bf16 v[8:11], v[172:175], v[214:217], v[8:11]
	v_mfma_f32_16x16x32_bf16 v[4:7], v[164:167], v[222:225], v[4:7]
	v_mfma_f32_16x16x32_bf16 v[0:3], v[172:175], v[222:225], v[0:3]
	s_barrier
	s_setprio 0
	s_add_i32 s43, s43, 2
	s_add_u32 s13, s13, 0x100
	s_addc_u32 s21, s21, 0
	s_cmp_gt_u32 s43, 29
	s_mov_b64 s[50:51], s[52:53]

; #define PG8_STAGE(bufoff, gbase, voff) do { _Pragma("unroll") for (int _i = 0; _i < 2; ++_i) \
;         __builtin_amdgcn_global_load_lds((const unsigned*)((const char*)(gbase) + (voff)[_i]), (PG8_LAS unsigned*)(lds + (bufoff) + ldsw + _i * 8192), 16, 0, 0); } while (0)
; #define PG8_LDA(dst, b, h) do { _Pragma("unroll") for (int m = 0; m < 4; ++m) _Pragma("unroll") for (int k = 0; k < 2; ++k) dst[m][k] = *(const PG8_LAS bf16x8*)(lds + PG8_SA(b, h) + aoff + m * 2048 + k * 1024); } while (0)
; #define PG8_LDB(dst, b, h) do { _Pragma("unroll") for (int n = 0; n < 2; ++n) _Pragma("unroll") for (int k = 0; k < 2; ++k) dst[n][k] = *(const PG8_LAS bf16x8*)(lds + PG8_SB(b, h) + boff + n * 2048 + k * 1024); } while (0)
; #define PG8_MMA(ai, bj, At, Bt) do { __builtin_amdgcn_s_setprio(1); _Pragma("unroll") for (int m = 0; m < 4; ++m) _Pragma("unroll") for (int n = 0; n < 2; ++n) _Pragma("unroll") for (int k = 0; k < 2; ++k) \
;         acc[ai][bj][m][n] = __builtin_amdgcn_mfma_f32_16x16x32_bf16(Bt[n][k], At[m][k], acc[ai][bj][m][n], 0, 0, 0); __builtin_amdgcn_s_setprio(0); } while (0)
; #define PG8_WAIT_V(n) asm volatile("s_waitcnt vmcnt(" #n ")" ::: "memory")
; #define PG8_WAIT_L(n) asm volatile("s_waitcnt lgkmcnt(" #n ")" ::: "memory")
; template <class Epi>
; __device__ __forceinline__ void gemm_phase(PG8_LAS unsigned char* lds, PG8_LAS unsigned char* xl, const Gemm g, const Sched& S, const Epi& E, const int wid) {
;     ...
;             const char* a1 = cA + (size_t)(t + 1) * kstep + j1;
;             const char* a2 = last ? nA : cA + (size_t)(t + 2) * kstep + ja2; const char* b2 = last ? nB : cB + (size_t)(t + 2) * kstep + jb2;
;             const char* a3 = a2 + kstep; const char* b3 = b2 + kstep;
;             PG8_LDB(B0, 0, 0); PG8_LDB(B1, 0, 1); PG8_SCHED; PG8_LDA(At, 0, 0); PG8_STAGE(PG8_SA(1, 1), a1 + hstepA, voffA);
;             PG8_WAIT_V(8); PG8_WAIT_L(0); PG8_BAR; if (do0) { PG8_MMA(0, 0, At, B0); PG8_MMA(0, 1, At, B1); } PG8_BAR; PG8_SCHED;
;             PG8_LDA(At, 0, 1); PG8_STAGE(PG8_SB(0, 0), b2, voffB); PG8_STAGE(PG8_SB(0, 1), b2 + hstepB, voffB); PG8_STAGE(PG8_SA(0, 0), a2, voffA);
;     ...
;         for (int a = 0; a < 2; ++a)
; #pragma unroll
;             for (int b = 0; b < 2; ++b)
; #pragma unroll
;                 for (int m = 0; m < 4; ++m)
; #pragma unroll
;                     for (int n = 0; n < 2; ++n) acc[a][b][m][n] = (f32x4){0.f, 0.f, 0.f, 0.f};
.LBB0_237:
	s_ashr_i32 s59, s58, 31
	s_lshl_b64 s[8:9], s[58:59], 20
	s_add_u32 s36, s61, s8
	s_addc_u32 s37, s76, s9
	s_and_b64 s[8:9], s[40:41], exec
	s_cselect_b32 s8, s37, s21
	s_cselect_b32 s9, s36, s20
	s_ashr_i32 s57, s56, 31
	s_lshl_b64 s[10:11], s[56:57], 20
	s_add_u32 s52, s1, s10
	s_addc_u32 s53, s60, s11
	s_and_b64 s[10:11], s[40:41], exec
	s_cselect_b32 s10, s53, s31
	s_cselect_b32 s11, s52, s30
	s_add_u32 s13, s30, 0x100
	s_addc_u32 s57, s31, 0
	s_mov_b32 s62, -2
	s_waitcnt lgkmcnt(0)
	s_cmp_lg_u32 s100, 1
	s_cbranch_scc1 .Ldefbar_skip_1
	s_mov_b32 s100, 0
	s_barrier
.Ldefbar_skip_1:
	v_add_u32_e32 v157, s22, v140
	v_add_u32_e32 v234, s22, v142
	v_add_u32_e32 v235, s22, v144
	v_add_u32_e32 v236, s22, v146
	v_add_u32_e32 v237, 0x10000, v158
	s_add_u32 s30, s20, 0x100
	s_addc_u32 s31, s21, 0
	s_add_i32 s54, 0, 0x10000
	s_cmp_eq_u32 s62, 28
	s_cselect_b32 s47, s8, s31
	s_cselect_b32 s46, s9, s30
	s_cselect_b32 s45, s10, s57
	s_cselect_b32 s44, s11, s13
	s_add_i32 s55, 0, 0x14000
	ds_read_b128 v[18:21], v237 offset:0
	ds_read_b128 v[22:25], v237 offset:1024
	ds_read_b128 v[160:163], v237 offset:2048
	ds_read_b128 v[164:167], v237 offset:3072
	ds_read_b128 v[168:171], v237 offset:16384
	ds_read_b128 v[172:175], v237 offset:17408
	ds_read_b128 v[176:179], v237 offset:18432
	ds_read_b128 v[180:183], v237 offset:19456
	s_add_i32 m0, s77, 0xc000
	ds_read_b128 v[184:187], v159
	ds_read_b128 v[188:191], v159 offset:1024
	ds_read_b128 v[210:213], v159 offset:2048
	ds_read_b128 v[214:217], v159 offset:3072
	ds_read_b128 v[218:221], v159 offset:4096
	ds_read_b128 v[222:225], v159 offset:5120
	ds_read_b128 v[226:229], v159 offset:6144
	ds_read_b128 v[230:233], v159 offset:7168
	global_load_lds_dwordx4 v148, s[20:21]
	s_add_i32 m0, s77, 0xe000
	s_nop 0
	global_load_lds_dwordx4 v150, s[20:21]
	s_waitcnt vmcnt(8)
	s_waitcnt lgkmcnt(0)
	s_setprio 1
	s_barrier
	v_mfma_f32_16x16x32_bf16 v[136:139], v[18:21], v[184:187], 0
	v_mfma_f32_16x16x32_bf16 v[132:135], v[160:163], v[184:187], 0
	v_mfma_f32_16x16x32_bf16 v[120:123], v[18:21], v[210:213], 0
	v_mfma_f32_16x16x32_bf16 v[116:119], v[160:163], v[210:213], 0
	v_mfma_f32_16x16x32_bf16 v[104:107], v[18:21], v[218:221], 0
	v_mfma_f32_16x16x32_bf16 v[100:103], v[160:163], v[218:221], 0
	v_mfma_f32_16x16x32_bf16 v[86:89], v[18:21], v[226:229], 0
	v_mfma_f32_16x16x32_bf16 v[82:85], v[160:163], v[226:229], 0
	v_mfma_f32_16x16x32_bf16 v[136:139], v[22:25], v[188:191], v[136:139]
	v_mfma_f32_16x16x32_bf16 v[132:135], v[164:167], v[188:191], v[132:135]
	v_mfma_f32_16x16x32_bf16 v[120:123], v[22:25], v[214:217], v[120:123]
	v_mfma_f32_16x16x32_bf16 v[116:119], v[164:167], v[214:217], v[116:119]
	v_mfma_f32_16x16x32_bf16 v[104:107], v[22:25], v[222:225], v[104:107]
	v_mfma_f32_16x16x32_bf16 v[100:103], v[164:167], v[222:225], v[100:103]
	v_mfma_f32_16x16x32_bf16 v[86:89], v[22:25], v[230:233], v[86:89]
	v_mfma_f32_16x16x32_bf16 v[82:85], v[164:167], v[230:233], v[82:85]
	s_setprio 0
	s_setprio 1
	v_mfma_f32_16x16x32_bf16 v[128:131], v[168:171], v[184:187], 0
	v_mfma_f32_16x16x32_bf16 v[124:127], v[176:179], v[184:187], 0
	v_mfma_f32_16x16x32_bf16 v[112:115], v[168:171], v[210:213], 0
	v_mfma_f32_16x16x32_bf16 v[108:111], v[176:179], v[210:213], 0
	v_mfma_f32_16x16x32_bf16 v[96:99], v[168:171], v[218:221], 0
	v_mfma_f32_16x16x32_bf16 v[92:95], v[176:179], v[218:221], 0
	v_mfma_f32_16x16x32_bf16 v[78:81], v[168:171], v[226:229], 0
	v_mfma_f32_16x16x32_bf16 v[74:77], v[176:179], v[226:229], 0
	v_mfma_f32_16x16x32_bf16 v[128:131], v[172:175], v[188:191], v[128:131]
	v_mfma_f32_16x16x32_bf16 v[124:127], v[180:183], v[188:191], v[124:127]
	v_mfma_f32_16x16x32_bf16 v[112:115], v[172:175], v[214:217], v[112:115]
	v_mfma_f32_16x16x32_bf16 v[108:111], v[180:183], v[214:217], v[108:111]
	v_mfma_f32_16x16x32_bf16 v[96:99], v[172:175], v[222:225], v[96:99]
	v_mfma_f32_16x16x32_bf16 v[92:95], v[180:183], v[222:225], v[92:95]
	v_mfma_f32_16x16x32_bf16 v[78:81], v[172:175], v[230:233], v[78:81]
	v_mfma_f32_16x16x32_bf16 v[74:77], v[180:183], v[230:233], v[74:77]
	s_barrier
	s_setprio 0
	s_add_i32 s20, s54, s29
	s_mov_b32 m0, s20
	ds_read_b128 v[184:187], v159 offset:16384
	ds_read_b128 v[188:191], v159 offset:17408
	ds_read_b128 v[210:213], v159 offset:18432
	ds_read_b128 v[214:217], v159 offset:19456
	ds_read_b128 v[218:221], v159 offset:20480
	ds_read_b128 v[222:225], v159 offset:21504
	ds_read_b128 v[226:229], v159 offset:22528
	ds_read_b128 v[230:233], v159 offset:23552
	global_load_lds_dwordx4 v142, s[44:45]
	s_add_i32 m0, s20, 0x2000
	s_add_u32 s20, s44, 0x80000
	s_addc_u32 s21, s45, 0
	s_add_i32 s54, s55, s29
	global_load_lds_dwordx4 v146, s[44:45]
	s_mov_b32 m0, s54
	s_nop 0
	global_load_lds_dwordx4 v142, s[20:21]
	s_add_i32 m0, s54, 0x2000
	s_nop 0
	global_load_lds_dwordx4 v146, s[20:21]
	s_mov_b32 m0, s77
	s_nop 0
	global_load_lds_dwordx4 v140, s[46:47]
	s_mov_b32 m0, s49
	s_nop 0
	global_load_lds_dwordx4 v144, s[46:47]
	s_waitcnt vmcnt(8)
	s_waitcnt lgkmcnt(0)
	s_setprio 1
	s_barrier
; #define PG8_STAGE(bufoff, gbase, voff) do { _Pragma("unroll") for (int _i = 0; _i < 2; ++_i) \
;         __builtin_amdgcn_global_load_lds((const unsigned*)((const char*)(gbase) + (voff)[_i]), (PG8_LAS unsigned*)(lds + (bufoff) + ldsw + _i * 8192), 16, 0, 0); } while (0)
; #define PG8_LDA(dst, b, h) do { _Pragma("unroll") for (int m = 0; m < 4; ++m) _Pragma("unroll") for (int k = 0; k < 2; ++k) dst[m][k] = *(const PG8_LAS bf16x8*)(lds + PG8_SA(b, h) + aoff + m * 2048 + k * 1024); } while (0)
; #define PG8_LDB(dst, b, h) do { _Pragma("unroll") for (int n = 0; n < 2; ++n) _Pragma("unroll") for (int k = 0; k < 2; ++k) dst[n][k] = *(const PG8_LAS bf16x8*)(lds + PG8_SB(b, h) + boff + n * 2048 + k * 1024); } while (0)
; #define PG8_MMA(ai, bj, At, Bt) do { __builtin_amdgcn_s_setprio(1); _Pragma("unroll") for (int m = 0; m < 4; ++m) _Pragma("unroll") for (int n = 0; n < 2; ++n) _Pragma("unroll") for (int k = 0; k < 2; ++k) \
;         acc[ai][bj][m][n] = __builtin_amdgcn_mfma_f32_16x16x32_bf16(Bt[n][k], At[m][k], acc[ai][bj][m][n], 0, 0, 0); __builtin_amdgcn_s_setprio(0); } while (0)
; #define PG8_WAIT_V(n) asm volatile("s_waitcnt vmcnt(" #n ")" ::: "memory")
; #define PG8_WAIT_L(n) asm volatile("s_waitcnt lgkmcnt(" #n ")" ::: "memory")
; #define PG8_BAR __builtin_amdgcn_s_barrier()
; #define PG8_SCHED __builtin_amdgcn_sched_barrier(0)
; template <class Epi>
; __device__ __forceinline__ void gemm_phase(PG8_LAS unsigned char* lds, PG8_LAS unsigned char* xl, const Gemm g, const Sched& S, const Epi& E, const int wid) {
;     ...
;             PG8_WAIT_V(8); PG8_WAIT_L(0); PG8_BAR; if (do1) { PG8_MMA(1, 0, At, B0); PG8_MMA(1, 1, At, B1); } PG8_BAR; PG8_SCHED;
;             PG8_LDB(B0, 1, 0); PG8_LDB(B1, 1, 1); PG8_SCHED; PG8_LDA(At, 1, 0); PG8_STAGE(PG8_SA(0, 1), a2 + hstepA, voffA);
;             PG8_WAIT_V(8); PG8_WAIT_L(0); PG8_BAR; if (do0) { PG8_MMA(0, 0, At, B0); PG8_MMA(0, 1, At, B1); } PG8_BAR; PG8_SCHED;
	v_mfma_f32_16x16x32_bf16 v[70:73], v[18:21], v[184:187], 0
	v_mfma_f32_16x16x32_bf16 v[66:69], v[160:163], v[184:187], 0
	v_mfma_f32_16x16x32_bf16 v[54:57], v[18:21], v[210:213], 0
	v_mfma_f32_16x16x32_bf16 v[50:53], v[160:163], v[210:213], 0
	v_mfma_f32_16x16x32_bf16 v[38:41], v[18:21], v[218:221], 0
	v_mfma_f32_16x16x32_bf16 v[34:37], v[160:163], v[218:221], 0
	v_mfma_f32_16x16x32_bf16 v[12:15], v[18:21], v[226:229], 0
	v_mfma_f32_16x16x32_bf16 v[8:11], v[160:163], v[226:229], 0
	v_mfma_f32_16x16x32_bf16 v[70:73], v[22:25], v[188:191], v[70:73]
	v_mfma_f32_16x16x32_bf16 v[66:69], v[164:167], v[188:191], v[66:69]
	v_mfma_f32_16x16x32_bf16 v[54:57], v[22:25], v[214:217], v[54:57]
	v_mfma_f32_16x16x32_bf16 v[50:53], v[164:167], v[214:217], v[50:53]
	v_mfma_f32_16x16x32_bf16 v[38:41], v[22:25], v[222:225], v[38:41]
	v_mfma_f32_16x16x32_bf16 v[34:37], v[164:167], v[222:225], v[34:37]
	v_mfma_f32_16x16x32_bf16 v[12:15], v[22:25], v[230:233], v[12:15]
	v_mfma_f32_16x16x32_bf16 v[8:11], v[164:167], v[230:233], v[8:11]
	s_setprio 0
	s_setprio 1
	v_mfma_f32_16x16x32_bf16 v[46:49], v[168:171], v[210:213], 0
	v_mfma_f32_16x16x32_bf16 v[42:45], v[176:179], v[210:213], 0
	v_mfma_f32_16x16x32_bf16 v[30:33], v[168:171], v[218:221], 0
	v_mfma_f32_16x16x32_bf16 v[26:29], v[176:179], v[218:221], 0
	v_mfma_f32_16x16x32_bf16 v[4:7], v[168:171], v[226:229], 0
	v_mfma_f32_16x16x32_bf16 v[0:3], v[176:179], v[226:229], 0
	v_mfma_f32_16x16x32_bf16 v[18:21], v[168:171], v[184:187], 0
	v_mfma_f32_16x16x32_bf16 v[22:25], v[176:179], v[184:187], 0
	v_mfma_f32_16x16x32_bf16 v[46:49], v[172:175], v[214:217], v[46:49]
	v_mfma_f32_16x16x32_bf16 v[42:45], v[180:183], v[214:217], v[42:45]
	v_mfma_f32_16x16x32_bf16 v[30:33], v[172:175], v[222:225], v[30:33]
	v_mfma_f32_16x16x32_bf16 v[26:29], v[180:183], v[222:225], v[26:29]
	v_mfma_f32_16x16x32_bf16 v[4:7], v[172:175], v[230:233], v[4:7]
	v_mfma_f32_16x16x32_bf16 v[0:3], v[180:183], v[230:233], v[0:3]
	v_mfma_f32_16x16x32_bf16 v[18:21], v[172:175], v[188:191], v[18:21]
	v_mfma_f32_16x16x32_bf16 v[22:25], v[180:183], v[188:191], v[22:25]
	s_barrier
	s_setprio 0
	s_add_i32 s54, 0, 0x18000
	s_add_i32 s55, 0, 0x1c000
	ds_read_b128 v[58:61], v237 offset:32768
	ds_read_b128 v[62:65], v237 offset:33792
	ds_read_b128 v[160:163], v237 offset:34816
	ds_read_b128 v[164:167], v237 offset:35840
	ds_read_b128 v[168:171], v237 offset:49152
	ds_read_b128 v[172:175], v237 offset:50176
	ds_read_b128 v[176:179], v237 offset:51200
	ds_read_b128 v[180:183], v237 offset:52224
	s_add_u32 s20, s46, 0x80000
	s_addc_u32 s21, s47, 0
	s_mov_b32 m0, s87
	ds_read_b128 v[184:187], v159 offset:32768
	ds_read_b128 v[188:191], v159 offset:33792
	ds_read_b128 v[210:213], v159 offset:34816
	ds_read_b128 v[214:217], v159 offset:35840
	ds_read_b128 v[218:221], v159 offset:36864
	ds_read_b128 v[222:225], v159 offset:37888
	ds_read_b128 v[226:229], v159 offset:38912
	ds_read_b128 v[230:233], v159 offset:39936
	global_load_lds_dwordx4 v140, s[20:21]
	s_mov_b32 m0, s88
	s_nop 0
	global_load_lds_dwordx4 v144, s[20:21]
	s_waitcnt vmcnt(8)
	s_waitcnt lgkmcnt(0)
	s_setprio 1
	s_barrier
	v_mfma_f32_16x16x32_bf16 v[136:139], v[58:61], v[184:187], v[136:139]
	v_mfma_f32_16x16x32_bf16 v[132:135], v[160:163], v[184:187], v[132:135]
	v_mfma_f32_16x16x32_bf16 v[120:123], v[58:61], v[210:213], v[120:123]
	v_mfma_f32_16x16x32_bf16 v[116:119], v[160:163], v[210:213], v[116:119]
	v_mfma_f32_16x16x32_bf16 v[104:107], v[58:61], v[218:221], v[104:107]
	v_mfma_f32_16x16x32_bf16 v[100:103], v[160:163], v[218:221], v[100:103]
	v_mfma_f32_16x16x32_bf16 v[86:89], v[58:61], v[226:229], v[86:89]
	v_mfma_f32_16x16x32_bf16 v[82:85], v[160:163], v[226:229], v[82:85]
	v_mfma_f32_16x16x32_bf16 v[136:139], v[62:65], v[188:191], v[136:139]
	v_mfma_f32_16x16x32_bf16 v[132:135], v[164:167], v[188:191], v[132:135]
	v_mfma_f32_16x16x32_bf16 v[120:123], v[62:65], v[214:217], v[120:123]
	v_mfma_f32_16x16x32_bf16 v[116:119], v[164:167], v[214:217], v[116:119]
	v_mfma_f32_16x16x32_bf16 v[104:107], v[62:65], v[222:225], v[104:107]
	v_mfma_f32_16x16x32_bf16 v[100:103], v[164:167], v[222:225], v[100:103]
	v_mfma_f32_16x16x32_bf16 v[86:89], v[62:65], v[230:233], v[86:89]
	v_mfma_f32_16x16x32_bf16 v[82:85], v[164:167], v[230:233], v[82:85]
	s_setprio 0
	s_setprio 1
	v_mfma_f32_16x16x32_bf16 v[128:131], v[168:171], v[184:187], v[128:131]
	v_mfma_f32_16x16x32_bf16 v[124:127], v[176:179], v[184:187], v[124:127]
	v_mfma_f32_16x16x32_bf16 v[112:115], v[168:171], v[210:213], v[112:115]
	v_mfma_f32_16x16x32_bf16 v[108:111], v[176:179], v[210:213], v[108:111]
	v_mfma_f32_16x16x32_bf16 v[96:99], v[168:171], v[218:221], v[96:99]
	v_mfma_f32_16x16x32_bf16 v[92:95], v[176:179], v[218:221], v[92:95]
	v_mfma_f32_16x16x32_bf16 v[78:81], v[168:171], v[226:229], v[78:81]
	v_mfma_f32_16x16x32_bf16 v[74:77], v[176:179], v[226:229], v[74:77]
	v_mfma_f32_16x16x32_bf16 v[128:131], v[172:175], v[188:191], v[128:131]
	v_mfma_f32_16x16x32_bf16 v[124:127], v[180:183], v[188:191], v[124:127]
	v_mfma_f32_16x16x32_bf16 v[112:115], v[172:175], v[214:217], v[112:115]
	v_mfma_f32_16x16x32_bf16 v[108:111], v[180:183], v[214:217], v[108:111]
	v_mfma_f32_16x16x32_bf16 v[96:99], v[172:175], v[222:225], v[96:99]
	v_mfma_f32_16x16x32_bf16 v[92:95], v[180:183], v[222:225], v[92:95]
	v_mfma_f32_16x16x32_bf16 v[78:81], v[172:175], v[230:233], v[78:81]
	v_mfma_f32_16x16x32_bf16 v[74:77], v[180:183], v[230:233], v[74:77]
	s_barrier
; #define PG8_STAGE(bufoff, gbase, voff) do { _Pragma("unroll") for (int _i = 0; _i < 2; ++_i) \
;         __builtin_amdgcn_global_load_lds((const unsigned*)((const char*)(gbase) + (voff)[_i]), (PG8_LAS unsigned*)(lds + (bufoff) + ldsw + _i * 8192), 16, 0, 0); } while (0)
; #define PG8_LDA(dst, b, h) do { _Pragma("unroll") for (int m = 0; m < 4; ++m) _Pragma("unroll") for (int k = 0; k < 2; ++k) dst[m][k] = *(const PG8_LAS bf16x8*)(lds + PG8_SA(b, h) + aoff + m * 2048 + k * 1024); } while (0)
; #define PG8_MMA(ai, bj, At, Bt) do { __builtin_amdgcn_s_setprio(1); _Pragma("unroll") for (int m = 0; m < 4; ++m) _Pragma("unroll") for (int n = 0; n < 2; ++n) _Pragma("unroll") for (int k = 0; k < 2; ++k) \
;         acc[ai][bj][m][n] = __builtin_amdgcn_mfma_f32_16x16x32_bf16(Bt[n][k], At[m][k], acc[ai][bj][m][n], 0, 0, 0); __builtin_amdgcn_s_setprio(0); } while (0)
; #define PG8_WAIT_V(n) asm volatile("s_waitcnt vmcnt(" #n ")" ::: "memory")
; #define PG8_WAIT_L(n) asm volatile("s_waitcnt lgkmcnt(" #n ")" ::: "memory")
; #define PG8_BAR __builtin_amdgcn_s_barrier()
; #define PG8_SCHED __builtin_amdgcn_sched_barrier(0)
; template <class Epi>
; __device__ __forceinline__ void gemm_phase(PG8_LAS unsigned char* lds, PG8_LAS unsigned char* xl, const Gemm g, const Sched& S, const Epi& E, const int wid) {
;     ...
;             PG8_LDA(At, 1, 1); PG8_STAGE(PG8_SB(1, 0), b3, voffB); PG8_STAGE(PG8_SB(1, 1), b3 + hstepB, voffB); PG8_STAGE(PG8_SA(1, 0), a3, voffA);
;             PG8_WAIT_V(8); PG8_WAIT_L(0); PG8_BAR; if (do1) { PG8_MMA(1, 0, At, B0); PG8_MMA(1, 1, At, B1); } PG8_BAR; PG8_SCHED;
;         }
	s_setprio 0
	s_add_i32 s20, s54, s29
	s_mov_b32 m0, s20
	ds_read_b128 v[184:187], v159 offset:49152
	ds_read_b128 v[188:191], v159 offset:50176
	ds_read_b128 v[210:213], v159 offset:51200
	ds_read_b128 v[214:217], v159 offset:52224
	ds_read_b128 v[218:221], v159 offset:53248
	ds_read_b128 v[222:225], v159 offset:54272
	ds_read_b128 v[226:229], v159 offset:55296
	ds_read_b128 v[230:233], v159 offset:56320
	global_load_lds_dwordx4 v234, s[44:45]
	s_add_i32 m0, s20, 0x2000
	s_add_u32 s20, s44, 0x80080
	global_load_lds_dwordx4 v236, s[44:45]
	s_addc_u32 s21, s45, 0
	s_add_i32 s44, s55, s29
	s_mov_b32 m0, s44
	s_nop 0
	global_load_lds_dwordx4 v142, s[20:21]
	s_add_i32 m0, s44, 0x2000
	s_nop 0
	global_load_lds_dwordx4 v146, s[20:21]
	s_mov_b32 m0, s91
	s_nop 0
	global_load_lds_dwordx4 v157, s[46:47]
	s_mov_b32 m0, s92
	s_nop 0
	global_load_lds_dwordx4 v235, s[46:47]
	s_waitcnt vmcnt(8)
	s_waitcnt lgkmcnt(0)
	s_setprio 1
	s_barrier
	v_mfma_f32_16x16x32_bf16 v[70:73], v[58:61], v[184:187], v[70:73]
	v_mfma_f32_16x16x32_bf16 v[66:69], v[160:163], v[184:187], v[66:69]
	v_mfma_f32_16x16x32_bf16 v[54:57], v[58:61], v[210:213], v[54:57]
	v_mfma_f32_16x16x32_bf16 v[50:53], v[160:163], v[210:213], v[50:53]
	v_mfma_f32_16x16x32_bf16 v[38:41], v[58:61], v[218:221], v[38:41]
	v_mfma_f32_16x16x32_bf16 v[34:37], v[160:163], v[218:221], v[34:37]
	v_mfma_f32_16x16x32_bf16 v[12:15], v[58:61], v[226:229], v[12:15]
	v_mfma_f32_16x16x32_bf16 v[8:11], v[160:163], v[226:229], v[8:11]
	v_mfma_f32_16x16x32_bf16 v[70:73], v[62:65], v[188:191], v[70:73]
	v_mfma_f32_16x16x32_bf16 v[66:69], v[164:167], v[188:191], v[66:69]
	v_mfma_f32_16x16x32_bf16 v[54:57], v[62:65], v[214:217], v[54:57]
	v_mfma_f32_16x16x32_bf16 v[50:53], v[164:167], v[214:217], v[50:53]
	v_mfma_f32_16x16x32_bf16 v[38:41], v[62:65], v[222:225], v[38:41]
	v_mfma_f32_16x16x32_bf16 v[34:37], v[164:167], v[222:225], v[34:37]
	v_mfma_f32_16x16x32_bf16 v[12:15], v[62:65], v[230:233], v[12:15]
	v_mfma_f32_16x16x32_bf16 v[8:11], v[164:167], v[230:233], v[8:11]
	s_setprio 0
	s_setprio 1
	v_mfma_f32_16x16x32_bf16 v[18:21], v[168:171], v[184:187], v[18:21]
	v_mfma_f32_16x16x32_bf16 v[62:65], v[172:175], v[188:191], v[18:21]
	v_mfma_f32_16x16x32_bf16 v[18:21], v[176:179], v[184:187], v[22:25]
	v_mfma_f32_16x16x32_bf16 v[58:61], v[180:183], v[188:191], v[18:21]
	v_mfma_f32_16x16x32_bf16 v[18:21], v[168:171], v[210:213], v[46:49]
	v_mfma_f32_16x16x32_bf16 v[46:49], v[172:175], v[214:217], v[18:21]
	v_mfma_f32_16x16x32_bf16 v[18:21], v[176:179], v[210:213], v[42:45]
	v_mfma_f32_16x16x32_bf16 v[42:45], v[180:183], v[214:217], v[18:21]
	v_mfma_f32_16x16x32_bf16 v[18:21], v[168:171], v[218:221], v[30:33]
	v_mfma_f32_16x16x32_bf16 v[30:33], v[172:175], v[222:225], v[18:21]
	v_mfma_f32_16x16x32_bf16 v[18:21], v[176:179], v[218:221], v[26:29]
	v_mfma_f32_16x16x32_bf16 v[4:7], v[168:171], v[226:229], v[4:7]
	v_mfma_f32_16x16x32_bf16 v[0:3], v[176:179], v[226:229], v[0:3]
	v_mfma_f32_16x16x32_bf16 v[26:29], v[180:183], v[222:225], v[18:21]
	v_mfma_f32_16x16x32_bf16 v[4:7], v[172:175], v[230:233], v[4:7]
	v_mfma_f32_16x16x32_bf16 v[0:3], v[180:183], v[230:233], v[0:3]
	s_barrier
	s_setprio 0
	s_add_i32 s62, s62, 2
	s_add_u32 s13, s13, 0x100
	s_addc_u32 s57, s57, 0
	s_cmp_gt_u32 s62, 29
	s_mov_b64 s[20:21], s[30:31]

; #define PG8_STAGE(bufoff, gbase, voff) do { _Pragma("unroll") for (int _i = 0; _i < 2; ++_i) \
;         __builtin_amdgcn_global_load_lds((const unsigned*)((const char*)(gbase) + (voff)[_i]), (PG8_LAS unsigned*)(lds + (bufoff) + ldsw + _i * 8192), 16, 0, 0); } while (0)
; #define PG8_LDA(dst, b, h) do { _Pragma("unroll") for (int m = 0; m < 4; ++m) _Pragma("unroll") for (int k = 0; k < 2; ++k) dst[m][k] = *(const PG8_LAS bf16x8*)(lds + PG8_SA(b, h) + aoff + m * 2048 + k * 1024); } while (0)
; #define PG8_LDB(dst, b, h) do { _Pragma("unroll") for (int n = 0; n < 2; ++n) _Pragma("unroll") for (int k = 0; k < 2; ++k) dst[n][k] = *(const PG8_LAS bf16x8*)(lds + PG8_SB(b, h) + boff + n * 2048 + k * 1024); } while (0)
; #define PG8_MMA(ai, bj, At, Bt) do { __builtin_amdgcn_s_setprio(1); _Pragma("unroll") for (int m = 0; m < 4; ++m) _Pragma("unroll") for (int n = 0; n < 2; ++n) _Pragma("unroll") for (int k = 0; k < 2; ++k) \
;         acc[ai][bj][m][n] = __builtin_amdgcn_mfma_f32_16x16x32_bf16(Bt[n][k], At[m][k], acc[ai][bj][m][n], 0, 0, 0); __builtin_amdgcn_s_setprio(0); } while (0)
; #define PG8_WAIT_V(n) asm volatile("s_waitcnt vmcnt(" #n ")" ::: "memory")
; #define PG8_WAIT_L(n) asm volatile("s_waitcnt lgkmcnt(" #n ")" ::: "memory")
; template <class Epi>
; __device__ __forceinline__ void gemm_phase(PG8_LAS unsigned char* lds, PG8_LAS unsigned char* xl, const Gemm g, const Sched& S, const Epi& E, const int wid) {
;     ...
;             const char* a1 = cA + (size_t)(t + 1) * kstep + j1;
;             const char* a2 = last ? nA : cA + (size_t)(t + 2) * kstep + ja2; const char* b2 = last ? nB : cB + (size_t)(t + 2) * kstep + jb2;
;             const char* a3 = a2 + kstep; const char* b3 = b2 + kstep;
;             PG8_LDB(B0, 0, 0); PG8_LDB(B1, 0, 1); PG8_SCHED; PG8_LDA(At, 0, 0); PG8_STAGE(PG8_SA(1, 1), a1 + hstepA, voffA);
;             PG8_WAIT_V(8); PG8_WAIT_L(0); PG8_BAR; if (do0) { PG8_MMA(0, 0, At, B0); PG8_MMA(0, 1, At, B1); } PG8_BAR; PG8_SCHED;
;             PG8_LDA(At, 0, 1); PG8_STAGE(PG8_SB(0, 0), b2, voffB); PG8_STAGE(PG8_SB(0, 1), b2 + hstepB, voffB); PG8_STAGE(PG8_SA(0, 0), a2, voffA);
;     ...
;         for (int a = 0; a < 2; ++a)
; #pragma unroll
;             for (int b = 0; b < 2; ++b)
; #pragma unroll
;                 for (int m = 0; m < 4; ++m)
; #pragma unroll
;                     for (int n = 0; n < 2; ++n) acc[a][b][m][n] = (f32x4){0.f, 0.f, 0.f, 0.f};
.LBB0_407:
	s_add_u32 s8, s76, 0x100
	s_addc_u32 s9, s77, 0
	s_mov_b32 s10, -2
	s_cmp_lg_u32 s100, 1
	s_cbranch_scc1 .Ldefbar_skip_2
	s_mov_b32 s100, 0
	s_barrier
.Ldefbar_skip_2:
	v_add_u32_e32 v190, s22, v128
	v_add_u32_e32 v191, s22, v130
	v_add_u32_e32 v226, s22, v132
	v_add_u32_e32 v227, s22, v134
	v_add_u32_e32 v228, 0x10000, v140
	s_add_u32 s76, s60, 0x100
	s_addc_u32 s77, s61, 0
	s_add_i32 s11, 0, 0x10000
	s_cmp_eq_u32 s10, 4
	s_cselect_b32 s41, s47, s77
	s_cselect_b32 s40, s46, s76
	s_cselect_b32 vcc_hi, s59, s9
	s_cselect_b32 vcc_lo, s58, s8
	s_add_i32 s21, 0, 0x14000
	ds_read_b128 v[142:145], v228 offset:0
	ds_read_b128 v[146:149], v228 offset:1024
	ds_read_b128 v[150:153], v228 offset:2048
	ds_read_b128 v[154:157], v228 offset:3072
	ds_read_b128 v[158:161], v228 offset:16384
	ds_read_b128 v[162:165], v228 offset:17408
	ds_read_b128 v[166:169], v228 offset:18432
	ds_read_b128 v[170:173], v228 offset:19456
	s_add_i32 m0, s13, 0xc000
	ds_read_b128 v[174:177], v141
	ds_read_b128 v[178:181], v141 offset:1024
	ds_read_b128 v[182:185], v141 offset:2048
	ds_read_b128 v[186:189], v141 offset:3072
	ds_read_b128 v[210:213], v141 offset:4096
	ds_read_b128 v[214:217], v141 offset:5120
	ds_read_b128 v[218:221], v141 offset:6144
	ds_read_b128 v[222:225], v141 offset:7168
	global_load_lds_dwordx4 v136, s[60:61]
	s_add_i32 m0, s13, 0xe000
	s_nop 0
	global_load_lds_dwordx4 v138, s[60:61]
	s_waitcnt vmcnt(8)
	s_waitcnt lgkmcnt(0)
	s_setprio 1
	s_barrier
	v_mfma_f32_16x16x32_bf16 v[124:127], v[142:145], v[174:177], 0
	v_mfma_f32_16x16x32_bf16 v[120:123], v[150:153], v[174:177], 0
	v_mfma_f32_16x16x32_bf16 v[116:119], v[142:145], v[182:185], 0
	v_mfma_f32_16x16x32_bf16 v[108:111], v[150:153], v[182:185], 0
	v_mfma_f32_16x16x32_bf16 v[100:103], v[142:145], v[210:213], 0
	v_mfma_f32_16x16x32_bf16 v[92:95], v[150:153], v[210:213], 0
	v_mfma_f32_16x16x32_bf16 v[84:87], v[142:145], v[218:221], 0
	v_mfma_f32_16x16x32_bf16 v[76:79], v[150:153], v[218:221], 0
	v_mfma_f32_16x16x32_bf16 v[124:127], v[146:149], v[178:181], v[124:127]
	v_mfma_f32_16x16x32_bf16 v[120:123], v[154:157], v[178:181], v[120:123]
	v_mfma_f32_16x16x32_bf16 v[116:119], v[146:149], v[186:189], v[116:119]
	v_mfma_f32_16x16x32_bf16 v[108:111], v[154:157], v[186:189], v[108:111]
	v_mfma_f32_16x16x32_bf16 v[100:103], v[146:149], v[214:217], v[100:103]
	v_mfma_f32_16x16x32_bf16 v[92:95], v[154:157], v[214:217], v[92:95]
	v_mfma_f32_16x16x32_bf16 v[84:87], v[146:149], v[222:225], v[84:87]
	v_mfma_f32_16x16x32_bf16 v[76:79], v[154:157], v[222:225], v[76:79]
	s_setprio 0
	s_setprio 1
	v_mfma_f32_16x16x32_bf16 v[112:115], v[158:161], v[174:177], 0
	v_mfma_f32_16x16x32_bf16 v[104:107], v[166:169], v[174:177], 0
	v_mfma_f32_16x16x32_bf16 v[96:99], v[158:161], v[182:185], 0
	v_mfma_f32_16x16x32_bf16 v[88:91], v[166:169], v[182:185], 0
	v_mfma_f32_16x16x32_bf16 v[80:83], v[158:161], v[210:213], 0
	v_mfma_f32_16x16x32_bf16 v[72:75], v[166:169], v[210:213], 0
	v_mfma_f32_16x16x32_bf16 v[68:71], v[158:161], v[218:221], 0
	v_mfma_f32_16x16x32_bf16 v[64:67], v[166:169], v[218:221], 0
	v_mfma_f32_16x16x32_bf16 v[112:115], v[162:165], v[178:181], v[112:115]
	v_mfma_f32_16x16x32_bf16 v[104:107], v[170:173], v[178:181], v[104:107]
	v_mfma_f32_16x16x32_bf16 v[96:99], v[162:165], v[186:189], v[96:99]
	v_mfma_f32_16x16x32_bf16 v[88:91], v[170:173], v[186:189], v[88:91]
	v_mfma_f32_16x16x32_bf16 v[80:83], v[162:165], v[214:217], v[80:83]
	v_mfma_f32_16x16x32_bf16 v[72:75], v[170:173], v[214:217], v[72:75]
	v_mfma_f32_16x16x32_bf16 v[68:71], v[162:165], v[222:225], v[68:71]
	v_mfma_f32_16x16x32_bf16 v[64:67], v[170:173], v[222:225], v[64:67]
	s_barrier
	s_setprio 0
	s_add_i32 s11, s11, s29
	s_mov_b32 m0, s11
	ds_read_b128 v[174:177], v141 offset:16384
	ds_read_b128 v[178:181], v141 offset:17408
	ds_read_b128 v[182:185], v141 offset:18432
	ds_read_b128 v[186:189], v141 offset:19456
	ds_read_b128 v[210:213], v141 offset:20480
	ds_read_b128 v[214:217], v141 offset:21504
	ds_read_b128 v[218:221], v141 offset:22528
	ds_read_b128 v[222:225], v141 offset:23552
	global_load_lds_dwordx4 v132, vcc
	s_add_i32 m0, s11, 0x2000
	s_add_u32 s54, vcc_lo, 0x80000
	s_addc_u32 s55, vcc_hi, 0
	s_add_i32 s11, s21, s29
	global_load_lds_dwordx4 v128, vcc
	s_mov_b32 m0, s11
	s_nop 0
	global_load_lds_dwordx4 v132, s[54:55]
	s_add_i32 m0, s11, 0x2000
	s_nop 0
	global_load_lds_dwordx4 v128, s[54:55]
	s_mov_b32 m0, s13
	s_nop 0
	global_load_lds_dwordx4 v134, s[40:41]
	s_mov_b32 m0, s67
	s_nop 0
	global_load_lds_dwordx4 v130, s[40:41]
	s_waitcnt vmcnt(8)
	s_waitcnt lgkmcnt(0)
	s_setprio 1
	s_barrier
; #define PG8_STAGE(bufoff, gbase, voff) do { _Pragma("unroll") for (int _i = 0; _i < 2; ++_i) \
;         __builtin_amdgcn_global_load_lds((const unsigned*)((const char*)(gbase) + (voff)[_i]), (PG8_LAS unsigned*)(lds + (bufoff) + ldsw + _i * 8192), 16, 0, 0); } while (0)
; #define PG8_LDA(dst, b, h) do { _Pragma("unroll") for (int m = 0; m < 4; ++m) _Pragma("unroll") for (int k = 0; k < 2; ++k) dst[m][k] = *(const PG8_LAS bf16x8*)(lds + PG8_SA(b, h) + aoff + m * 2048 + k * 1024); } while (0)
; #define PG8_LDB(dst, b, h) do { _Pragma("unroll") for (int n = 0; n < 2; ++n) _Pragma("unroll") for (int k = 0; k < 2; ++k) dst[n][k] = *(const PG8_LAS bf16x8*)(lds + PG8_SB(b, h) + boff + n * 2048 + k * 1024); } while (0)
; #define PG8_MMA(ai, bj, At, Bt) do { __builtin_amdgcn_s_setprio(1); _Pragma("unroll") for (int m = 0; m < 4; ++m) _Pragma("unroll") for (int n = 0; n < 2; ++n) _Pragma("unroll") for (int k = 0; k < 2; ++k) \
;         acc[ai][bj][m][n] = __builtin_amdgcn_mfma_f32_16x16x32_bf16(Bt[n][k], At[m][k], acc[ai][bj][m][n], 0, 0, 0); __builtin_amdgcn_s_setprio(0); } while (0)
; #define PG8_WAIT_V(n) asm volatile("s_waitcnt vmcnt(" #n ")" ::: "memory")
; #define PG8_WAIT_L(n) asm volatile("s_waitcnt lgkmcnt(" #n ")" ::: "memory")
; #define PG8_BAR __builtin_amdgcn_s_barrier()
; #define PG8_SCHED __builtin_amdgcn_sched_barrier(0)
; template <class Epi>
; __device__ __forceinline__ void gemm_phase(PG8_LAS unsigned char* lds, PG8_LAS unsigned char* xl, const Gemm g, const Sched& S, const Epi& E, const int wid) {
;     ...
;             PG8_WAIT_V(8); PG8_WAIT_L(0); PG8_BAR; if (do1) { PG8_MMA(1, 0, At, B0); PG8_MMA(1, 1, At, B1); } PG8_BAR; PG8_SCHED;
;             PG8_LDB(B0, 1, 0); PG8_LDB(B1, 1, 1); PG8_SCHED; PG8_LDA(At, 1, 0); PG8_STAGE(PG8_SA(0, 1), a2 + hstepA, voffA);
;             PG8_WAIT_V(8); PG8_WAIT_L(0); PG8_BAR; if (do0) { PG8_MMA(0, 0, At, B0); PG8_MMA(0, 1, At, B1); } PG8_BAR; PG8_SCHED;
	v_mfma_f32_16x16x32_bf16 v[60:63], v[142:145], v[174:177], 0
	v_mfma_f32_16x16x32_bf16 v[56:59], v[150:153], v[174:177], 0
	v_mfma_f32_16x16x32_bf16 v[52:55], v[142:145], v[182:185], 0
	v_mfma_f32_16x16x32_bf16 v[44:47], v[150:153], v[182:185], 0
	v_mfma_f32_16x16x32_bf16 v[36:39], v[142:145], v[210:213], 0
	v_mfma_f32_16x16x32_bf16 v[28:31], v[150:153], v[210:213], 0
	v_mfma_f32_16x16x32_bf16 v[20:23], v[142:145], v[218:221], 0
	v_mfma_f32_16x16x32_bf16 v[12:15], v[150:153], v[218:221], 0
	v_mfma_f32_16x16x32_bf16 v[60:63], v[146:149], v[178:181], v[60:63]
	v_mfma_f32_16x16x32_bf16 v[56:59], v[154:157], v[178:181], v[56:59]
	v_mfma_f32_16x16x32_bf16 v[52:55], v[146:149], v[186:189], v[52:55]
	v_mfma_f32_16x16x32_bf16 v[44:47], v[154:157], v[186:189], v[44:47]
	v_mfma_f32_16x16x32_bf16 v[36:39], v[146:149], v[214:217], v[36:39]
	v_mfma_f32_16x16x32_bf16 v[28:31], v[154:157], v[214:217], v[28:31]
	v_mfma_f32_16x16x32_bf16 v[20:23], v[146:149], v[222:225], v[20:23]
	v_mfma_f32_16x16x32_bf16 v[12:15], v[154:157], v[222:225], v[12:15]
	s_setprio 0
	s_setprio 1
	v_mfma_f32_16x16x32_bf16 v[48:51], v[158:161], v[174:177], 0
	v_mfma_f32_16x16x32_bf16 v[40:43], v[166:169], v[174:177], 0
	v_mfma_f32_16x16x32_bf16 v[32:35], v[158:161], v[182:185], 0
	v_mfma_f32_16x16x32_bf16 v[24:27], v[166:169], v[182:185], 0
	v_mfma_f32_16x16x32_bf16 v[16:19], v[158:161], v[210:213], 0
	v_mfma_f32_16x16x32_bf16 v[8:11], v[166:169], v[210:213], 0
	v_mfma_f32_16x16x32_bf16 v[4:7], v[158:161], v[218:221], 0
	v_mfma_f32_16x16x32_bf16 v[0:3], v[166:169], v[218:221], 0
	v_mfma_f32_16x16x32_bf16 v[48:51], v[162:165], v[178:181], v[48:51]
	v_mfma_f32_16x16x32_bf16 v[40:43], v[170:173], v[178:181], v[40:43]
	v_mfma_f32_16x16x32_bf16 v[32:35], v[162:165], v[186:189], v[32:35]
	v_mfma_f32_16x16x32_bf16 v[24:27], v[170:173], v[186:189], v[24:27]
	v_mfma_f32_16x16x32_bf16 v[16:19], v[162:165], v[214:217], v[16:19]
	v_mfma_f32_16x16x32_bf16 v[8:11], v[170:173], v[214:217], v[8:11]
	v_mfma_f32_16x16x32_bf16 v[4:7], v[162:165], v[222:225], v[4:7]
	v_mfma_f32_16x16x32_bf16 v[0:3], v[170:173], v[222:225], v[0:3]
	s_barrier
	s_setprio 0
	s_add_i32 s11, 0, 0x18000
	s_add_i32 s21, 0, 0x1c000
	ds_read_b128 v[142:145], v228 offset:32768
	ds_read_b128 v[146:149], v228 offset:33792
	ds_read_b128 v[150:153], v228 offset:34816
	ds_read_b128 v[154:157], v228 offset:35840
	ds_read_b128 v[158:161], v228 offset:49152
	ds_read_b128 v[162:165], v228 offset:50176
	ds_read_b128 v[166:169], v228 offset:51200
	ds_read_b128 v[170:173], v228 offset:52224
	s_add_u32 s100, s40, 0x100000
	s_addc_u32 s101, s41, 0
	s_mov_b32 m0, s68
	ds_read_b128 v[174:177], v141 offset:32768
	ds_read_b128 v[178:181], v141 offset:33792
	ds_read_b128 v[182:185], v141 offset:34816
	ds_read_b128 v[186:189], v141 offset:35840
	ds_read_b128 v[210:213], v141 offset:36864
	ds_read_b128 v[214:217], v141 offset:37888
	ds_read_b128 v[218:221], v141 offset:38912
	ds_read_b128 v[222:225], v141 offset:39936
	global_load_lds_dwordx4 v134, s[100:101]
	s_mov_b32 m0, s69
	s_nop 0
	global_load_lds_dwordx4 v130, s[100:101]
	s_waitcnt vmcnt(8)
	s_waitcnt lgkmcnt(0)
	s_setprio 1
	s_barrier
	v_mfma_f32_16x16x32_bf16 v[124:127], v[142:145], v[174:177], v[124:127]
	v_mfma_f32_16x16x32_bf16 v[120:123], v[150:153], v[174:177], v[120:123]
	v_mfma_f32_16x16x32_bf16 v[116:119], v[142:145], v[182:185], v[116:119]
	v_mfma_f32_16x16x32_bf16 v[108:111], v[150:153], v[182:185], v[108:111]
	v_mfma_f32_16x16x32_bf16 v[100:103], v[142:145], v[210:213], v[100:103]
	v_mfma_f32_16x16x32_bf16 v[92:95], v[150:153], v[210:213], v[92:95]
	v_mfma_f32_16x16x32_bf16 v[84:87], v[142:145], v[218:221], v[84:87]
	v_mfma_f32_16x16x32_bf16 v[76:79], v[150:153], v[218:221], v[76:79]
	v_mfma_f32_16x16x32_bf16 v[124:127], v[146:149], v[178:181], v[124:127]
	v_mfma_f32_16x16x32_bf16 v[120:123], v[154:157], v[178:181], v[120:123]
	v_mfma_f32_16x16x32_bf16 v[116:119], v[146:149], v[186:189], v[116:119]
	v_mfma_f32_16x16x32_bf16 v[108:111], v[154:157], v[186:189], v[108:111]
	v_mfma_f32_16x16x32_bf16 v[100:103], v[146:149], v[214:217], v[100:103]
	v_mfma_f32_16x16x32_bf16 v[92:95], v[154:157], v[214:217], v[92:95]
	v_mfma_f32_16x16x32_bf16 v[84:87], v[146:149], v[222:225], v[84:87]
	v_mfma_f32_16x16x32_bf16 v[76:79], v[154:157], v[222:225], v[76:79]
	s_setprio 0
	s_setprio 1
	v_mfma_f32_16x16x32_bf16 v[112:115], v[158:161], v[174:177], v[112:115]
	v_mfma_f32_16x16x32_bf16 v[104:107], v[166:169], v[174:177], v[104:107]
	v_mfma_f32_16x16x32_bf16 v[96:99], v[158:161], v[182:185], v[96:99]
	v_mfma_f32_16x16x32_bf16 v[88:91], v[166:169], v[182:185], v[88:91]
	v_mfma_f32_16x16x32_bf16 v[80:83], v[158:161], v[210:213], v[80:83]
	v_mfma_f32_16x16x32_bf16 v[72:75], v[166:169], v[210:213], v[72:75]
	v_mfma_f32_16x16x32_bf16 v[68:71], v[158:161], v[218:221], v[68:71]
	v_mfma_f32_16x16x32_bf16 v[64:67], v[166:169], v[218:221], v[64:67]
	v_mfma_f32_16x16x32_bf16 v[112:115], v[162:165], v[178:181], v[112:115]
	v_mfma_f32_16x16x32_bf16 v[104:107], v[170:173], v[178:181], v[104:107]
	v_mfma_f32_16x16x32_bf16 v[96:99], v[162:165], v[186:189], v[96:99]
	v_mfma_f32_16x16x32_bf16 v[88:91], v[170:173], v[186:189], v[88:91]
	v_mfma_f32_16x16x32_bf16 v[80:83], v[162:165], v[214:217], v[80:83]
	v_mfma_f32_16x16x32_bf16 v[72:75], v[170:173], v[214:217], v[72:75]
	v_mfma_f32_16x16x32_bf16 v[68:71], v[162:165], v[222:225], v[68:71]
	v_mfma_f32_16x16x32_bf16 v[64:67], v[170:173], v[222:225], v[64:67]
	s_barrier
; #define PG8_STAGE(bufoff, gbase, voff) do { _Pragma("unroll") for (int _i = 0; _i < 2; ++_i) \
;         __builtin_amdgcn_global_load_lds((const unsigned*)((const char*)(gbase) + (voff)[_i]), (PG8_LAS unsigned*)(lds + (bufoff) + ldsw + _i * 8192), 16, 0, 0); } while (0)
; #define PG8_LDA(dst, b, h) do { _Pragma("unroll") for (int m = 0; m < 4; ++m) _Pragma("unroll") for (int k = 0; k < 2; ++k) dst[m][k] = *(const PG8_LAS bf16x8*)(lds + PG8_SA(b, h) + aoff + m * 2048 + k * 1024); } while (0)
; #define PG8_MMA(ai, bj, At, Bt) do { __builtin_amdgcn_s_setprio(1); _Pragma("unroll") for (int m = 0; m < 4; ++m) _Pragma("unroll") for (int n = 0; n < 2; ++n) _Pragma("unroll") for (int k = 0; k < 2; ++k) \
;         acc[ai][bj][m][n] = __builtin_amdgcn_mfma_f32_16x16x32_bf16(Bt[n][k], At[m][k], acc[ai][bj][m][n], 0, 0, 0); __builtin_amdgcn_s_setprio(0); } while (0)
; #define PG8_WAIT_V(n) asm volatile("s_waitcnt vmcnt(" #n ")" ::: "memory")
; #define PG8_WAIT_L(n) asm volatile("s_waitcnt lgkmcnt(" #n ")" ::: "memory")
; #define PG8_BAR __builtin_amdgcn_s_barrier()
; #define PG8_SCHED __builtin_amdgcn_sched_barrier(0)
; template <class Epi>
; __device__ __forceinline__ void gemm_phase(PG8_LAS unsigned char* lds, PG8_LAS unsigned char* xl, const Gemm g, const Sched& S, const Epi& E, const int wid) {
;     ...
;             PG8_LDA(At, 1, 1); PG8_STAGE(PG8_SB(1, 0), b3, voffB); PG8_STAGE(PG8_SB(1, 1), b3 + hstepB, voffB); PG8_STAGE(PG8_SA(1, 0), a3, voffA);
;             PG8_WAIT_V(8); PG8_WAIT_L(0); PG8_BAR; if (do1) { PG8_MMA(1, 0, At, B0); PG8_MMA(1, 1, At, B1); } PG8_BAR; PG8_SCHED;
;         }
	s_setprio 0
	s_add_i32 s11, s11, s29
	s_mov_b32 m0, s11
	ds_read_b128 v[174:177], v141 offset:49152
	ds_read_b128 v[178:181], v141 offset:50176
	ds_read_b128 v[182:185], v141 offset:51200
	ds_read_b128 v[186:189], v141 offset:52224
	ds_read_b128 v[210:213], v141 offset:53248
	ds_read_b128 v[214:217], v141 offset:54272
	ds_read_b128 v[218:221], v141 offset:55296
	ds_read_b128 v[222:225], v141 offset:56320
	global_load_lds_dwordx4 v226, vcc
	s_add_i32 m0, s11, 0x2000
	s_add_u32 s100, vcc_lo, 0x80080
	global_load_lds_dwordx4 v190, vcc
	s_addc_u32 s101, vcc_hi, 0
	s_add_i32 s11, s21, s29
	s_mov_b32 m0, s11
	s_nop 0
	global_load_lds_dwordx4 v132, s[100:101]
	s_add_i32 m0, s11, 0x2000
	s_nop 0
	global_load_lds_dwordx4 v128, s[100:101]
	s_mov_b32 m0, s88
	s_nop 0
	global_load_lds_dwordx4 v227, s[40:41]
	s_mov_b32 m0, s89
	s_nop 0
	global_load_lds_dwordx4 v191, s[40:41]
	s_waitcnt vmcnt(8)
	s_waitcnt lgkmcnt(0)
	s_setprio 1
	s_barrier
	v_mfma_f32_16x16x32_bf16 v[60:63], v[142:145], v[174:177], v[60:63]
	v_mfma_f32_16x16x32_bf16 v[56:59], v[150:153], v[174:177], v[56:59]
	v_mfma_f32_16x16x32_bf16 v[52:55], v[142:145], v[182:185], v[52:55]
	v_mfma_f32_16x16x32_bf16 v[44:47], v[150:153], v[182:185], v[44:47]
	v_mfma_f32_16x16x32_bf16 v[36:39], v[142:145], v[210:213], v[36:39]
	v_mfma_f32_16x16x32_bf16 v[28:31], v[150:153], v[210:213], v[28:31]
	v_mfma_f32_16x16x32_bf16 v[20:23], v[142:145], v[218:221], v[20:23]
	v_mfma_f32_16x16x32_bf16 v[12:15], v[150:153], v[218:221], v[12:15]
	v_mfma_f32_16x16x32_bf16 v[60:63], v[146:149], v[178:181], v[60:63]
	v_mfma_f32_16x16x32_bf16 v[56:59], v[154:157], v[178:181], v[56:59]
	v_mfma_f32_16x16x32_bf16 v[52:55], v[146:149], v[186:189], v[52:55]
	v_mfma_f32_16x16x32_bf16 v[44:47], v[154:157], v[186:189], v[44:47]
	v_mfma_f32_16x16x32_bf16 v[36:39], v[146:149], v[214:217], v[36:39]
	v_mfma_f32_16x16x32_bf16 v[28:31], v[154:157], v[214:217], v[28:31]
	v_mfma_f32_16x16x32_bf16 v[20:23], v[146:149], v[222:225], v[20:23]
	v_mfma_f32_16x16x32_bf16 v[12:15], v[154:157], v[222:225], v[12:15]
	s_setprio 0
	s_setprio 1
	v_mfma_f32_16x16x32_bf16 v[48:51], v[158:161], v[174:177], v[48:51]
	v_mfma_f32_16x16x32_bf16 v[40:43], v[166:169], v[174:177], v[40:43]
	v_mfma_f32_16x16x32_bf16 v[32:35], v[158:161], v[182:185], v[32:35]
	v_mfma_f32_16x16x32_bf16 v[24:27], v[166:169], v[182:185], v[24:27]
	v_mfma_f32_16x16x32_bf16 v[16:19], v[158:161], v[210:213], v[16:19]
	v_mfma_f32_16x16x32_bf16 v[8:11], v[166:169], v[210:213], v[8:11]
	v_mfma_f32_16x16x32_bf16 v[4:7], v[158:161], v[218:221], v[4:7]
	v_mfma_f32_16x16x32_bf16 v[0:3], v[166:169], v[218:221], v[0:3]
	v_mfma_f32_16x16x32_bf16 v[48:51], v[162:165], v[178:181], v[48:51]
	v_mfma_f32_16x16x32_bf16 v[40:43], v[170:173], v[178:181], v[40:43]
	v_mfma_f32_16x16x32_bf16 v[32:35], v[162:165], v[186:189], v[32:35]
	v_mfma_f32_16x16x32_bf16 v[24:27], v[170:173], v[186:189], v[24:27]
	v_mfma_f32_16x16x32_bf16 v[16:19], v[162:165], v[214:217], v[16:19]
	v_mfma_f32_16x16x32_bf16 v[8:11], v[170:173], v[214:217], v[8:11]
	v_mfma_f32_16x16x32_bf16 v[4:7], v[162:165], v[222:225], v[4:7]
	v_mfma_f32_16x16x32_bf16 v[0:3], v[170:173], v[222:225], v[0:3]
	s_barrier
	s_setprio 0
	s_add_i32 s10, s10, 2
	s_add_u32 s8, s8, 0x100
	s_addc_u32 s9, s9, 0
	s_cmp_gt_u32 s10, 5
	s_mov_b64 s[60:61], s[76:77]

; #define PG8_STAGE(bufoff, gbase, voff) do { _Pragma("unroll") for (int _i = 0; _i < 2; ++_i) \
;         __builtin_amdgcn_global_load_lds((const unsigned*)((const char*)(gbase) + (voff)[_i]), (PG8_LAS unsigned*)(lds + (bufoff) + ldsw + _i * 8192), 16, 0, 0); } while (0)
; #define PG8_LDA(dst, b, h) do { _Pragma("unroll") for (int m = 0; m < 4; ++m) _Pragma("unroll") for (int k = 0; k < 2; ++k) dst[m][k] = *(const PG8_LAS bf16x8*)(lds + PG8_SA(b, h) + aoff + m * 2048 + k * 1024); } while (0)
; #define PG8_LDB(dst, b, h) do { _Pragma("unroll") for (int n = 0; n < 2; ++n) _Pragma("unroll") for (int k = 0; k < 2; ++k) dst[n][k] = *(const PG8_LAS bf16x8*)(lds + PG8_SB(b, h) + boff + n * 2048 + k * 1024); } while (0)
; #define PG8_MMA(ai, bj, At, Bt) do { __builtin_amdgcn_s_setprio(1); _Pragma("unroll") for (int m = 0; m < 4; ++m) _Pragma("unroll") for (int n = 0; n < 2; ++n) _Pragma("unroll") for (int k = 0; k < 2; ++k) \
;         acc[ai][bj][m][n] = __builtin_amdgcn_mfma_f32_16x16x32_bf16(Bt[n][k], At[m][k], acc[ai][bj][m][n], 0, 0, 0); __builtin_amdgcn_s_setprio(0); } while (0)
; #define PG8_WAIT_V(n) asm volatile("s_waitcnt vmcnt(" #n ")" ::: "memory")
; #define PG8_WAIT_L(n) asm volatile("s_waitcnt lgkmcnt(" #n ")" ::: "memory")
; template <class Epi>
; __device__ __forceinline__ void gemm_phase(PG8_LAS unsigned char* lds, PG8_LAS unsigned char* xl, const Gemm g, const Sched& S, const Epi& E, const int wid) {
;     ...
;             const char* a1 = cA + (size_t)(t + 1) * kstep + j1;
;             const char* a2 = last ? nA : cA + (size_t)(t + 2) * kstep + ja2; const char* b2 = last ? nB : cB + (size_t)(t + 2) * kstep + jb2;
;             const char* a3 = a2 + kstep; const char* b3 = b2 + kstep;
;             PG8_LDB(B0, 0, 0); PG8_LDB(B1, 0, 1); PG8_SCHED; PG8_LDA(At, 0, 0); PG8_STAGE(PG8_SA(1, 1), a1 + hstepA, voffA);
;             PG8_WAIT_V(8); PG8_WAIT_L(0); PG8_BAR; if (do0) { PG8_MMA(0, 0, At, B0); PG8_MMA(0, 1, At, B1); } PG8_BAR; PG8_SCHED;
;             PG8_LDA(At, 0, 1); PG8_STAGE(PG8_SB(0, 0), b2, voffB); PG8_STAGE(PG8_SB(0, 1), b2 + hstepB, voffB); PG8_STAGE(PG8_SA(0, 0), a2, voffA);
;     ...
;         for (int a = 0; a < 2; ++a)
; #pragma unroll
;             for (int b = 0; b < 2; ++b)
; #pragma unroll
;                 for (int m = 0; m < 4; ++m)
; #pragma unroll
;                     for (int n = 0; n < 2; ++n) acc[a][b][m][n] = (f32x4){0.f, 0.f, 0.f, 0.f};
.LBB0_427:
	s_add_u32 s8, s60, 0x100
	s_addc_u32 s9, s61, 0
	s_mov_b32 s10, -2
	s_cmp_lg_u32 s100, 1
	s_cbranch_scc1 .Ldefbar_skip_3
	s_mov_b32 s100, 0
	s_barrier
.Ldefbar_skip_3:
	v_add_u32_e32 v190, s22, v128
	v_add_u32_e32 v191, s22, v130
	v_add_u32_e32 v226, s22, v132
	v_add_u32_e32 v227, s22, v134
	v_add_u32_e32 v228, 0x10000, v140
	s_add_u32 s60, s58, 0x100
	s_addc_u32 s61, s59, 0
	s_add_i32 s11, 0, 0x10000
	s_cmp_eq_u32 s10, 4
	s_cselect_b32 s41, s47, s61
	s_cselect_b32 s40, s46, s60
	s_cselect_b32 s77, s57, s9
	s_cselect_b32 s76, s56, s8
	s_add_i32 s21, 0, 0x14000
	ds_read_b128 v[142:145], v228 offset:0
	ds_read_b128 v[146:149], v228 offset:1024
	ds_read_b128 v[150:153], v228 offset:2048
	ds_read_b128 v[154:157], v228 offset:3072
	ds_read_b128 v[158:161], v228 offset:16384
	ds_read_b128 v[162:165], v228 offset:17408
	ds_read_b128 v[166:169], v228 offset:18432
	ds_read_b128 v[170:173], v228 offset:19456
	s_add_i32 m0, s13, 0xc000
	ds_read_b128 v[174:177], v141
	ds_read_b128 v[178:181], v141 offset:1024
	ds_read_b128 v[182:185], v141 offset:2048
	ds_read_b128 v[186:189], v141 offset:3072
	ds_read_b128 v[210:213], v141 offset:4096
	ds_read_b128 v[214:217], v141 offset:5120
	ds_read_b128 v[218:221], v141 offset:6144
	ds_read_b128 v[222:225], v141 offset:7168
	global_load_lds_dwordx4 v136, s[58:59]
	s_add_i32 m0, s13, 0xe000
	s_nop 0
	global_load_lds_dwordx4 v138, s[58:59]
	s_waitcnt vmcnt(8)
	s_waitcnt lgkmcnt(0)
	s_setprio 1
	s_barrier
	v_mfma_f32_16x16x32_bf16 v[124:127], v[142:145], v[174:177], 0
	v_mfma_f32_16x16x32_bf16 v[120:123], v[150:153], v[174:177], 0
	v_mfma_f32_16x16x32_bf16 v[116:119], v[142:145], v[182:185], 0
	v_mfma_f32_16x16x32_bf16 v[108:111], v[150:153], v[182:185], 0
	v_mfma_f32_16x16x32_bf16 v[100:103], v[142:145], v[210:213], 0
	v_mfma_f32_16x16x32_bf16 v[92:95], v[150:153], v[210:213], 0
	v_mfma_f32_16x16x32_bf16 v[84:87], v[142:145], v[218:221], 0
	v_mfma_f32_16x16x32_bf16 v[76:79], v[150:153], v[218:221], 0
	v_mfma_f32_16x16x32_bf16 v[124:127], v[146:149], v[178:181], v[124:127]
	v_mfma_f32_16x16x32_bf16 v[120:123], v[154:157], v[178:181], v[120:123]
	v_mfma_f32_16x16x32_bf16 v[116:119], v[146:149], v[186:189], v[116:119]
	v_mfma_f32_16x16x32_bf16 v[108:111], v[154:157], v[186:189], v[108:111]
	v_mfma_f32_16x16x32_bf16 v[100:103], v[146:149], v[214:217], v[100:103]
	v_mfma_f32_16x16x32_bf16 v[92:95], v[154:157], v[214:217], v[92:95]
	v_mfma_f32_16x16x32_bf16 v[84:87], v[146:149], v[222:225], v[84:87]
	v_mfma_f32_16x16x32_bf16 v[76:79], v[154:157], v[222:225], v[76:79]
	s_setprio 0
	s_setprio 1
	v_mfma_f32_16x16x32_bf16 v[112:115], v[158:161], v[174:177], 0
	v_mfma_f32_16x16x32_bf16 v[104:107], v[166:169], v[174:177], 0
	v_mfma_f32_16x16x32_bf16 v[96:99], v[158:161], v[182:185], 0
	v_mfma_f32_16x16x32_bf16 v[88:91], v[166:169], v[182:185], 0
	v_mfma_f32_16x16x32_bf16 v[80:83], v[158:161], v[210:213], 0
	v_mfma_f32_16x16x32_bf16 v[72:75], v[166:169], v[210:213], 0
	v_mfma_f32_16x16x32_bf16 v[68:71], v[158:161], v[218:221], 0
	v_mfma_f32_16x16x32_bf16 v[64:67], v[166:169], v[218:221], 0
	v_mfma_f32_16x16x32_bf16 v[112:115], v[162:165], v[178:181], v[112:115]
	v_mfma_f32_16x16x32_bf16 v[104:107], v[170:173], v[178:181], v[104:107]
	v_mfma_f32_16x16x32_bf16 v[96:99], v[162:165], v[186:189], v[96:99]
	v_mfma_f32_16x16x32_bf16 v[88:91], v[170:173], v[186:189], v[88:91]
	v_mfma_f32_16x16x32_bf16 v[80:83], v[162:165], v[214:217], v[80:83]
	v_mfma_f32_16x16x32_bf16 v[72:75], v[170:173], v[214:217], v[72:75]
	v_mfma_f32_16x16x32_bf16 v[68:71], v[162:165], v[222:225], v[68:71]
	v_mfma_f32_16x16x32_bf16 v[64:67], v[170:173], v[222:225], v[64:67]
	s_barrier
	s_setprio 0
	s_add_i32 s11, s11, s29
	s_mov_b32 m0, s11
	ds_read_b128 v[174:177], v141 offset:16384
	ds_read_b128 v[178:181], v141 offset:17408
	ds_read_b128 v[182:185], v141 offset:18432
	ds_read_b128 v[186:189], v141 offset:19456
	ds_read_b128 v[210:213], v141 offset:20480
	ds_read_b128 v[214:217], v141 offset:21504
	ds_read_b128 v[218:221], v141 offset:22528
	ds_read_b128 v[222:225], v141 offset:23552
	global_load_lds_dwordx4 v132, s[76:77]
	s_add_i32 m0, s11, 0x2000
	s_add_u32 s54, s76, 0x100000
	s_addc_u32 s55, s77, 0
	s_add_i32 s11, s21, s29
	global_load_lds_dwordx4 v128, s[76:77]
	s_mov_b32 m0, s11
	s_nop 0
	global_load_lds_dwordx4 v132, s[54:55]
	s_add_i32 m0, s11, 0x2000
	s_nop 0
	global_load_lds_dwordx4 v128, s[54:55]
	s_mov_b32 m0, s13
	s_nop 0
	global_load_lds_dwordx4 v134, s[40:41]
	s_mov_b32 m0, s69
	s_nop 0
	global_load_lds_dwordx4 v130, s[40:41]
	s_waitcnt vmcnt(8)
	s_waitcnt lgkmcnt(0)
	s_setprio 1
	s_barrier
; #define PG8_STAGE(bufoff, gbase, voff) do { _Pragma("unroll") for (int _i = 0; _i < 2; ++_i) \
;         __builtin_amdgcn_global_load_lds((const unsigned*)((const char*)(gbase) + (voff)[_i]), (PG8_LAS unsigned*)(lds + (bufoff) + ldsw + _i * 8192), 16, 0, 0); } while (0)
; #define PG8_LDA(dst, b, h) do { _Pragma("unroll") for (int m = 0; m < 4; ++m) _Pragma("unroll") for (int k = 0; k < 2; ++k) dst[m][k] = *(const PG8_LAS bf16x8*)(lds + PG8_SA(b, h) + aoff + m * 2048 + k * 1024); } while (0)
; #define PG8_LDB(dst, b, h) do { _Pragma("unroll") for (int n = 0; n < 2; ++n) _Pragma("unroll") for (int k = 0; k < 2; ++k) dst[n][k] = *(const PG8_LAS bf16x8*)(lds + PG8_SB(b, h) + boff + n * 2048 + k * 1024); } while (0)
; #define PG8_MMA(ai, bj, At, Bt) do { __builtin_amdgcn_s_setprio(1); _Pragma("unroll") for (int m = 0; m < 4; ++m) _Pragma("unroll") for (int n = 0; n < 2; ++n) _Pragma("unroll") for (int k = 0; k < 2; ++k) \
;         acc[ai][bj][m][n] = __builtin_amdgcn_mfma_f32_16x16x32_bf16(Bt[n][k], At[m][k], acc[ai][bj][m][n], 0, 0, 0); __builtin_amdgcn_s_setprio(0); } while (0)
; #define PG8_WAIT_V(n) asm volatile("s_waitcnt vmcnt(" #n ")" ::: "memory")
; #define PG8_WAIT_L(n) asm volatile("s_waitcnt lgkmcnt(" #n ")" ::: "memory")
; #define PG8_BAR __builtin_amdgcn_s_barrier()
; #define PG8_SCHED __builtin_amdgcn_sched_barrier(0)
; template <class Epi>
; __device__ __forceinline__ void gemm_phase(PG8_LAS unsigned char* lds, PG8_LAS unsigned char* xl, const Gemm g, const Sched& S, const Epi& E, const int wid) {
;     ...
;             PG8_WAIT_V(8); PG8_WAIT_L(0); PG8_BAR; if (do1) { PG8_MMA(1, 0, At, B0); PG8_MMA(1, 1, At, B1); } PG8_BAR; PG8_SCHED;
;             PG8_LDB(B0, 1, 0); PG8_LDB(B1, 1, 1); PG8_SCHED; PG8_LDA(At, 1, 0); PG8_STAGE(PG8_SA(0, 1), a2 + hstepA, voffA);
;             PG8_WAIT_V(8); PG8_WAIT_L(0); PG8_BAR; if (do0) { PG8_MMA(0, 0, At, B0); PG8_MMA(0, 1, At, B1); } PG8_BAR; PG8_SCHED;
	v_mfma_f32_16x16x32_bf16 v[60:63], v[142:145], v[174:177], 0
	v_mfma_f32_16x16x32_bf16 v[56:59], v[150:153], v[174:177], 0
	v_mfma_f32_16x16x32_bf16 v[52:55], v[142:145], v[182:185], 0
	v_mfma_f32_16x16x32_bf16 v[44:47], v[150:153], v[182:185], 0
	v_mfma_f32_16x16x32_bf16 v[36:39], v[142:145], v[210:213], 0
	v_mfma_f32_16x16x32_bf16 v[28:31], v[150:153], v[210:213], 0
	v_mfma_f32_16x16x32_bf16 v[20:23], v[142:145], v[218:221], 0
	v_mfma_f32_16x16x32_bf16 v[12:15], v[150:153], v[218:221], 0
	v_mfma_f32_16x16x32_bf16 v[60:63], v[146:149], v[178:181], v[60:63]
	v_mfma_f32_16x16x32_bf16 v[56:59], v[154:157], v[178:181], v[56:59]
	v_mfma_f32_16x16x32_bf16 v[52:55], v[146:149], v[186:189], v[52:55]
	v_mfma_f32_16x16x32_bf16 v[44:47], v[154:157], v[186:189], v[44:47]
	v_mfma_f32_16x16x32_bf16 v[36:39], v[146:149], v[214:217], v[36:39]
	v_mfma_f32_16x16x32_bf16 v[28:31], v[154:157], v[214:217], v[28:31]
	v_mfma_f32_16x16x32_bf16 v[20:23], v[146:149], v[222:225], v[20:23]
	v_mfma_f32_16x16x32_bf16 v[12:15], v[154:157], v[222:225], v[12:15]
	s_setprio 0
	s_setprio 1
	v_mfma_f32_16x16x32_bf16 v[48:51], v[158:161], v[174:177], 0
	v_mfma_f32_16x16x32_bf16 v[40:43], v[166:169], v[174:177], 0
	v_mfma_f32_16x16x32_bf16 v[32:35], v[158:161], v[182:185], 0
	v_mfma_f32_16x16x32_bf16 v[24:27], v[166:169], v[182:185], 0
	v_mfma_f32_16x16x32_bf16 v[16:19], v[158:161], v[210:213], 0
	v_mfma_f32_16x16x32_bf16 v[8:11], v[166:169], v[210:213], 0
	v_mfma_f32_16x16x32_bf16 v[4:7], v[158:161], v[218:221], 0
	v_mfma_f32_16x16x32_bf16 v[0:3], v[166:169], v[218:221], 0
	v_mfma_f32_16x16x32_bf16 v[48:51], v[162:165], v[178:181], v[48:51]
	v_mfma_f32_16x16x32_bf16 v[40:43], v[170:173], v[178:181], v[40:43]
	v_mfma_f32_16x16x32_bf16 v[32:35], v[162:165], v[186:189], v[32:35]
	v_mfma_f32_16x16x32_bf16 v[24:27], v[170:173], v[186:189], v[24:27]
	v_mfma_f32_16x16x32_bf16 v[16:19], v[162:165], v[214:217], v[16:19]
	v_mfma_f32_16x16x32_bf16 v[8:11], v[170:173], v[214:217], v[8:11]
	v_mfma_f32_16x16x32_bf16 v[4:7], v[162:165], v[222:225], v[4:7]
	v_mfma_f32_16x16x32_bf16 v[0:3], v[170:173], v[222:225], v[0:3]
	s_barrier
	s_setprio 0
	s_add_i32 s11, 0, 0x18000
	s_add_i32 s21, 0, 0x1c000
	ds_read_b128 v[142:145], v228 offset:32768
	ds_read_b128 v[146:149], v228 offset:33792
	ds_read_b128 v[150:153], v228 offset:34816
	ds_read_b128 v[154:157], v228 offset:35840
	ds_read_b128 v[158:161], v228 offset:49152
	ds_read_b128 v[162:165], v228 offset:50176
	ds_read_b128 v[166:169], v228 offset:51200
	ds_read_b128 v[170:173], v228 offset:52224
	s_add_u32 s100, s40, 0x80000
	s_addc_u32 s101, s41, 0
	s_mov_b32 m0, s70
	ds_read_b128 v[174:177], v141 offset:32768
	ds_read_b128 v[178:181], v141 offset:33792
	ds_read_b128 v[182:185], v141 offset:34816
	ds_read_b128 v[186:189], v141 offset:35840
	ds_read_b128 v[210:213], v141 offset:36864
	ds_read_b128 v[214:217], v141 offset:37888
	ds_read_b128 v[218:221], v141 offset:38912
	ds_read_b128 v[222:225], v141 offset:39936
	global_load_lds_dwordx4 v134, s[100:101]
	s_mov_b32 m0, s71
	s_nop 0
	global_load_lds_dwordx4 v130, s[100:101]
	s_waitcnt vmcnt(8)
	s_waitcnt lgkmcnt(0)
	s_setprio 1
	s_barrier
	v_mfma_f32_16x16x32_bf16 v[124:127], v[142:145], v[174:177], v[124:127]
	v_mfma_f32_16x16x32_bf16 v[120:123], v[150:153], v[174:177], v[120:123]
	v_mfma_f32_16x16x32_bf16 v[116:119], v[142:145], v[182:185], v[116:119]
	v_mfma_f32_16x16x32_bf16 v[108:111], v[150:153], v[182:185], v[108:111]
	v_mfma_f32_16x16x32_bf16 v[100:103], v[142:145], v[210:213], v[100:103]
	v_mfma_f32_16x16x32_bf16 v[92:95], v[150:153], v[210:213], v[92:95]
	v_mfma_f32_16x16x32_bf16 v[84:87], v[142:145], v[218:221], v[84:87]
	v_mfma_f32_16x16x32_bf16 v[76:79], v[150:153], v[218:221], v[76:79]
	v_mfma_f32_16x16x32_bf16 v[124:127], v[146:149], v[178:181], v[124:127]
	v_mfma_f32_16x16x32_bf16 v[120:123], v[154:157], v[178:181], v[120:123]
	v_mfma_f32_16x16x32_bf16 v[116:119], v[146:149], v[186:189], v[116:119]
	v_mfma_f32_16x16x32_bf16 v[108:111], v[154:157], v[186:189], v[108:111]
	v_mfma_f32_16x16x32_bf16 v[100:103], v[146:149], v[214:217], v[100:103]
	v_mfma_f32_16x16x32_bf16 v[92:95], v[154:157], v[214:217], v[92:95]
	v_mfma_f32_16x16x32_bf16 v[84:87], v[146:149], v[222:225], v[84:87]
	v_mfma_f32_16x16x32_bf16 v[76:79], v[154:157], v[222:225], v[76:79]
	s_setprio 0
	s_setprio 1
	v_mfma_f32_16x16x32_bf16 v[112:115], v[158:161], v[174:177], v[112:115]
	v_mfma_f32_16x16x32_bf16 v[104:107], v[166:169], v[174:177], v[104:107]
	v_mfma_f32_16x16x32_bf16 v[96:99], v[158:161], v[182:185], v[96:99]
	v_mfma_f32_16x16x32_bf16 v[88:91], v[166:169], v[182:185], v[88:91]
	v_mfma_f32_16x16x32_bf16 v[80:83], v[158:161], v[210:213], v[80:83]
	v_mfma_f32_16x16x32_bf16 v[72:75], v[166:169], v[210:213], v[72:75]
	v_mfma_f32_16x16x32_bf16 v[68:71], v[158:161], v[218:221], v[68:71]
	v_mfma_f32_16x16x32_bf16 v[64:67], v[166:169], v[218:221], v[64:67]
	v_mfma_f32_16x16x32_bf16 v[112:115], v[162:165], v[178:181], v[112:115]
	v_mfma_f32_16x16x32_bf16 v[104:107], v[170:173], v[178:181], v[104:107]
	v_mfma_f32_16x16x32_bf16 v[96:99], v[162:165], v[186:189], v[96:99]
	v_mfma_f32_16x16x32_bf16 v[88:91], v[170:173], v[186:189], v[88:91]
	v_mfma_f32_16x16x32_bf16 v[80:83], v[162:165], v[214:217], v[80:83]
	v_mfma_f32_16x16x32_bf16 v[72:75], v[170:173], v[214:217], v[72:75]
	v_mfma_f32_16x16x32_bf16 v[68:71], v[162:165], v[222:225], v[68:71]
	v_mfma_f32_16x16x32_bf16 v[64:67], v[170:173], v[222:225], v[64:67]
	s_barrier
; #define PG8_STAGE(bufoff, gbase, voff) do { _Pragma("unroll") for (int _i = 0; _i < 2; ++_i) \
;         __builtin_amdgcn_global_load_lds((const unsigned*)((const char*)(gbase) + (voff)[_i]), (PG8_LAS unsigned*)(lds + (bufoff) + ldsw + _i * 8192), 16, 0, 0); } while (0)
; #define PG8_LDA(dst, b, h) do { _Pragma("unroll") for (int m = 0; m < 4; ++m) _Pragma("unroll") for (int k = 0; k < 2; ++k) dst[m][k] = *(const PG8_LAS bf16x8*)(lds + PG8_SA(b, h) + aoff + m * 2048 + k * 1024); } while (0)
; #define PG8_MMA(ai, bj, At, Bt) do { __builtin_amdgcn_s_setprio(1); _Pragma("unroll") for (int m = 0; m < 4; ++m) _Pragma("unroll") for (int n = 0; n < 2; ++n) _Pragma("unroll") for (int k = 0; k < 2; ++k) \
;         acc[ai][bj][m][n] = __builtin_amdgcn_mfma_f32_16x16x32_bf16(Bt[n][k], At[m][k], acc[ai][bj][m][n], 0, 0, 0); __builtin_amdgcn_s_setprio(0); } while (0)
; #define PG8_WAIT_V(n) asm volatile("s_waitcnt vmcnt(" #n ")" ::: "memory")
; #define PG8_WAIT_L(n) asm volatile("s_waitcnt lgkmcnt(" #n ")" ::: "memory")
; #define PG8_BAR __builtin_amdgcn_s_barrier()
; #define PG8_SCHED __builtin_amdgcn_sched_barrier(0)
; template <class Epi>
; __device__ __forceinline__ void gemm_phase(PG8_LAS unsigned char* lds, PG8_LAS unsigned char* xl, const Gemm g, const Sched& S, const Epi& E, const int wid) {
;     ...
;             PG8_LDA(At, 1, 1); PG8_STAGE(PG8_SB(1, 0), b3, voffB); PG8_STAGE(PG8_SB(1, 1), b3 + hstepB, voffB); PG8_STAGE(PG8_SA(1, 0), a3, voffA);
;             PG8_WAIT_V(8); PG8_WAIT_L(0); PG8_BAR; if (do1) { PG8_MMA(1, 0, At, B0); PG8_MMA(1, 1, At, B1); } PG8_BAR; PG8_SCHED;
;         }
	s_setprio 0
	s_add_i32 s11, s11, s29
	s_mov_b32 m0, s11
	ds_read_b128 v[174:177], v141 offset:49152
	ds_read_b128 v[178:181], v141 offset:50176
	ds_read_b128 v[182:185], v141 offset:51200
	ds_read_b128 v[186:189], v141 offset:52224
	ds_read_b128 v[210:213], v141 offset:53248
	ds_read_b128 v[214:217], v141 offset:54272
	ds_read_b128 v[218:221], v141 offset:55296
	ds_read_b128 v[222:225], v141 offset:56320
	global_load_lds_dwordx4 v226, s[76:77]
	s_add_i32 m0, s11, 0x2000
	s_add_u32 s100, s76, 0x100080
	global_load_lds_dwordx4 v190, s[76:77]
	s_addc_u32 s101, s77, 0
	s_add_i32 s11, s21, s29
	s_mov_b32 m0, s11
	s_nop 0
	global_load_lds_dwordx4 v132, s[100:101]
	s_add_i32 m0, s11, 0x2000
	s_nop 0
	global_load_lds_dwordx4 v128, s[100:101]
	s_mov_b32 m0, s90
	s_nop 0
	global_load_lds_dwordx4 v227, s[40:41]
	s_mov_b32 m0, s91
	s_nop 0
	global_load_lds_dwordx4 v191, s[40:41]
	s_waitcnt vmcnt(8)
	s_waitcnt lgkmcnt(0)
	s_setprio 1
	s_barrier
	v_mfma_f32_16x16x32_bf16 v[60:63], v[142:145], v[174:177], v[60:63]
	v_mfma_f32_16x16x32_bf16 v[56:59], v[150:153], v[174:177], v[56:59]
	v_mfma_f32_16x16x32_bf16 v[52:55], v[142:145], v[182:185], v[52:55]
	v_mfma_f32_16x16x32_bf16 v[44:47], v[150:153], v[182:185], v[44:47]
	v_mfma_f32_16x16x32_bf16 v[36:39], v[142:145], v[210:213], v[36:39]
	v_mfma_f32_16x16x32_bf16 v[28:31], v[150:153], v[210:213], v[28:31]
	v_mfma_f32_16x16x32_bf16 v[20:23], v[142:145], v[218:221], v[20:23]
	v_mfma_f32_16x16x32_bf16 v[12:15], v[150:153], v[218:221], v[12:15]
	v_mfma_f32_16x16x32_bf16 v[60:63], v[146:149], v[178:181], v[60:63]
	v_mfma_f32_16x16x32_bf16 v[56:59], v[154:157], v[178:181], v[56:59]
	v_mfma_f32_16x16x32_bf16 v[52:55], v[146:149], v[186:189], v[52:55]
	v_mfma_f32_16x16x32_bf16 v[44:47], v[154:157], v[186:189], v[44:47]
	v_mfma_f32_16x16x32_bf16 v[36:39], v[146:149], v[214:217], v[36:39]
	v_mfma_f32_16x16x32_bf16 v[28:31], v[154:157], v[214:217], v[28:31]
	v_mfma_f32_16x16x32_bf16 v[20:23], v[146:149], v[222:225], v[20:23]
	v_mfma_f32_16x16x32_bf16 v[12:15], v[154:157], v[222:225], v[12:15]
	s_setprio 0
	s_setprio 1
	v_mfma_f32_16x16x32_bf16 v[48:51], v[158:161], v[174:177], v[48:51]
	v_mfma_f32_16x16x32_bf16 v[40:43], v[166:169], v[174:177], v[40:43]
	v_mfma_f32_16x16x32_bf16 v[32:35], v[158:161], v[182:185], v[32:35]
	v_mfma_f32_16x16x32_bf16 v[24:27], v[166:169], v[182:185], v[24:27]
	v_mfma_f32_16x16x32_bf16 v[16:19], v[158:161], v[210:213], v[16:19]
	v_mfma_f32_16x16x32_bf16 v[8:11], v[166:169], v[210:213], v[8:11]
	v_mfma_f32_16x16x32_bf16 v[4:7], v[158:161], v[218:221], v[4:7]
	v_mfma_f32_16x16x32_bf16 v[0:3], v[166:169], v[218:221], v[0:3]
	v_mfma_f32_16x16x32_bf16 v[48:51], v[162:165], v[178:181], v[48:51]
	v_mfma_f32_16x16x32_bf16 v[40:43], v[170:173], v[178:181], v[40:43]
	v_mfma_f32_16x16x32_bf16 v[32:35], v[162:165], v[186:189], v[32:35]
	v_mfma_f32_16x16x32_bf16 v[24:27], v[170:173], v[186:189], v[24:27]
	v_mfma_f32_16x16x32_bf16 v[16:19], v[162:165], v[214:217], v[16:19]
	v_mfma_f32_16x16x32_bf16 v[8:11], v[170:173], v[214:217], v[8:11]
	v_mfma_f32_16x16x32_bf16 v[4:7], v[162:165], v[222:225], v[4:7]
	v_mfma_f32_16x16x32_bf16 v[0:3], v[170:173], v[222:225], v[0:3]
	s_barrier
	s_setprio 0
	s_add_i32 s10, s10, 2
	s_add_u32 s8, s8, 0x100
	s_addc_u32 s9, s9, 0
	s_cmp_gt_u32 s10, 5
	s_mov_b64 s[58:59], s[60:61]

; #define PG8_STAGE(bufoff, gbase, voff) do { _Pragma("unroll") for (int _i = 0; _i < 2; ++_i) \
;         __builtin_amdgcn_global_load_lds((const unsigned*)((const char*)(gbase) + (voff)[_i]), (PG8_LAS unsigned*)(lds + (bufoff) + ldsw + _i * 8192), 16, 0, 0); } while (0)
; #define PG8_LDA(dst, b, h) do { _Pragma("unroll") for (int m = 0; m < 4; ++m) _Pragma("unroll") for (int k = 0; k < 2; ++k) dst[m][k] = *(const PG8_LAS bf16x8*)(lds + PG8_SA(b, h) + aoff + m * 2048 + k * 1024); } while (0)
; #define PG8_LDB(dst, b, h) do { _Pragma("unroll") for (int n = 0; n < 2; ++n) _Pragma("unroll") for (int k = 0; k < 2; ++k) dst[n][k] = *(const PG8_LAS bf16x8*)(lds + PG8_SB(b, h) + boff + n * 2048 + k * 1024); } while (0)
; #define PG8_MMA(ai, bj, At, Bt) do { __builtin_amdgcn_s_setprio(1); _Pragma("unroll") for (int m = 0; m < 4; ++m) _Pragma("unroll") for (int n = 0; n < 2; ++n) _Pragma("unroll") for (int k = 0; k < 2; ++k) \
;         acc[ai][bj][m][n] = __builtin_amdgcn_mfma_f32_16x16x32_bf16(Bt[n][k], At[m][k], acc[ai][bj][m][n], 0, 0, 0); __builtin_amdgcn_s_setprio(0); } while (0)
; #define PG8_WAIT_V(n) asm volatile("s_waitcnt vmcnt(" #n ")" ::: "memory")
; #define PG8_WAIT_L(n) asm volatile("s_waitcnt lgkmcnt(" #n ")" ::: "memory")
; template <class Epi>
; __device__ __forceinline__ void gemm_phase(PG8_LAS unsigned char* lds, PG8_LAS unsigned char* xl, const Gemm g, const Sched& S, const Epi& E, const int wid) {
;     ...
;             const char* a1 = cA + (size_t)(t + 1) * kstep + j1;
;             const char* a2 = last ? nA : cA + (size_t)(t + 2) * kstep + ja2; const char* b2 = last ? nB : cB + (size_t)(t + 2) * kstep + jb2;
;             const char* a3 = a2 + kstep; const char* b3 = b2 + kstep;
;             PG8_LDB(B0, 0, 0); PG8_LDB(B1, 0, 1); PG8_SCHED; PG8_LDA(At, 0, 0); PG8_STAGE(PG8_SA(1, 1), a1 + hstepA, voffA);
;             PG8_WAIT_V(8); PG8_WAIT_L(0); PG8_BAR; if (do0) { PG8_MMA(0, 0, At, B0); PG8_MMA(0, 1, At, B1); } PG8_BAR; PG8_SCHED;
;             PG8_LDA(At, 0, 1); PG8_STAGE(PG8_SB(0, 0), b2, voffB); PG8_STAGE(PG8_SB(0, 1), b2 + hstepB, voffB); PG8_STAGE(PG8_SA(0, 0), a2, voffA);
;     ...
;         for (int a = 0; a < 2; ++a)
; #pragma unroll
;             for (int b = 0; b < 2; ++b)
; #pragma unroll
;                 for (int m = 0; m < 4; ++m)
; #pragma unroll
;                     for (int n = 0; n < 2; ++n) acc[a][b][m][n] = (f32x4){0.f, 0.f, 0.f, 0.f};
.LBB0_526:
	s_ashr_i32 s37, s36, 31
	s_lshl_b64 s[8:9], s[36:37], 20
	s_add_u32 s42, s76, s8
	s_addc_u32 s43, s77, s9
	s_and_b64 s[8:9], s[46:47], exec
	s_cselect_b32 s8, s43, s13
	s_cselect_b32 s9, s42, s12
	s_ashr_i32 s59, s58, 31
	s_lshl_b64 s[10:11], s[58:59], 20
	s_add_u32 s30, s60, s10
	s_addc_u32 s31, s61, s11
	s_and_b64 s[10:11], s[46:47], exec
	s_cselect_b32 s10, s31, s21
	s_cselect_b32 s11, s30, s20
	s_add_u32 s59, s20, 0x100
	s_addc_u32 s62, s21, 0
	s_mov_b32 s66, -2
	s_waitcnt lgkmcnt(0)
	s_cmp_lg_u32 s100, 1
	s_cbranch_scc1 .Ldefbar_skip_4
	s_mov_b32 s100, 0
	s_barrier
.Ldefbar_skip_4:
	v_add_u32_e32 v157, s22, v140
	v_add_u32_e32 v204, s22, v142
	v_add_u32_e32 v205, s22, v144
	v_add_u32_e32 v234, s22, v146
	v_add_u32_e32 v235, 0x10000, v158
	s_add_u32 s20, s12, 0x100
	s_addc_u32 s21, s13, 0
	s_add_i32 s54, 0, 0x10000
	s_cmp_eq_u32 s66, 28
	s_cselect_b32 s53, s8, s21
	s_cselect_b32 s52, s9, s20
	s_cselect_b32 s51, s10, s62
	s_cselect_b32 s50, s11, s59
	s_add_i32 s55, 0, 0x14000
	ds_read_b128 v[22:25], v235 offset:0
	ds_read_b128 v[26:29], v235 offset:1024
	ds_read_b128 v[160:163], v235 offset:2048
	ds_read_b128 v[164:167], v235 offset:3072
	ds_read_b128 v[168:171], v235 offset:16384
	ds_read_b128 v[172:175], v235 offset:17408
	ds_read_b128 v[176:179], v235 offset:18432
	ds_read_b128 v[180:183], v235 offset:19456
	s_add_i32 m0, s45, 0xc000
	ds_read_b128 v[184:187], v159
	ds_read_b128 v[188:191], v159 offset:1024
	ds_read_b128 v[210:213], v159 offset:2048
	ds_read_b128 v[214:217], v159 offset:3072
	ds_read_b128 v[218:221], v159 offset:4096
	ds_read_b128 v[222:225], v159 offset:5120
	ds_read_b128 v[226:229], v159 offset:6144
	ds_read_b128 v[230:233], v159 offset:7168
	global_load_lds_dwordx4 v148, s[12:13]
	s_add_i32 m0, s45, 0xe000
	s_nop 0
	global_load_lds_dwordx4 v150, s[12:13]
	s_waitcnt vmcnt(8)
	s_waitcnt lgkmcnt(0)
	s_setprio 1
	s_barrier
	v_mfma_f32_16x16x32_bf16 v[136:139], v[22:25], v[184:187], 0
	v_mfma_f32_16x16x32_bf16 v[132:135], v[160:163], v[184:187], 0
	v_mfma_f32_16x16x32_bf16 v[120:123], v[22:25], v[210:213], 0
	v_mfma_f32_16x16x32_bf16 v[116:119], v[160:163], v[210:213], 0
	v_mfma_f32_16x16x32_bf16 v[104:107], v[22:25], v[218:221], 0
	v_mfma_f32_16x16x32_bf16 v[100:103], v[160:163], v[218:221], 0
	v_mfma_f32_16x16x32_bf16 v[86:89], v[22:25], v[226:229], 0
	v_mfma_f32_16x16x32_bf16 v[82:85], v[160:163], v[226:229], 0
	v_mfma_f32_16x16x32_bf16 v[136:139], v[26:29], v[188:191], v[136:139]
	v_mfma_f32_16x16x32_bf16 v[132:135], v[164:167], v[188:191], v[132:135]
	v_mfma_f32_16x16x32_bf16 v[120:123], v[26:29], v[214:217], v[120:123]
	v_mfma_f32_16x16x32_bf16 v[116:119], v[164:167], v[214:217], v[116:119]
	v_mfma_f32_16x16x32_bf16 v[104:107], v[26:29], v[222:225], v[104:107]
	v_mfma_f32_16x16x32_bf16 v[100:103], v[164:167], v[222:225], v[100:103]
	v_mfma_f32_16x16x32_bf16 v[86:89], v[26:29], v[230:233], v[86:89]
	v_mfma_f32_16x16x32_bf16 v[82:85], v[164:167], v[230:233], v[82:85]
	s_setprio 0
	s_setprio 1
	v_mfma_f32_16x16x32_bf16 v[128:131], v[168:171], v[184:187], 0
	v_mfma_f32_16x16x32_bf16 v[124:127], v[176:179], v[184:187], 0
	v_mfma_f32_16x16x32_bf16 v[112:115], v[168:171], v[210:213], 0
	v_mfma_f32_16x16x32_bf16 v[108:111], v[176:179], v[210:213], 0
	v_mfma_f32_16x16x32_bf16 v[96:99], v[168:171], v[218:221], 0
	v_mfma_f32_16x16x32_bf16 v[92:95], v[176:179], v[218:221], 0
	v_mfma_f32_16x16x32_bf16 v[78:81], v[168:171], v[226:229], 0
	v_mfma_f32_16x16x32_bf16 v[74:77], v[176:179], v[226:229], 0
	v_mfma_f32_16x16x32_bf16 v[128:131], v[172:175], v[188:191], v[128:131]
	v_mfma_f32_16x16x32_bf16 v[124:127], v[180:183], v[188:191], v[124:127]
	v_mfma_f32_16x16x32_bf16 v[112:115], v[172:175], v[214:217], v[112:115]
	v_mfma_f32_16x16x32_bf16 v[108:111], v[180:183], v[214:217], v[108:111]
	v_mfma_f32_16x16x32_bf16 v[96:99], v[172:175], v[222:225], v[96:99]
	v_mfma_f32_16x16x32_bf16 v[92:95], v[180:183], v[222:225], v[92:95]
	v_mfma_f32_16x16x32_bf16 v[78:81], v[172:175], v[230:233], v[78:81]
	v_mfma_f32_16x16x32_bf16 v[74:77], v[180:183], v[230:233], v[74:77]
	s_barrier
	s_setprio 0
	s_add_i32 s12, s54, s29
	s_mov_b32 m0, s12
	ds_read_b128 v[184:187], v159 offset:16384
	ds_read_b128 v[188:191], v159 offset:17408
	ds_read_b128 v[210:213], v159 offset:18432
	ds_read_b128 v[214:217], v159 offset:19456
	ds_read_b128 v[218:221], v159 offset:20480
	ds_read_b128 v[222:225], v159 offset:21504
	ds_read_b128 v[226:229], v159 offset:22528
	ds_read_b128 v[230:233], v159 offset:23552
	global_load_lds_dwordx4 v142, s[50:51]
	s_add_i32 m0, s12, 0x2000
	s_add_u32 s12, s50, 0x80000
	s_addc_u32 s13, s51, 0
	s_add_i32 s54, s55, s29
	global_load_lds_dwordx4 v146, s[50:51]
	s_mov_b32 m0, s54
	s_nop 0
	global_load_lds_dwordx4 v142, s[12:13]
	s_add_i32 m0, s54, 0x2000
	s_nop 0
	global_load_lds_dwordx4 v146, s[12:13]
	s_mov_b32 m0, s45
	s_nop 0
	global_load_lds_dwordx4 v140, s[52:53]
	s_mov_b32 m0, s41
	s_nop 0
	global_load_lds_dwordx4 v144, s[52:53]
	s_waitcnt vmcnt(8)
	s_waitcnt lgkmcnt(0)
	s_setprio 1
	s_barrier
; #define PG8_STAGE(bufoff, gbase, voff) do { _Pragma("unroll") for (int _i = 0; _i < 2; ++_i) \
;         __builtin_amdgcn_global_load_lds((const unsigned*)((const char*)(gbase) + (voff)[_i]), (PG8_LAS unsigned*)(lds + (bufoff) + ldsw + _i * 8192), 16, 0, 0); } while (0)
; #define PG8_LDA(dst, b, h) do { _Pragma("unroll") for (int m = 0; m < 4; ++m) _Pragma("unroll") for (int k = 0; k < 2; ++k) dst[m][k] = *(const PG8_LAS bf16x8*)(lds + PG8_SA(b, h) + aoff + m * 2048 + k * 1024); } while (0)
; #define PG8_LDB(dst, b, h) do { _Pragma("unroll") for (int n = 0; n < 2; ++n) _Pragma("unroll") for (int k = 0; k < 2; ++k) dst[n][k] = *(const PG8_LAS bf16x8*)(lds + PG8_SB(b, h) + boff + n * 2048 + k * 1024); } while (0)
; #define PG8_MMA(ai, bj, At, Bt) do { __builtin_amdgcn_s_setprio(1); _Pragma("unroll") for (int m = 0; m < 4; ++m) _Pragma("unroll") for (int n = 0; n < 2; ++n) _Pragma("unroll") for (int k = 0; k < 2; ++k) \
;         acc[ai][bj][m][n] = __builtin_amdgcn_mfma_f32_16x16x32_bf16(Bt[n][k], At[m][k], acc[ai][bj][m][n], 0, 0, 0); __builtin_amdgcn_s_setprio(0); } while (0)
; #define PG8_WAIT_V(n) asm volatile("s_waitcnt vmcnt(" #n ")" ::: "memory")
; #define PG8_WAIT_L(n) asm volatile("s_waitcnt lgkmcnt(" #n ")" ::: "memory")
; #define PG8_BAR __builtin_amdgcn_s_barrier()
; #define PG8_SCHED __builtin_amdgcn_sched_barrier(0)
; template <class Epi>
; __device__ __forceinline__ void gemm_phase(PG8_LAS unsigned char* lds, PG8_LAS unsigned char* xl, const Gemm g, const Sched& S, const Epi& E, const int wid) {
;     ...
;             PG8_WAIT_V(8); PG8_WAIT_L(0); PG8_BAR; if (do1) { PG8_MMA(1, 0, At, B0); PG8_MMA(1, 1, At, B1); } PG8_BAR; PG8_SCHED;
;             PG8_LDB(B0, 1, 0); PG8_LDB(B1, 1, 1); PG8_SCHED; PG8_LDA(At, 1, 0); PG8_STAGE(PG8_SA(0, 1), a2 + hstepA, voffA);
;             PG8_WAIT_V(8); PG8_WAIT_L(0); PG8_BAR; if (do0) { PG8_MMA(0, 0, At, B0); PG8_MMA(0, 1, At, B1); } PG8_BAR; PG8_SCHED;
	v_mfma_f32_16x16x32_bf16 v[70:73], v[22:25], v[184:187], 0
	v_mfma_f32_16x16x32_bf16 v[66:69], v[160:163], v[184:187], 0
	v_mfma_f32_16x16x32_bf16 v[54:57], v[22:25], v[210:213], 0
	v_mfma_f32_16x16x32_bf16 v[50:53], v[160:163], v[210:213], 0
	v_mfma_f32_16x16x32_bf16 v[38:41], v[22:25], v[218:221], 0
	v_mfma_f32_16x16x32_bf16 v[34:37], v[160:163], v[218:221], 0
	v_mfma_f32_16x16x32_bf16 v[12:15], v[22:25], v[226:229], 0
	v_mfma_f32_16x16x32_bf16 v[8:11], v[160:163], v[226:229], 0
	v_mfma_f32_16x16x32_bf16 v[70:73], v[26:29], v[188:191], v[70:73]
	v_mfma_f32_16x16x32_bf16 v[66:69], v[164:167], v[188:191], v[66:69]
	v_mfma_f32_16x16x32_bf16 v[54:57], v[26:29], v[214:217], v[54:57]
	v_mfma_f32_16x16x32_bf16 v[50:53], v[164:167], v[214:217], v[50:53]
	v_mfma_f32_16x16x32_bf16 v[38:41], v[26:29], v[222:225], v[38:41]
	v_mfma_f32_16x16x32_bf16 v[34:37], v[164:167], v[222:225], v[34:37]
	v_mfma_f32_16x16x32_bf16 v[12:15], v[26:29], v[230:233], v[12:15]
	v_mfma_f32_16x16x32_bf16 v[8:11], v[164:167], v[230:233], v[8:11]
	s_setprio 0
	s_setprio 1
	v_mfma_f32_16x16x32_bf16 v[46:49], v[168:171], v[210:213], 0
	v_mfma_f32_16x16x32_bf16 v[42:45], v[176:179], v[210:213], 0
	v_mfma_f32_16x16x32_bf16 v[30:33], v[168:171], v[218:221], 0
	v_mfma_f32_16x16x32_bf16 v[18:21], v[176:179], v[218:221], 0
	v_mfma_f32_16x16x32_bf16 v[4:7], v[168:171], v[226:229], 0
	v_mfma_f32_16x16x32_bf16 v[0:3], v[176:179], v[226:229], 0
	v_mfma_f32_16x16x32_bf16 v[22:25], v[168:171], v[184:187], 0
	v_mfma_f32_16x16x32_bf16 v[26:29], v[176:179], v[184:187], 0
	v_mfma_f32_16x16x32_bf16 v[46:49], v[172:175], v[214:217], v[46:49]
	v_mfma_f32_16x16x32_bf16 v[42:45], v[180:183], v[214:217], v[42:45]
	v_mfma_f32_16x16x32_bf16 v[30:33], v[172:175], v[222:225], v[30:33]
	v_mfma_f32_16x16x32_bf16 v[18:21], v[180:183], v[222:225], v[18:21]
	v_mfma_f32_16x16x32_bf16 v[4:7], v[172:175], v[230:233], v[4:7]
	v_mfma_f32_16x16x32_bf16 v[0:3], v[180:183], v[230:233], v[0:3]
	v_mfma_f32_16x16x32_bf16 v[22:25], v[172:175], v[188:191], v[22:25]
	v_mfma_f32_16x16x32_bf16 v[26:29], v[180:183], v[188:191], v[26:29]
	s_barrier
	s_setprio 0
	s_add_i32 s54, 0, 0x18000
	s_add_i32 s55, 0, 0x1c000
	ds_read_b128 v[58:61], v235 offset:32768
	ds_read_b128 v[62:65], v235 offset:33792
	ds_read_b128 v[160:163], v235 offset:34816
	ds_read_b128 v[164:167], v235 offset:35840
	ds_read_b128 v[168:171], v235 offset:49152
	ds_read_b128 v[172:175], v235 offset:50176
	ds_read_b128 v[176:179], v235 offset:51200
	ds_read_b128 v[180:183], v235 offset:52224
	s_add_u32 s12, s52, 0x80000
	s_addc_u32 s13, s53, 0
	s_mov_b32 m0, s88
	ds_read_b128 v[184:187], v159 offset:32768
	ds_read_b128 v[188:191], v159 offset:33792
	ds_read_b128 v[210:213], v159 offset:34816
	ds_read_b128 v[214:217], v159 offset:35840
	ds_read_b128 v[218:221], v159 offset:36864
	ds_read_b128 v[222:225], v159 offset:37888
	ds_read_b128 v[226:229], v159 offset:38912
	ds_read_b128 v[230:233], v159 offset:39936
	global_load_lds_dwordx4 v140, s[12:13]
	s_mov_b32 m0, s89
	s_nop 0
	global_load_lds_dwordx4 v144, s[12:13]
	s_waitcnt vmcnt(8)
	s_waitcnt lgkmcnt(0)
	s_setprio 1
	s_barrier
	v_mfma_f32_16x16x32_bf16 v[136:139], v[58:61], v[184:187], v[136:139]
	v_mfma_f32_16x16x32_bf16 v[132:135], v[160:163], v[184:187], v[132:135]
	v_mfma_f32_16x16x32_bf16 v[120:123], v[58:61], v[210:213], v[120:123]
	v_mfma_f32_16x16x32_bf16 v[116:119], v[160:163], v[210:213], v[116:119]
	v_mfma_f32_16x16x32_bf16 v[104:107], v[58:61], v[218:221], v[104:107]
	v_mfma_f32_16x16x32_bf16 v[100:103], v[160:163], v[218:221], v[100:103]
	v_mfma_f32_16x16x32_bf16 v[86:89], v[58:61], v[226:229], v[86:89]
	v_mfma_f32_16x16x32_bf16 v[82:85], v[160:163], v[226:229], v[82:85]
	v_mfma_f32_16x16x32_bf16 v[136:139], v[62:65], v[188:191], v[136:139]
	v_mfma_f32_16x16x32_bf16 v[132:135], v[164:167], v[188:191], v[132:135]
	v_mfma_f32_16x16x32_bf16 v[120:123], v[62:65], v[214:217], v[120:123]
	v_mfma_f32_16x16x32_bf16 v[116:119], v[164:167], v[214:217], v[116:119]
	v_mfma_f32_16x16x32_bf16 v[104:107], v[62:65], v[222:225], v[104:107]
	v_mfma_f32_16x16x32_bf16 v[100:103], v[164:167], v[222:225], v[100:103]
	v_mfma_f32_16x16x32_bf16 v[86:89], v[62:65], v[230:233], v[86:89]
	v_mfma_f32_16x16x32_bf16 v[82:85], v[164:167], v[230:233], v[82:85]
	s_setprio 0
	s_setprio 1
	v_mfma_f32_16x16x32_bf16 v[128:131], v[168:171], v[184:187], v[128:131]
	v_mfma_f32_16x16x32_bf16 v[124:127], v[176:179], v[184:187], v[124:127]
	v_mfma_f32_16x16x32_bf16 v[112:115], v[168:171], v[210:213], v[112:115]
	v_mfma_f32_16x16x32_bf16 v[108:111], v[176:179], v[210:213], v[108:111]
	v_mfma_f32_16x16x32_bf16 v[96:99], v[168:171], v[218:221], v[96:99]
	v_mfma_f32_16x16x32_bf16 v[92:95], v[176:179], v[218:221], v[92:95]
	v_mfma_f32_16x16x32_bf16 v[78:81], v[168:171], v[226:229], v[78:81]
	v_mfma_f32_16x16x32_bf16 v[74:77], v[176:179], v[226:229], v[74:77]
	v_mfma_f32_16x16x32_bf16 v[128:131], v[172:175], v[188:191], v[128:131]
	v_mfma_f32_16x16x32_bf16 v[124:127], v[180:183], v[188:191], v[124:127]
	v_mfma_f32_16x16x32_bf16 v[112:115], v[172:175], v[214:217], v[112:115]
	v_mfma_f32_16x16x32_bf16 v[108:111], v[180:183], v[214:217], v[108:111]
	v_mfma_f32_16x16x32_bf16 v[96:99], v[172:175], v[222:225], v[96:99]
	v_mfma_f32_16x16x32_bf16 v[92:95], v[180:183], v[222:225], v[92:95]
	v_mfma_f32_16x16x32_bf16 v[78:81], v[172:175], v[230:233], v[78:81]
	v_mfma_f32_16x16x32_bf16 v[74:77], v[180:183], v[230:233], v[74:77]
	s_barrier
; #define PG8_STAGE(bufoff, gbase, voff) do { _Pragma("unroll") for (int _i = 0; _i < 2; ++_i) \
;         __builtin_amdgcn_global_load_lds((const unsigned*)((const char*)(gbase) + (voff)[_i]), (PG8_LAS unsigned*)(lds + (bufoff) + ldsw + _i * 8192), 16, 0, 0); } while (0)
; #define PG8_LDA(dst, b, h) do { _Pragma("unroll") for (int m = 0; m < 4; ++m) _Pragma("unroll") for (int k = 0; k < 2; ++k) dst[m][k] = *(const PG8_LAS bf16x8*)(lds + PG8_SA(b, h) + aoff + m * 2048 + k * 1024); } while (0)
; #define PG8_MMA(ai, bj, At, Bt) do { __builtin_amdgcn_s_setprio(1); _Pragma("unroll") for (int m = 0; m < 4; ++m) _Pragma("unroll") for (int n = 0; n < 2; ++n) _Pragma("unroll") for (int k = 0; k < 2; ++k) \
;         acc[ai][bj][m][n] = __builtin_amdgcn_mfma_f32_16x16x32_bf16(Bt[n][k], At[m][k], acc[ai][bj][m][n], 0, 0, 0); __builtin_amdgcn_s_setprio(0); } while (0)
; #define PG8_WAIT_V(n) asm volatile("s_waitcnt vmcnt(" #n ")" ::: "memory")
; #define PG8_WAIT_L(n) asm volatile("s_waitcnt lgkmcnt(" #n ")" ::: "memory")
; #define PG8_BAR __builtin_amdgcn_s_barrier()
; #define PG8_SCHED __builtin_amdgcn_sched_barrier(0)
; template <class Epi>
; __device__ __forceinline__ void gemm_phase(PG8_LAS unsigned char* lds, PG8_LAS unsigned char* xl, const Gemm g, const Sched& S, const Epi& E, const int wid) {
;     ...
;             PG8_LDA(At, 1, 1); PG8_STAGE(PG8_SB(1, 0), b3, voffB); PG8_STAGE(PG8_SB(1, 1), b3 + hstepB, voffB); PG8_STAGE(PG8_SA(1, 0), a3, voffA);
;             PG8_WAIT_V(8); PG8_WAIT_L(0); PG8_BAR; if (do1) { PG8_MMA(1, 0, At, B0); PG8_MMA(1, 1, At, B1); } PG8_BAR; PG8_SCHED;
;         }
	s_setprio 0
	s_add_i32 s12, s54, s29
	s_mov_b32 m0, s12
	ds_read_b128 v[184:187], v159 offset:49152
	ds_read_b128 v[188:191], v159 offset:50176
	ds_read_b128 v[210:213], v159 offset:51200
	ds_read_b128 v[214:217], v159 offset:52224
	ds_read_b128 v[218:221], v159 offset:53248
	ds_read_b128 v[222:225], v159 offset:54272
	ds_read_b128 v[226:229], v159 offset:55296
	ds_read_b128 v[230:233], v159 offset:56320
	global_load_lds_dwordx4 v204, s[50:51]
	s_add_i32 m0, s12, 0x2000
	s_add_u32 s12, s50, 0x80080
	global_load_lds_dwordx4 v234, s[50:51]
	s_addc_u32 s13, s51, 0
	s_add_i32 s50, s55, s29
	s_mov_b32 m0, s50
	s_nop 0
	global_load_lds_dwordx4 v142, s[12:13]
	s_add_i32 m0, s50, 0x2000
	s_nop 0
	global_load_lds_dwordx4 v146, s[12:13]
	s_mov_b32 m0, s90
	s_nop 0
	global_load_lds_dwordx4 v157, s[52:53]
	s_mov_b32 m0, s91
	s_nop 0
	global_load_lds_dwordx4 v205, s[52:53]
	s_waitcnt vmcnt(8)
	s_waitcnt lgkmcnt(0)
	s_setprio 1
	s_barrier
	v_mfma_f32_16x16x32_bf16 v[70:73], v[58:61], v[184:187], v[70:73]
	v_mfma_f32_16x16x32_bf16 v[66:69], v[160:163], v[184:187], v[66:69]
	v_mfma_f32_16x16x32_bf16 v[54:57], v[58:61], v[210:213], v[54:57]
	v_mfma_f32_16x16x32_bf16 v[50:53], v[160:163], v[210:213], v[50:53]
	v_mfma_f32_16x16x32_bf16 v[38:41], v[58:61], v[218:221], v[38:41]
	v_mfma_f32_16x16x32_bf16 v[34:37], v[160:163], v[218:221], v[34:37]
	v_mfma_f32_16x16x32_bf16 v[12:15], v[58:61], v[226:229], v[12:15]
	v_mfma_f32_16x16x32_bf16 v[8:11], v[160:163], v[226:229], v[8:11]
	v_mfma_f32_16x16x32_bf16 v[70:73], v[62:65], v[188:191], v[70:73]
	v_mfma_f32_16x16x32_bf16 v[66:69], v[164:167], v[188:191], v[66:69]
	v_mfma_f32_16x16x32_bf16 v[54:57], v[62:65], v[214:217], v[54:57]
	v_mfma_f32_16x16x32_bf16 v[50:53], v[164:167], v[214:217], v[50:53]
	v_mfma_f32_16x16x32_bf16 v[38:41], v[62:65], v[222:225], v[38:41]
	v_mfma_f32_16x16x32_bf16 v[34:37], v[164:167], v[222:225], v[34:37]
	v_mfma_f32_16x16x32_bf16 v[12:15], v[62:65], v[230:233], v[12:15]
	v_mfma_f32_16x16x32_bf16 v[8:11], v[164:167], v[230:233], v[8:11]
	s_setprio 0
	s_setprio 1
	v_mfma_f32_16x16x32_bf16 v[22:25], v[168:171], v[184:187], v[22:25]
	v_mfma_f32_16x16x32_bf16 v[62:65], v[172:175], v[188:191], v[22:25]
	v_mfma_f32_16x16x32_bf16 v[22:25], v[176:179], v[184:187], v[26:29]
	v_mfma_f32_16x16x32_bf16 v[58:61], v[180:183], v[188:191], v[22:25]
	v_mfma_f32_16x16x32_bf16 v[22:25], v[168:171], v[210:213], v[46:49]
	v_mfma_f32_16x16x32_bf16 v[46:49], v[172:175], v[214:217], v[22:25]
	v_mfma_f32_16x16x32_bf16 v[22:25], v[176:179], v[210:213], v[42:45]
	v_mfma_f32_16x16x32_bf16 v[42:45], v[180:183], v[214:217], v[22:25]
	v_mfma_f32_16x16x32_bf16 v[22:25], v[168:171], v[218:221], v[30:33]
	v_mfma_f32_16x16x32_bf16 v[18:21], v[176:179], v[218:221], v[18:21]
	v_mfma_f32_16x16x32_bf16 v[4:7], v[168:171], v[226:229], v[4:7]
	v_mfma_f32_16x16x32_bf16 v[0:3], v[176:179], v[226:229], v[0:3]
	v_mfma_f32_16x16x32_bf16 v[30:33], v[172:175], v[222:225], v[22:25]
	v_mfma_f32_16x16x32_bf16 v[18:21], v[180:183], v[222:225], v[18:21]
	v_mfma_f32_16x16x32_bf16 v[4:7], v[172:175], v[230:233], v[4:7]
	v_mfma_f32_16x16x32_bf16 v[0:3], v[180:183], v[230:233], v[0:3]
	s_barrier
	s_setprio 0
	s_add_i32 s66, s66, 2
	s_add_u32 s59, s59, 0x100
	s_addc_u32 s62, s62, 0
	s_cmp_gt_u32 s66, 29
	s_mov_b64 s[12:13], s[20:21]

; #define PG8_STAGE(bufoff, gbase, voff) do { _Pragma("unroll") for (int _i = 0; _i < 2; ++_i) \
;         __builtin_amdgcn_global_load_lds((const unsigned*)((const char*)(gbase) + (voff)[_i]), (PG8_LAS unsigned*)(lds + (bufoff) + ldsw + _i * 8192), 16, 0, 0); } while (0)
; #define PG8_LDA(dst, b, h) do { _Pragma("unroll") for (int m = 0; m < 4; ++m) _Pragma("unroll") for (int k = 0; k < 2; ++k) dst[m][k] = *(const PG8_LAS bf16x8*)(lds + PG8_SA(b, h) + aoff + m * 2048 + k * 1024); } while (0)
; #define PG8_LDB(dst, b, h) do { _Pragma("unroll") for (int n = 0; n < 2; ++n) _Pragma("unroll") for (int k = 0; k < 2; ++k) dst[n][k] = *(const PG8_LAS bf16x8*)(lds + PG8_SB(b, h) + boff + n * 2048 + k * 1024); } while (0)
; #define PG8_MMA(ai, bj, At, Bt) do { __builtin_amdgcn_s_setprio(1); _Pragma("unroll") for (int m = 0; m < 4; ++m) _Pragma("unroll") for (int n = 0; n < 2; ++n) _Pragma("unroll") for (int k = 0; k < 2; ++k) \
;         acc[ai][bj][m][n] = __builtin_amdgcn_mfma_f32_16x16x32_bf16(Bt[n][k], At[m][k], acc[ai][bj][m][n], 0, 0, 0); __builtin_amdgcn_s_setprio(0); } while (0)
; #define PG8_WAIT_V(n) asm volatile("s_waitcnt vmcnt(" #n ")" ::: "memory")
; #define PG8_WAIT_L(n) asm volatile("s_waitcnt lgkmcnt(" #n ")" ::: "memory")
; template <class Epi>
; __device__ __forceinline__ void gemm_phase(PG8_LAS unsigned char* lds, PG8_LAS unsigned char* xl, const Gemm g, const Sched& S, const Epi& E, const int wid) {
;     ...
;             const char* a1 = cA + (size_t)(t + 1) * kstep + j1;
;             const char* a2 = last ? nA : cA + (size_t)(t + 2) * kstep + ja2; const char* b2 = last ? nB : cB + (size_t)(t + 2) * kstep + jb2;
;             const char* a3 = a2 + kstep; const char* b3 = b2 + kstep;
;             PG8_LDB(B0, 0, 0); PG8_LDB(B1, 0, 1); PG8_SCHED; PG8_LDA(At, 0, 0); PG8_STAGE(PG8_SA(1, 1), a1 + hstepA, voffA);
;             PG8_WAIT_V(8); PG8_WAIT_L(0); PG8_BAR; if (do0) { PG8_MMA(0, 0, At, B0); PG8_MMA(0, 1, At, B1); } PG8_BAR; PG8_SCHED;
;             PG8_LDA(At, 0, 1); PG8_STAGE(PG8_SB(0, 0), b2, voffB); PG8_STAGE(PG8_SB(0, 1), b2 + hstepB, voffB); PG8_STAGE(PG8_SA(0, 0), a2, voffA);
;     ...
;         for (int a = 0; a < 2; ++a)
; #pragma unroll
;             for (int b = 0; b < 2; ++b)
; #pragma unroll
;                 for (int m = 0; m < 4; ++m)
; #pragma unroll
;                     for (int n = 0; n < 2; ++n) acc[a][b][m][n] = (f32x4){0.f, 0.f, 0.f, 0.f};
.LBB0_764:
	s_ashr_i32 s31, s30, 31
	s_lshl_b64 s[8:9], s[30:31], 20
	s_add_u32 s40, s51, s8
	s_addc_u32 s41, s52, s9
	s_and_b64 s[8:9], s[48:49], exec
	s_cselect_b32 s8, s41, s45
	s_cselect_b32 s9, s40, s44
	s_add_u32 s42, s42, 0x2c0080
	s_addc_u32 s43, s43, 0
	s_add_u32 s10, s44, 0x100
	s_addc_u32 s11, s45, 0
	s_mov_b32 s13, -2
	s_waitcnt lgkmcnt(0)
	s_cmp_lg_u32 s100, 1
	s_cbranch_scc1 .Ldefbar_skip_6
	s_mov_b32 s100, 0
	s_barrier
.Ldefbar_skip_6:
	v_add_u32_e32 v204, s22, v188
	v_add_u32_e32 v205, s22, v190
	v_add_u32_e32 v218, s22, v210
	v_add_u32_e32 v219, s22, v212
	v_add_u32_e32 v226, 0x10000, v195
	s_add_u32 s21, s42, 0xffd40080
	s_addc_u32 s31, s43, -1
	s_add_i32 s54, 0, 0x10000
	s_cmp_eq_u32 s13, 28
	s_cselect_b32 s49, s37, s31
	s_cselect_b32 s48, s36, s21
	s_cselect_b32 s45, s8, s11
	s_cselect_b32 s44, s9, s10
	s_add_i32 s21, 0, 0x14000
	ds_read_b128 v[120:123], v226 offset:0
	ds_read_b128 v[124:127], v226 offset:1024
	ds_read_b128 v[128:131], v226 offset:2048
	ds_read_b128 v[136:139], v226 offset:3072
	ds_read_b128 v[144:147], v226 offset:16384
	ds_read_b128 v[148:151], v226 offset:17408
	ds_read_b128 v[152:155], v226 offset:18432
	ds_read_b128 v[156:159], v226 offset:19456
	s_add_i32 m0, s53, 0xc000
	ds_read_b128 v[160:163], v220
	ds_read_b128 v[164:167], v220 offset:1024
	ds_read_b128 v[168:171], v220 offset:2048
	ds_read_b128 v[172:175], v220 offset:3072
	ds_read_b128 v[176:179], v220 offset:4096
	ds_read_b128 v[180:183], v220 offset:5120
	ds_read_b128 v[184:187], v220 offset:6144
	ds_read_b128 v[222:225], v220 offset:7168
	global_load_lds_dwordx4 v214, s[42:43]
	s_add_i32 m0, s53, 0xe000
	s_nop 0
	global_load_lds_dwordx4 v216, s[42:43]
	s_waitcnt vmcnt(8)
	s_waitcnt lgkmcnt(0)
	s_setprio 1
	s_barrier
	v_mfma_f32_16x16x32_bf16 v[140:143], v[120:123], v[160:163], 0
	v_mfma_f32_16x16x32_bf16 v[132:135], v[128:131], v[160:163], 0
	v_mfma_f32_16x16x32_bf16 v[108:111], v[120:123], v[168:171], 0
	v_mfma_f32_16x16x32_bf16 v[104:107], v[128:131], v[168:171], 0
	v_mfma_f32_16x16x32_bf16 v[92:95], v[120:123], v[176:179], 0
	v_mfma_f32_16x16x32_bf16 v[88:91], v[128:131], v[176:179], 0
	v_mfma_f32_16x16x32_bf16 v[76:79], v[120:123], v[184:187], 0
	v_mfma_f32_16x16x32_bf16 v[72:75], v[128:131], v[184:187], 0
	v_mfma_f32_16x16x32_bf16 v[140:143], v[124:127], v[164:167], v[140:143]
	v_mfma_f32_16x16x32_bf16 v[132:135], v[136:139], v[164:167], v[132:135]
	v_mfma_f32_16x16x32_bf16 v[108:111], v[124:127], v[172:175], v[108:111]
	v_mfma_f32_16x16x32_bf16 v[104:107], v[136:139], v[172:175], v[104:107]
	v_mfma_f32_16x16x32_bf16 v[92:95], v[124:127], v[180:183], v[92:95]
	v_mfma_f32_16x16x32_bf16 v[88:91], v[136:139], v[180:183], v[88:91]
	v_mfma_f32_16x16x32_bf16 v[76:79], v[124:127], v[222:225], v[76:79]
	v_mfma_f32_16x16x32_bf16 v[72:75], v[136:139], v[222:225], v[72:75]
	s_setprio 0
	s_setprio 1
	v_mfma_f32_16x16x32_bf16 v[116:119], v[144:147], v[160:163], 0
	v_mfma_f32_16x16x32_bf16 v[112:115], v[152:155], v[160:163], 0
	v_mfma_f32_16x16x32_bf16 v[100:103], v[144:147], v[168:171], 0
	v_mfma_f32_16x16x32_bf16 v[96:99], v[152:155], v[168:171], 0
	v_mfma_f32_16x16x32_bf16 v[84:87], v[144:147], v[176:179], 0
	v_mfma_f32_16x16x32_bf16 v[80:83], v[152:155], v[176:179], 0
	v_mfma_f32_16x16x32_bf16 v[68:71], v[144:147], v[184:187], 0
	v_mfma_f32_16x16x32_bf16 v[64:67], v[152:155], v[184:187], 0
	v_mfma_f32_16x16x32_bf16 v[116:119], v[148:151], v[164:167], v[116:119]
	v_mfma_f32_16x16x32_bf16 v[112:115], v[156:159], v[164:167], v[112:115]
	v_mfma_f32_16x16x32_bf16 v[100:103], v[148:151], v[172:175], v[100:103]
	v_mfma_f32_16x16x32_bf16 v[96:99], v[156:159], v[172:175], v[96:99]
	v_mfma_f32_16x16x32_bf16 v[84:87], v[148:151], v[180:183], v[84:87]
	v_mfma_f32_16x16x32_bf16 v[80:83], v[156:159], v[180:183], v[80:83]
	v_mfma_f32_16x16x32_bf16 v[68:71], v[148:151], v[222:225], v[68:71]
	v_mfma_f32_16x16x32_bf16 v[64:67], v[156:159], v[222:225], v[64:67]
	s_barrier
	s_setprio 0
	s_add_i32 s31, s54, s29
	s_mov_b32 m0, s31
	ds_read_b128 v[160:163], v220 offset:16384
	ds_read_b128 v[164:167], v220 offset:17408
	ds_read_b128 v[168:171], v220 offset:18432
	ds_read_b128 v[172:175], v220 offset:19456
	ds_read_b128 v[176:179], v220 offset:20480
	ds_read_b128 v[180:183], v220 offset:21504
	ds_read_b128 v[184:187], v220 offset:22528
	ds_read_b128 v[222:225], v220 offset:23552
	global_load_lds_dwordx4 v190, s[44:45]
	s_add_i32 m0, s31, 0x2000
	s_add_u32 s54, s44, 0x80000
	s_addc_u32 s55, s45, 0
	s_add_i32 s21, s21, s29
	global_load_lds_dwordx4 v212, s[44:45]
	s_mov_b32 m0, s21
	s_nop 0
	global_load_lds_dwordx4 v190, s[54:55]
	s_add_i32 m0, s21, 0x2000
	s_nop 0
	global_load_lds_dwordx4 v212, s[54:55]
	s_mov_b32 m0, s53
	s_nop 0
	global_load_lds_dwordx4 v188, s[48:49]
	s_mov_b32 m0, s56
	s_nop 0
	global_load_lds_dwordx4 v210, s[48:49]
	s_waitcnt vmcnt(8)
	s_waitcnt lgkmcnt(0)
	s_setprio 1
	s_barrier
; #define PG8_STAGE(bufoff, gbase, voff) do { _Pragma("unroll") for (int _i = 0; _i < 2; ++_i) \
;         __builtin_amdgcn_global_load_lds((const unsigned*)((const char*)(gbase) + (voff)[_i]), (PG8_LAS unsigned*)(lds + (bufoff) + ldsw + _i * 8192), 16, 0, 0); } while (0)
; #define PG8_LDA(dst, b, h) do { _Pragma("unroll") for (int m = 0; m < 4; ++m) _Pragma("unroll") for (int k = 0; k < 2; ++k) dst[m][k] = *(const PG8_LAS bf16x8*)(lds + PG8_SA(b, h) + aoff + m * 2048 + k * 1024); } while (0)
; #define PG8_LDB(dst, b, h) do { _Pragma("unroll") for (int n = 0; n < 2; ++n) _Pragma("unroll") for (int k = 0; k < 2; ++k) dst[n][k] = *(const PG8_LAS bf16x8*)(lds + PG8_SB(b, h) + boff + n * 2048 + k * 1024); } while (0)
; #define PG8_MMA(ai, bj, At, Bt) do { __builtin_amdgcn_s_setprio(1); _Pragma("unroll") for (int m = 0; m < 4; ++m) _Pragma("unroll") for (int n = 0; n < 2; ++n) _Pragma("unroll") for (int k = 0; k < 2; ++k) \
;         acc[ai][bj][m][n] = __builtin_amdgcn_mfma_f32_16x16x32_bf16(Bt[n][k], At[m][k], acc[ai][bj][m][n], 0, 0, 0); __builtin_amdgcn_s_setprio(0); } while (0)
; #define PG8_WAIT_V(n) asm volatile("s_waitcnt vmcnt(" #n ")" ::: "memory")
; #define PG8_WAIT_L(n) asm volatile("s_waitcnt lgkmcnt(" #n ")" ::: "memory")
; #define PG8_BAR __builtin_amdgcn_s_barrier()
; #define PG8_SCHED __builtin_amdgcn_sched_barrier(0)
; template <class Epi>
; __device__ __forceinline__ void gemm_phase(PG8_LAS unsigned char* lds, PG8_LAS unsigned char* xl, const Gemm g, const Sched& S, const Epi& E, const int wid) {
;     ...
;             PG8_WAIT_V(8); PG8_WAIT_L(0); PG8_BAR; if (do1) { PG8_MMA(1, 0, At, B0); PG8_MMA(1, 1, At, B1); } PG8_BAR; PG8_SCHED;
;             PG8_LDB(B0, 1, 0); PG8_LDB(B1, 1, 1); PG8_SCHED; PG8_LDA(At, 1, 0); PG8_STAGE(PG8_SA(0, 1), a2 + hstepA, voffA);
;             PG8_WAIT_V(8); PG8_WAIT_L(0); PG8_BAR; if (do0) { PG8_MMA(0, 0, At, B0); PG8_MMA(0, 1, At, B1); } PG8_BAR; PG8_SCHED;
	v_mfma_f32_16x16x32_bf16 v[60:63], v[120:123], v[160:163], 0
	v_mfma_f32_16x16x32_bf16 v[56:59], v[128:131], v[160:163], 0
	v_mfma_f32_16x16x32_bf16 v[44:47], v[120:123], v[168:171], 0
	v_mfma_f32_16x16x32_bf16 v[40:43], v[128:131], v[168:171], 0
	v_mfma_f32_16x16x32_bf16 v[28:31], v[120:123], v[176:179], 0
	v_mfma_f32_16x16x32_bf16 v[24:27], v[128:131], v[176:179], 0
	v_mfma_f32_16x16x32_bf16 v[12:15], v[120:123], v[184:187], 0
	v_mfma_f32_16x16x32_bf16 v[8:11], v[128:131], v[184:187], 0
	v_mfma_f32_16x16x32_bf16 v[60:63], v[124:127], v[164:167], v[60:63]
	v_mfma_f32_16x16x32_bf16 v[56:59], v[136:139], v[164:167], v[56:59]
	v_mfma_f32_16x16x32_bf16 v[44:47], v[124:127], v[172:175], v[44:47]
	v_mfma_f32_16x16x32_bf16 v[40:43], v[136:139], v[172:175], v[40:43]
	v_mfma_f32_16x16x32_bf16 v[28:31], v[124:127], v[180:183], v[28:31]
	v_mfma_f32_16x16x32_bf16 v[24:27], v[136:139], v[180:183], v[24:27]
	v_mfma_f32_16x16x32_bf16 v[12:15], v[124:127], v[222:225], v[12:15]
	v_mfma_f32_16x16x32_bf16 v[8:11], v[136:139], v[222:225], v[8:11]
	s_setprio 0
	s_setprio 1
	v_mfma_f32_16x16x32_bf16 v[52:55], v[144:147], v[160:163], 0
	v_mfma_f32_16x16x32_bf16 v[48:51], v[152:155], v[160:163], 0
	v_mfma_f32_16x16x32_bf16 v[36:39], v[144:147], v[168:171], 0
	v_mfma_f32_16x16x32_bf16 v[32:35], v[152:155], v[168:171], 0
	v_mfma_f32_16x16x32_bf16 v[20:23], v[144:147], v[176:179], 0
	v_mfma_f32_16x16x32_bf16 v[16:19], v[152:155], v[176:179], 0
	v_mfma_f32_16x16x32_bf16 v[4:7], v[144:147], v[184:187], 0
	v_mfma_f32_16x16x32_bf16 v[0:3], v[152:155], v[184:187], 0
	v_mfma_f32_16x16x32_bf16 v[52:55], v[148:151], v[164:167], v[52:55]
	v_mfma_f32_16x16x32_bf16 v[48:51], v[156:159], v[164:167], v[48:51]
	v_mfma_f32_16x16x32_bf16 v[36:39], v[148:151], v[172:175], v[36:39]
	v_mfma_f32_16x16x32_bf16 v[32:35], v[156:159], v[172:175], v[32:35]
	v_mfma_f32_16x16x32_bf16 v[20:23], v[148:151], v[180:183], v[20:23]
	v_mfma_f32_16x16x32_bf16 v[16:19], v[156:159], v[180:183], v[16:19]
	v_mfma_f32_16x16x32_bf16 v[4:7], v[148:151], v[222:225], v[4:7]
	v_mfma_f32_16x16x32_bf16 v[0:3], v[156:159], v[222:225], v[0:3]
	s_barrier
	s_setprio 0
	s_add_i32 s21, 0, 0x18000
	s_add_i32 s31, 0, 0x1c000
	ds_read_b128 v[120:123], v226 offset:32768
	ds_read_b128 v[124:127], v226 offset:33792
	ds_read_b128 v[128:131], v226 offset:34816
	ds_read_b128 v[136:139], v226 offset:35840
	ds_read_b128 v[144:147], v226 offset:49152
	ds_read_b128 v[148:151], v226 offset:50176
	ds_read_b128 v[152:155], v226 offset:51200
	ds_read_b128 v[156:159], v226 offset:52224
	s_add_u32 s100, s48, 0x2c0000
	s_addc_u32 s101, s49, 0
	s_mov_b32 m0, s57
	ds_read_b128 v[160:163], v220 offset:32768
	ds_read_b128 v[164:167], v220 offset:33792
	ds_read_b128 v[168:171], v220 offset:34816
	ds_read_b128 v[172:175], v220 offset:35840
	ds_read_b128 v[176:179], v220 offset:36864
	ds_read_b128 v[180:183], v220 offset:37888
	ds_read_b128 v[184:187], v220 offset:38912
	ds_read_b128 v[222:225], v220 offset:39936
	global_load_lds_dwordx4 v188, s[100:101]
	s_mov_b32 m0, s58
	s_nop 0
	global_load_lds_dwordx4 v210, s[100:101]
	s_waitcnt vmcnt(8)
	s_waitcnt lgkmcnt(0)
	s_setprio 1
	s_barrier
	v_mfma_f32_16x16x32_bf16 v[140:143], v[120:123], v[160:163], v[140:143]
	v_mfma_f32_16x16x32_bf16 v[132:135], v[128:131], v[160:163], v[132:135]
	v_mfma_f32_16x16x32_bf16 v[108:111], v[120:123], v[168:171], v[108:111]
	v_mfma_f32_16x16x32_bf16 v[104:107], v[128:131], v[168:171], v[104:107]
	v_mfma_f32_16x16x32_bf16 v[92:95], v[120:123], v[176:179], v[92:95]
	v_mfma_f32_16x16x32_bf16 v[88:91], v[128:131], v[176:179], v[88:91]
	v_mfma_f32_16x16x32_bf16 v[76:79], v[120:123], v[184:187], v[76:79]
	v_mfma_f32_16x16x32_bf16 v[72:75], v[128:131], v[184:187], v[72:75]
	v_mfma_f32_16x16x32_bf16 v[140:143], v[124:127], v[164:167], v[140:143]
	v_mfma_f32_16x16x32_bf16 v[132:135], v[136:139], v[164:167], v[132:135]
	v_mfma_f32_16x16x32_bf16 v[108:111], v[124:127], v[172:175], v[108:111]
	v_mfma_f32_16x16x32_bf16 v[104:107], v[136:139], v[172:175], v[104:107]
	v_mfma_f32_16x16x32_bf16 v[92:95], v[124:127], v[180:183], v[92:95]
	v_mfma_f32_16x16x32_bf16 v[88:91], v[136:139], v[180:183], v[88:91]
	v_mfma_f32_16x16x32_bf16 v[76:79], v[124:127], v[222:225], v[76:79]
	v_mfma_f32_16x16x32_bf16 v[72:75], v[136:139], v[222:225], v[72:75]
	s_setprio 0
	s_setprio 1
	v_mfma_f32_16x16x32_bf16 v[116:119], v[144:147], v[160:163], v[116:119]
	v_mfma_f32_16x16x32_bf16 v[112:115], v[152:155], v[160:163], v[112:115]
	v_mfma_f32_16x16x32_bf16 v[100:103], v[144:147], v[168:171], v[100:103]
	v_mfma_f32_16x16x32_bf16 v[96:99], v[152:155], v[168:171], v[96:99]
	v_mfma_f32_16x16x32_bf16 v[84:87], v[144:147], v[176:179], v[84:87]
	v_mfma_f32_16x16x32_bf16 v[80:83], v[152:155], v[176:179], v[80:83]
	v_mfma_f32_16x16x32_bf16 v[68:71], v[144:147], v[184:187], v[68:71]
	v_mfma_f32_16x16x32_bf16 v[64:67], v[152:155], v[184:187], v[64:67]
	v_mfma_f32_16x16x32_bf16 v[116:119], v[148:151], v[164:167], v[116:119]
	v_mfma_f32_16x16x32_bf16 v[112:115], v[156:159], v[164:167], v[112:115]
	v_mfma_f32_16x16x32_bf16 v[100:103], v[148:151], v[172:175], v[100:103]
	v_mfma_f32_16x16x32_bf16 v[96:99], v[156:159], v[172:175], v[96:99]
	v_mfma_f32_16x16x32_bf16 v[84:87], v[148:151], v[180:183], v[84:87]
	v_mfma_f32_16x16x32_bf16 v[80:83], v[156:159], v[180:183], v[80:83]
	v_mfma_f32_16x16x32_bf16 v[68:71], v[148:151], v[222:225], v[68:71]
	v_mfma_f32_16x16x32_bf16 v[64:67], v[156:159], v[222:225], v[64:67]
	s_barrier
; #define PG8_STAGE(bufoff, gbase, voff) do { _Pragma("unroll") for (int _i = 0; _i < 2; ++_i) \
;         __builtin_amdgcn_global_load_lds((const unsigned*)((const char*)(gbase) + (voff)[_i]), (PG8_LAS unsigned*)(lds + (bufoff) + ldsw + _i * 8192), 16, 0, 0); } while (0)
; #define PG8_LDA(dst, b, h) do { _Pragma("unroll") for (int m = 0; m < 4; ++m) _Pragma("unroll") for (int k = 0; k < 2; ++k) dst[m][k] = *(const PG8_LAS bf16x8*)(lds + PG8_SA(b, h) + aoff + m * 2048 + k * 1024); } while (0)
; #define PG8_MMA(ai, bj, At, Bt) do { __builtin_amdgcn_s_setprio(1); _Pragma("unroll") for (int m = 0; m < 4; ++m) _Pragma("unroll") for (int n = 0; n < 2; ++n) _Pragma("unroll") for (int k = 0; k < 2; ++k) \
;         acc[ai][bj][m][n] = __builtin_amdgcn_mfma_f32_16x16x32_bf16(Bt[n][k], At[m][k], acc[ai][bj][m][n], 0, 0, 0); __builtin_amdgcn_s_setprio(0); } while (0)
; #define PG8_WAIT_V(n) asm volatile("s_waitcnt vmcnt(" #n ")" ::: "memory")
; #define PG8_WAIT_L(n) asm volatile("s_waitcnt lgkmcnt(" #n ")" ::: "memory")
; #define PG8_BAR __builtin_amdgcn_s_barrier()
; #define PG8_SCHED __builtin_amdgcn_sched_barrier(0)
; template <class Epi>
; __device__ __forceinline__ void gemm_phase(PG8_LAS unsigned char* lds, PG8_LAS unsigned char* xl, const Gemm g, const Sched& S, const Epi& E, const int wid) {
;     ...
;             PG8_LDA(At, 1, 1); PG8_STAGE(PG8_SB(1, 0), b3, voffB); PG8_STAGE(PG8_SB(1, 1), b3 + hstepB, voffB); PG8_STAGE(PG8_SA(1, 0), a3, voffA);
;             PG8_WAIT_V(8); PG8_WAIT_L(0); PG8_BAR; if (do1) { PG8_MMA(1, 0, At, B0); PG8_MMA(1, 1, At, B1); } PG8_BAR; PG8_SCHED;
;         }
	s_setprio 0
	s_add_i32 s21, s21, s29
	s_mov_b32 m0, s21
	ds_read_b128 v[160:163], v220 offset:49152
	ds_read_b128 v[164:167], v220 offset:50176
	ds_read_b128 v[168:171], v220 offset:51200
	ds_read_b128 v[172:175], v220 offset:52224
	ds_read_b128 v[176:179], v220 offset:53248
	ds_read_b128 v[180:183], v220 offset:54272
	ds_read_b128 v[184:187], v220 offset:55296
	ds_read_b128 v[222:225], v220 offset:56320
	global_load_lds_dwordx4 v205, s[44:45]
	s_add_i32 m0, s21, 0x2000
	s_add_u32 s100, s44, 0x80080
	global_load_lds_dwordx4 v219, s[44:45]
	s_addc_u32 s101, s45, 0
	s_add_i32 s21, s31, s29
	s_mov_b32 m0, s21
	s_nop 0
	global_load_lds_dwordx4 v190, s[100:101]
	s_add_i32 m0, s21, 0x2000
	s_nop 0
	global_load_lds_dwordx4 v212, s[100:101]
	s_mov_b32 m0, s66
	s_nop 0
	global_load_lds_dwordx4 v204, s[48:49]
	s_mov_b32 m0, s67
	s_nop 0
	global_load_lds_dwordx4 v218, s[48:49]
	s_waitcnt vmcnt(8)
	s_waitcnt lgkmcnt(0)
	s_setprio 1
	s_barrier
	v_mfma_f32_16x16x32_bf16 v[60:63], v[120:123], v[160:163], v[60:63]
	v_mfma_f32_16x16x32_bf16 v[56:59], v[128:131], v[160:163], v[56:59]
	v_mfma_f32_16x16x32_bf16 v[44:47], v[120:123], v[168:171], v[44:47]
	v_mfma_f32_16x16x32_bf16 v[40:43], v[128:131], v[168:171], v[40:43]
	v_mfma_f32_16x16x32_bf16 v[28:31], v[120:123], v[176:179], v[28:31]
	v_mfma_f32_16x16x32_bf16 v[24:27], v[128:131], v[176:179], v[24:27]
	v_mfma_f32_16x16x32_bf16 v[12:15], v[120:123], v[184:187], v[12:15]
	v_mfma_f32_16x16x32_bf16 v[8:11], v[128:131], v[184:187], v[8:11]
	v_mfma_f32_16x16x32_bf16 v[60:63], v[124:127], v[164:167], v[60:63]
	v_mfma_f32_16x16x32_bf16 v[56:59], v[136:139], v[164:167], v[56:59]
	v_mfma_f32_16x16x32_bf16 v[44:47], v[124:127], v[172:175], v[44:47]
	v_mfma_f32_16x16x32_bf16 v[40:43], v[136:139], v[172:175], v[40:43]
	v_mfma_f32_16x16x32_bf16 v[28:31], v[124:127], v[180:183], v[28:31]
	v_mfma_f32_16x16x32_bf16 v[24:27], v[136:139], v[180:183], v[24:27]
	v_mfma_f32_16x16x32_bf16 v[12:15], v[124:127], v[222:225], v[12:15]
	v_mfma_f32_16x16x32_bf16 v[8:11], v[136:139], v[222:225], v[8:11]
	s_setprio 0
	s_setprio 1
	v_mfma_f32_16x16x32_bf16 v[52:55], v[144:147], v[160:163], v[52:55]
	v_mfma_f32_16x16x32_bf16 v[48:51], v[152:155], v[160:163], v[48:51]
	v_mfma_f32_16x16x32_bf16 v[36:39], v[144:147], v[168:171], v[36:39]
	v_mfma_f32_16x16x32_bf16 v[32:35], v[152:155], v[168:171], v[32:35]
	v_mfma_f32_16x16x32_bf16 v[20:23], v[144:147], v[176:179], v[20:23]
	v_mfma_f32_16x16x32_bf16 v[16:19], v[152:155], v[176:179], v[16:19]
	v_mfma_f32_16x16x32_bf16 v[4:7], v[144:147], v[184:187], v[4:7]
	v_mfma_f32_16x16x32_bf16 v[0:3], v[152:155], v[184:187], v[0:3]
	v_mfma_f32_16x16x32_bf16 v[52:55], v[148:151], v[164:167], v[52:55]
	v_mfma_f32_16x16x32_bf16 v[48:51], v[156:159], v[164:167], v[48:51]
	v_mfma_f32_16x16x32_bf16 v[36:39], v[148:151], v[172:175], v[36:39]
	v_mfma_f32_16x16x32_bf16 v[32:35], v[156:159], v[172:175], v[32:35]
	v_mfma_f32_16x16x32_bf16 v[20:23], v[148:151], v[180:183], v[20:23]
	v_mfma_f32_16x16x32_bf16 v[16:19], v[156:159], v[180:183], v[16:19]
	v_mfma_f32_16x16x32_bf16 v[4:7], v[148:151], v[222:225], v[4:7]
	v_mfma_f32_16x16x32_bf16 v[0:3], v[156:159], v[222:225], v[0:3]
	s_barrier
	s_setprio 0
	s_add_i32 s13, s13, 2
	s_add_u32 s42, s42, 0x100
	s_addc_u32 s43, s43, 0
	s_add_u32 s10, s10, 0x100
	s_addc_u32 s11, s11, 0
	s_cmp_gt_u32 s13, 29

; __device__ __forceinline__ int lane_id_opq() { int l; asm volatile("v_mbcnt_lo_u32_b32 %0, -1, 0\n\tv_mbcnt_hi_u32_b32 %0, -1, %0" : "=v"(l)); return l; }
; #define PG8_STAGE(bufoff, gbase, voff) do { _Pragma("unroll") for (int _i = 0; _i < 2; ++_i) \
;         __builtin_amdgcn_global_load_lds((const unsigned*)((const char*)(gbase) + (voff)[_i]), (PG8_LAS unsigned*)(lds + (bufoff) + ldsw + _i * 8192), 16, 0, 0); } while (0)
; #define PG8_WAIT_V(n) asm volatile("s_waitcnt vmcnt(" #n ")" ::: "memory")
; #define PG8_WAIT_L(n) asm volatile("s_waitcnt lgkmcnt(" #n ")" ::: "memory")
; template <class Epi>
; __device__ __forceinline__ void gemm_phase(PG8_LAS unsigned char* lds, PG8_LAS unsigned char* xl, const Gemm g, const Sched& S, const Epi& E, const int wid) {
;     ...
;         for (int t = 0; t < nt; t += 2) {
;             const bool last = (t == nt - 2);
;             const bool do0 = !blkdiag_v<Epi> || t == 0, do1 = !blkdiag_v<Epi> || t != 0;
;             long j1 = 0, ja2 = 0, jb2 = 0;
;             if constexpr (Epi::MID) {
;                 if (t == g.tj) { const int lnM = lane_id_opq(); E.mid(acc, cur, wr, wc, lnM & 15, lnM >> 4); }
;                 if (t >= g.tj) j1 = g.jA;
;                 if (t + 2 >= g.tj) { ja2 = g.jA; jb2 = g.jB; } }
;             const char* a1 = cA + (size_t)(t + 1) * kstep + j1;
;             const char* a2 = last ? nA : cA + (size_t)(t + 2) * kstep + ja2; const char* b2 = last ? nB : cB + (size_t)(t + 2) * kstep + jb2;
;             const char* a3 = a2 + kstep; const char* b3 = b2 + kstep;
;             PG8_LDB(B0, 0, 0); PG8_LDB(B1, 0, 1); PG8_SCHED; PG8_LDA(At, 0, 0); PG8_STAGE(PG8_SA(1, 1), a1 + hstepA, voffA);
;             PG8_WAIT_V(8); PG8_WAIT_L(0); PG8_BAR; if (do0) { PG8_MMA(0, 0, At, B0); PG8_MMA(0, 1, At, B1); } PG8_BAR; PG8_SCHED;
;             PG8_LDA(At, 0, 1); PG8_STAGE(PG8_SB(0, 0), b2, voffB); PG8_STAGE(PG8_SB(0, 1), b2 + hstepB, voffB); PG8_STAGE(PG8_SA(0, 0), a2, voffA);
;             PG8_WAIT_V(8); PG8_WAIT_L(0); PG8_BAR; if (do1) { PG8_MMA(1, 0, At, B0); PG8_MMA(1, 1, At, B1); } PG8_BAR; PG8_SCHED;
;     ...
; #pragma unroll
;         for (int a = 0; a < 2; ++a)
; #pragma unroll
;             for (int b = 0; b < 2; ++b)
; #pragma unroll
;                 for (int m = 0; m < 4; ++m)
; #pragma unroll
;                     for (int n = 0; n < 2; ++n) acc[a][b][m][n] = (f32x4){0.f, 0.f, 0.f, 0.f};
.LBB0_858:
	s_add_u32 s8, s50, 0x100
	s_addc_u32 s9, s51, 0
	s_mov_b32 s10, -2
	s_cmp_lg_u32 s100, 1
	s_cbranch_scc1 .Ldefbar_skip_7
	s_mov_b32 s100, 0
	s_barrier
.Ldefbar_skip_7:
	v_add_u32_e32 v204, s22, v184
	v_add_u32_e32 v205, s22, v186
	v_add_u32_e32 v214, s22, v188
	v_add_u32_e32 v215, s22, v190
	v_add_u32_e32 v226, 0x10000, v195
	s_add_u32 s46, s48, 0x100
	s_addc_u32 s47, s49, 0
	s_add_i32 s11, 0, 0x10000
	s_cmp_eq_u32 s10, 28
	s_cselect_b32 vcc_hi, s59, s47
	s_cselect_b32 vcc_lo, s58, s46
	s_cselect_b32 s51, s21, s9
	s_cselect_b32 s50, s20, s8
	s_add_i32 s13, 0, 0x14000
	ds_read_b128 v[120:123], v226 offset:0
	ds_read_b128 v[124:127], v226 offset:1024
	ds_read_b128 v[136:139], v226 offset:2048
	ds_read_b128 v[140:143], v226 offset:3072
	ds_read_b128 v[144:147], v226 offset:16384
	ds_read_b128 v[148:151], v226 offset:17408
	ds_read_b128 v[152:155], v226 offset:18432
	ds_read_b128 v[156:159], v226 offset:19456
	s_add_i32 m0, s89, 0xc000
	ds_read_b128 v[160:163], v216
	ds_read_b128 v[164:167], v216 offset:1024
	ds_read_b128 v[168:171], v216 offset:2048
	ds_read_b128 v[172:175], v216 offset:3072
	ds_read_b128 v[176:179], v216 offset:4096
	ds_read_b128 v[180:183], v216 offset:5120
	ds_read_b128 v[218:221], v216 offset:6144
	ds_read_b128 v[222:225], v216 offset:7168
	global_load_lds_dwordx4 v210, s[48:49]
	s_add_i32 m0, s89, 0xe000
	s_nop 0
	global_load_lds_dwordx4 v212, s[48:49]
	s_waitcnt vmcnt(8)
	s_waitcnt lgkmcnt(0)
	s_setprio 1
	s_barrier
	v_mfma_f32_16x16x32_bf16 v[132:135], v[120:123], v[160:163], 0
	v_mfma_f32_16x16x32_bf16 v[128:131], v[136:139], v[160:163], 0
	v_mfma_f32_16x16x32_bf16 v[108:111], v[120:123], v[168:171], 0
	v_mfma_f32_16x16x32_bf16 v[104:107], v[136:139], v[168:171], 0
	v_mfma_f32_16x16x32_bf16 v[92:95], v[120:123], v[176:179], 0
	v_mfma_f32_16x16x32_bf16 v[88:91], v[136:139], v[176:179], 0
	v_mfma_f32_16x16x32_bf16 v[76:79], v[120:123], v[218:221], 0
	v_mfma_f32_16x16x32_bf16 v[72:75], v[136:139], v[218:221], 0
	v_mfma_f32_16x16x32_bf16 v[132:135], v[124:127], v[164:167], v[132:135]
	v_mfma_f32_16x16x32_bf16 v[128:131], v[140:143], v[164:167], v[128:131]
	v_mfma_f32_16x16x32_bf16 v[108:111], v[124:127], v[172:175], v[108:111]
	v_mfma_f32_16x16x32_bf16 v[104:107], v[140:143], v[172:175], v[104:107]
	v_mfma_f32_16x16x32_bf16 v[92:95], v[124:127], v[180:183], v[92:95]
	v_mfma_f32_16x16x32_bf16 v[88:91], v[140:143], v[180:183], v[88:91]
	v_mfma_f32_16x16x32_bf16 v[76:79], v[124:127], v[222:225], v[76:79]
	v_mfma_f32_16x16x32_bf16 v[72:75], v[140:143], v[222:225], v[72:75]
	s_setprio 0
	s_setprio 1
	v_mfma_f32_16x16x32_bf16 v[116:119], v[144:147], v[160:163], 0
	v_mfma_f32_16x16x32_bf16 v[112:115], v[152:155], v[160:163], 0
	v_mfma_f32_16x16x32_bf16 v[100:103], v[144:147], v[168:171], 0
	v_mfma_f32_16x16x32_bf16 v[96:99], v[152:155], v[168:171], 0
	v_mfma_f32_16x16x32_bf16 v[84:87], v[144:147], v[176:179], 0
	v_mfma_f32_16x16x32_bf16 v[80:83], v[152:155], v[176:179], 0
	v_mfma_f32_16x16x32_bf16 v[68:71], v[144:147], v[218:221], 0
	v_mfma_f32_16x16x32_bf16 v[64:67], v[152:155], v[218:221], 0
	v_mfma_f32_16x16x32_bf16 v[116:119], v[148:151], v[164:167], v[116:119]
	v_mfma_f32_16x16x32_bf16 v[112:115], v[156:159], v[164:167], v[112:115]
	v_mfma_f32_16x16x32_bf16 v[100:103], v[148:151], v[172:175], v[100:103]
	v_mfma_f32_16x16x32_bf16 v[96:99], v[156:159], v[172:175], v[96:99]
	v_mfma_f32_16x16x32_bf16 v[84:87], v[148:151], v[180:183], v[84:87]
	v_mfma_f32_16x16x32_bf16 v[80:83], v[156:159], v[180:183], v[80:83]
	v_mfma_f32_16x16x32_bf16 v[68:71], v[148:151], v[222:225], v[68:71]
	v_mfma_f32_16x16x32_bf16 v[64:67], v[156:159], v[222:225], v[64:67]
	s_barrier
	s_setprio 0
	s_add_i32 s11, s11, s29
	s_mov_b32 m0, s11
	ds_read_b128 v[160:163], v216 offset:16384
	ds_read_b128 v[164:167], v216 offset:17408
	ds_read_b128 v[168:171], v216 offset:18432
	ds_read_b128 v[172:175], v216 offset:19456
	ds_read_b128 v[176:179], v216 offset:20480
	ds_read_b128 v[180:183], v216 offset:21504
	ds_read_b128 v[218:221], v216 offset:22528
	ds_read_b128 v[222:225], v216 offset:23552
	global_load_lds_dwordx4 v186, s[50:51]
	s_add_i32 m0, s11, 0x2000
	s_add_u32 s48, s50, 0x80000
	s_addc_u32 s49, s51, 0
	s_add_i32 s11, s13, s29
	global_load_lds_dwordx4 v190, s[50:51]
	s_mov_b32 m0, s11
	s_nop 0
	global_load_lds_dwordx4 v186, s[48:49]
	s_add_i32 m0, s11, 0x2000
	s_nop 0
	global_load_lds_dwordx4 v190, s[48:49]
	s_mov_b32 m0, s89
	s_nop 0
	global_load_lds_dwordx4 v184, vcc
	s_mov_b32 m0, s90
	s_nop 0
	global_load_lds_dwordx4 v188, vcc
	s_waitcnt vmcnt(8)
	s_waitcnt lgkmcnt(0)
	s_setprio 1
	s_barrier
	v_mfma_f32_16x16x32_bf16 v[60:63], v[120:123], v[160:163], 0
	v_mfma_f32_16x16x32_bf16 v[56:59], v[136:139], v[160:163], 0
	v_mfma_f32_16x16x32_bf16 v[44:47], v[120:123], v[168:171], 0
	v_mfma_f32_16x16x32_bf16 v[40:43], v[136:139], v[168:171], 0
	v_mfma_f32_16x16x32_bf16 v[28:31], v[120:123], v[176:179], 0
	v_mfma_f32_16x16x32_bf16 v[24:27], v[136:139], v[176:179], 0
	v_mfma_f32_16x16x32_bf16 v[12:15], v[120:123], v[218:221], 0
	v_mfma_f32_16x16x32_bf16 v[8:11], v[136:139], v[218:221], 0
	v_mfma_f32_16x16x32_bf16 v[60:63], v[124:127], v[164:167], v[60:63]
	v_mfma_f32_16x16x32_bf16 v[56:59], v[140:143], v[164:167], v[56:59]
	v_mfma_f32_16x16x32_bf16 v[44:47], v[124:127], v[172:175], v[44:47]
	v_mfma_f32_16x16x32_bf16 v[40:43], v[140:143], v[172:175], v[40:43]
	v_mfma_f32_16x16x32_bf16 v[28:31], v[124:127], v[180:183], v[28:31]
	v_mfma_f32_16x16x32_bf16 v[24:27], v[140:143], v[180:183], v[24:27]
	v_mfma_f32_16x16x32_bf16 v[12:15], v[124:127], v[222:225], v[12:15]
	v_mfma_f32_16x16x32_bf16 v[8:11], v[140:143], v[222:225], v[8:11]
	s_setprio 0
	s_setprio 1
	v_mfma_f32_16x16x32_bf16 v[52:55], v[144:147], v[160:163], 0
	v_mfma_f32_16x16x32_bf16 v[48:51], v[152:155], v[160:163], 0
	v_mfma_f32_16x16x32_bf16 v[36:39], v[144:147], v[168:171], 0
	v_mfma_f32_16x16x32_bf16 v[32:35], v[152:155], v[168:171], 0
	v_mfma_f32_16x16x32_bf16 v[20:23], v[144:147], v[176:179], 0
	v_mfma_f32_16x16x32_bf16 v[16:19], v[152:155], v[176:179], 0
	v_mfma_f32_16x16x32_bf16 v[4:7], v[144:147], v[218:221], 0
	v_mfma_f32_16x16x32_bf16 v[0:3], v[152:155], v[218:221], 0
	v_mfma_f32_16x16x32_bf16 v[52:55], v[148:151], v[164:167], v[52:55]
	v_mfma_f32_16x16x32_bf16 v[48:51], v[156:159], v[164:167], v[48:51]
	v_mfma_f32_16x16x32_bf16 v[36:39], v[148:151], v[172:175], v[36:39]
	v_mfma_f32_16x16x32_bf16 v[32:35], v[156:159], v[172:175], v[32:35]
	v_mfma_f32_16x16x32_bf16 v[20:23], v[148:151], v[180:183], v[20:23]
	v_mfma_f32_16x16x32_bf16 v[16:19], v[156:159], v[180:183], v[16:19]
	v_mfma_f32_16x16x32_bf16 v[4:7], v[148:151], v[222:225], v[4:7]
	v_mfma_f32_16x16x32_bf16 v[0:3], v[156:159], v[222:225], v[0:3]
	s_barrier
; #define PG8_STAGE(bufoff, gbase, voff) do { _Pragma("unroll") for (int _i = 0; _i < 2; ++_i) \
;         __builtin_amdgcn_global_load_lds((const unsigned*)((const char*)(gbase) + (voff)[_i]), (PG8_LAS unsigned*)(lds + (bufoff) + ldsw + _i * 8192), 16, 0, 0); } while (0)
; #define PG8_LDA(dst, b, h) do { _Pragma("unroll") for (int m = 0; m < 4; ++m) _Pragma("unroll") for (int k = 0; k < 2; ++k) dst[m][k] = *(const PG8_LAS bf16x8*)(lds + PG8_SA(b, h) + aoff + m * 2048 + k * 1024); } while (0)
; #define PG8_LDB(dst, b, h) do { _Pragma("unroll") for (int n = 0; n < 2; ++n) _Pragma("unroll") for (int k = 0; k < 2; ++k) dst[n][k] = *(const PG8_LAS bf16x8*)(lds + PG8_SB(b, h) + boff + n * 2048 + k * 1024); } while (0)
; #define PG8_MMA(ai, bj, At, Bt) do { __builtin_amdgcn_s_setprio(1); _Pragma("unroll") for (int m = 0; m < 4; ++m) _Pragma("unroll") for (int n = 0; n < 2; ++n) _Pragma("unroll") for (int k = 0; k < 2; ++k) \
;         acc[ai][bj][m][n] = __builtin_amdgcn_mfma_f32_16x16x32_bf16(Bt[n][k], At[m][k], acc[ai][bj][m][n], 0, 0, 0); __builtin_amdgcn_s_setprio(0); } while (0)
; #define PG8_WAIT_V(n) asm volatile("s_waitcnt vmcnt(" #n ")" ::: "memory")
; #define PG8_WAIT_L(n) asm volatile("s_waitcnt lgkmcnt(" #n ")" ::: "memory")
; #define PG8_BAR __builtin_amdgcn_s_barrier()
; #define PG8_SCHED __builtin_amdgcn_sched_barrier(0)
; template <class Epi>
; __device__ __forceinline__ void gemm_phase(PG8_LAS unsigned char* lds, PG8_LAS unsigned char* xl, const Gemm g, const Sched& S, const Epi& E, const int wid) {
;     ...
;             PG8_LDB(B0, 1, 0); PG8_LDB(B1, 1, 1); PG8_SCHED; PG8_LDA(At, 1, 0); PG8_STAGE(PG8_SA(0, 1), a2 + hstepA, voffA);
;             PG8_WAIT_V(8); PG8_WAIT_L(0); PG8_BAR; if (do0) { PG8_MMA(0, 0, At, B0); PG8_MMA(0, 1, At, B1); } PG8_BAR; PG8_SCHED;
;             PG8_LDA(At, 1, 1); PG8_STAGE(PG8_SB(1, 0), b3, voffB); PG8_STAGE(PG8_SB(1, 1), b3 + hstepB, voffB); PG8_STAGE(PG8_SA(1, 0), a3, voffA);
;             PG8_WAIT_V(8); PG8_WAIT_L(0); PG8_BAR; if (do1) { PG8_MMA(1, 0, At, B0); PG8_MMA(1, 1, At, B1); } PG8_BAR; PG8_SCHED;
;         }
	s_setprio 0
	s_add_i32 s11, 0, 0x18000
	s_add_i32 s13, 0, 0x1c000
	ds_read_b128 v[120:123], v226 offset:32768
	ds_read_b128 v[124:127], v226 offset:33792
	ds_read_b128 v[136:139], v226 offset:34816
	ds_read_b128 v[140:143], v226 offset:35840
	ds_read_b128 v[144:147], v226 offset:49152
	ds_read_b128 v[148:151], v226 offset:50176
	ds_read_b128 v[152:155], v226 offset:51200
	ds_read_b128 v[156:159], v226 offset:52224
	s_add_u32 s48, vcc_lo, 0x80000
	s_addc_u32 s49, vcc_hi, 0
	s_mov_b32 m0, s91
	ds_read_b128 v[160:163], v216 offset:32768
	ds_read_b128 v[164:167], v216 offset:33792
	ds_read_b128 v[168:171], v216 offset:34816
	ds_read_b128 v[172:175], v216 offset:35840
	ds_read_b128 v[176:179], v216 offset:36864
	ds_read_b128 v[180:183], v216 offset:37888
	ds_read_b128 v[218:221], v216 offset:38912
	ds_read_b128 v[222:225], v216 offset:39936
	global_load_lds_dwordx4 v184, s[48:49]
	s_mov_b32 m0, s92
	s_nop 0
	global_load_lds_dwordx4 v188, s[48:49]
	s_waitcnt vmcnt(8)
	s_waitcnt lgkmcnt(0)
	s_setprio 1
	s_barrier
	v_mfma_f32_16x16x32_bf16 v[132:135], v[120:123], v[160:163], v[132:135]
	v_mfma_f32_16x16x32_bf16 v[128:131], v[136:139], v[160:163], v[128:131]
	v_mfma_f32_16x16x32_bf16 v[108:111], v[120:123], v[168:171], v[108:111]
	v_mfma_f32_16x16x32_bf16 v[104:107], v[136:139], v[168:171], v[104:107]
	v_mfma_f32_16x16x32_bf16 v[92:95], v[120:123], v[176:179], v[92:95]
	v_mfma_f32_16x16x32_bf16 v[88:91], v[136:139], v[176:179], v[88:91]
	v_mfma_f32_16x16x32_bf16 v[76:79], v[120:123], v[218:221], v[76:79]
	v_mfma_f32_16x16x32_bf16 v[72:75], v[136:139], v[218:221], v[72:75]
	v_mfma_f32_16x16x32_bf16 v[132:135], v[124:127], v[164:167], v[132:135]
	v_mfma_f32_16x16x32_bf16 v[128:131], v[140:143], v[164:167], v[128:131]
	v_mfma_f32_16x16x32_bf16 v[108:111], v[124:127], v[172:175], v[108:111]
	v_mfma_f32_16x16x32_bf16 v[104:107], v[140:143], v[172:175], v[104:107]
	v_mfma_f32_16x16x32_bf16 v[92:95], v[124:127], v[180:183], v[92:95]
	v_mfma_f32_16x16x32_bf16 v[88:91], v[140:143], v[180:183], v[88:91]
	v_mfma_f32_16x16x32_bf16 v[76:79], v[124:127], v[222:225], v[76:79]
	v_mfma_f32_16x16x32_bf16 v[72:75], v[140:143], v[222:225], v[72:75]
	s_setprio 0
	s_setprio 1
	v_mfma_f32_16x16x32_bf16 v[116:119], v[144:147], v[160:163], v[116:119]
	v_mfma_f32_16x16x32_bf16 v[112:115], v[152:155], v[160:163], v[112:115]
	v_mfma_f32_16x16x32_bf16 v[100:103], v[144:147], v[168:171], v[100:103]
	v_mfma_f32_16x16x32_bf16 v[96:99], v[152:155], v[168:171], v[96:99]
	v_mfma_f32_16x16x32_bf16 v[84:87], v[144:147], v[176:179], v[84:87]
	v_mfma_f32_16x16x32_bf16 v[80:83], v[152:155], v[176:179], v[80:83]
	v_mfma_f32_16x16x32_bf16 v[68:71], v[144:147], v[218:221], v[68:71]
	v_mfma_f32_16x16x32_bf16 v[64:67], v[152:155], v[218:221], v[64:67]
	v_mfma_f32_16x16x32_bf16 v[116:119], v[148:151], v[164:167], v[116:119]
	v_mfma_f32_16x16x32_bf16 v[112:115], v[156:159], v[164:167], v[112:115]
	v_mfma_f32_16x16x32_bf16 v[100:103], v[148:151], v[172:175], v[100:103]
	v_mfma_f32_16x16x32_bf16 v[96:99], v[156:159], v[172:175], v[96:99]
	v_mfma_f32_16x16x32_bf16 v[84:87], v[148:151], v[180:183], v[84:87]
	v_mfma_f32_16x16x32_bf16 v[80:83], v[156:159], v[180:183], v[80:83]
	v_mfma_f32_16x16x32_bf16 v[68:71], v[148:151], v[222:225], v[68:71]
	v_mfma_f32_16x16x32_bf16 v[64:67], v[156:159], v[222:225], v[64:67]
	s_barrier
	s_setprio 0
	s_add_i32 s11, s11, s29
	s_mov_b32 m0, s11
	ds_read_b128 v[160:163], v216 offset:49152
	ds_read_b128 v[164:167], v216 offset:50176
	ds_read_b128 v[168:171], v216 offset:51200
	ds_read_b128 v[172:175], v216 offset:52224
	ds_read_b128 v[176:179], v216 offset:53248
	ds_read_b128 v[180:183], v216 offset:54272
	ds_read_b128 v[218:221], v216 offset:55296
	ds_read_b128 v[222:225], v216 offset:56320
	global_load_lds_dwordx4 v205, s[50:51]
	s_add_i32 m0, s11, 0x2000
	s_add_u32 s48, s50, 0x80080
	global_load_lds_dwordx4 v215, s[50:51]
	s_addc_u32 s49, s51, 0
	s_add_i32 s11, s13, s29
	s_mov_b32 m0, s11
	s_nop 0
	global_load_lds_dwordx4 v186, s[48:49]
	s_add_i32 m0, s11, 0x2000
	s_nop 0
	global_load_lds_dwordx4 v190, s[48:49]
	s_mov_b32 m0, s95
	s_nop 0
	global_load_lds_dwordx4 v204, vcc
	s_mov_b32 m0, s96
	s_nop 0
	global_load_lds_dwordx4 v214, vcc
	s_waitcnt vmcnt(8)
	s_waitcnt lgkmcnt(0)
	s_setprio 1
	s_barrier
	v_mfma_f32_16x16x32_bf16 v[60:63], v[120:123], v[160:163], v[60:63]
	v_mfma_f32_16x16x32_bf16 v[56:59], v[136:139], v[160:163], v[56:59]
	v_mfma_f32_16x16x32_bf16 v[44:47], v[120:123], v[168:171], v[44:47]
	v_mfma_f32_16x16x32_bf16 v[40:43], v[136:139], v[168:171], v[40:43]
	v_mfma_f32_16x16x32_bf16 v[28:31], v[120:123], v[176:179], v[28:31]
	v_mfma_f32_16x16x32_bf16 v[24:27], v[136:139], v[176:179], v[24:27]
	v_mfma_f32_16x16x32_bf16 v[12:15], v[120:123], v[218:221], v[12:15]
	v_mfma_f32_16x16x32_bf16 v[8:11], v[136:139], v[218:221], v[8:11]
	v_mfma_f32_16x16x32_bf16 v[60:63], v[124:127], v[164:167], v[60:63]
	v_mfma_f32_16x16x32_bf16 v[56:59], v[140:143], v[164:167], v[56:59]
	v_mfma_f32_16x16x32_bf16 v[44:47], v[124:127], v[172:175], v[44:47]
	v_mfma_f32_16x16x32_bf16 v[40:43], v[140:143], v[172:175], v[40:43]
	v_mfma_f32_16x16x32_bf16 v[28:31], v[124:127], v[180:183], v[28:31]
	v_mfma_f32_16x16x32_bf16 v[24:27], v[140:143], v[180:183], v[24:27]
	v_mfma_f32_16x16x32_bf16 v[12:15], v[124:127], v[222:225], v[12:15]
	v_mfma_f32_16x16x32_bf16 v[8:11], v[140:143], v[222:225], v[8:11]
	s_setprio 0
	s_setprio 1
	v_mfma_f32_16x16x32_bf16 v[52:55], v[144:147], v[160:163], v[52:55]
	v_mfma_f32_16x16x32_bf16 v[48:51], v[152:155], v[160:163], v[48:51]
	v_mfma_f32_16x16x32_bf16 v[36:39], v[144:147], v[168:171], v[36:39]
	v_mfma_f32_16x16x32_bf16 v[32:35], v[152:155], v[168:171], v[32:35]
	v_mfma_f32_16x16x32_bf16 v[20:23], v[144:147], v[176:179], v[20:23]
	v_mfma_f32_16x16x32_bf16 v[16:19], v[152:155], v[176:179], v[16:19]
	v_mfma_f32_16x16x32_bf16 v[4:7], v[144:147], v[218:221], v[4:7]
	v_mfma_f32_16x16x32_bf16 v[0:3], v[152:155], v[218:221], v[0:3]
	v_mfma_f32_16x16x32_bf16 v[52:55], v[148:151], v[164:167], v[52:55]
	v_mfma_f32_16x16x32_bf16 v[48:51], v[156:159], v[164:167], v[48:51]
	v_mfma_f32_16x16x32_bf16 v[36:39], v[148:151], v[172:175], v[36:39]
	v_mfma_f32_16x16x32_bf16 v[32:35], v[156:159], v[172:175], v[32:35]
	v_mfma_f32_16x16x32_bf16 v[20:23], v[148:151], v[180:183], v[20:23]
	v_mfma_f32_16x16x32_bf16 v[16:19], v[156:159], v[180:183], v[16:19]
	v_mfma_f32_16x16x32_bf16 v[4:7], v[148:151], v[222:225], v[4:7]
	v_mfma_f32_16x16x32_bf16 v[0:3], v[156:159], v[222:225], v[0:3]
	s_barrier
	s_setprio 0
	s_add_i32 s10, s10, 2
	s_add_u32 s8, s8, 0x100
	s_addc_u32 s9, s9, 0
	s_cmp_gt_u32 s10, 29
	s_mov_b64 s[48:49], s[46:47]

; __device__ __forceinline__ int lane_id_opq() { int l; asm volatile("v_mbcnt_lo_u32_b32 %0, -1, 0\n\tv_mbcnt_hi_u32_b32 %0, -1, %0" : "=v"(l)); return l; }
; #define PG8_STAGE(bufoff, gbase, voff) do { _Pragma("unroll") for (int _i = 0; _i < 2; ++_i) \
;         __builtin_amdgcn_global_load_lds((const unsigned*)((const char*)(gbase) + (voff)[_i]), (PG8_LAS unsigned*)(lds + (bufoff) + ldsw + _i * 8192), 16, 0, 0); } while (0)
; #define PG8_WAIT_V(n) asm volatile("s_waitcnt vmcnt(" #n ")" ::: "memory")
; #define PG8_WAIT_L(n) asm volatile("s_waitcnt lgkmcnt(" #n ")" ::: "memory")
; template <class Epi>
; __device__ __forceinline__ void gemm_phase(PG8_LAS unsigned char* lds, PG8_LAS unsigned char* xl, const Gemm g, const Sched& S, const Epi& E, const int wid) {
;     ...
;         for (int t = 0; t < nt; t += 2) {
;             const bool last = (t == nt - 2);
;             const bool do0 = !blkdiag_v<Epi> || t == 0, do1 = !blkdiag_v<Epi> || t != 0;
;             long j1 = 0, ja2 = 0, jb2 = 0;
;             if constexpr (Epi::MID) {
;                 if (t == g.tj) { const int lnM = lane_id_opq(); E.mid(acc, cur, wr, wc, lnM & 15, lnM >> 4); }
;                 if (t >= g.tj) j1 = g.jA;
;                 if (t + 2 >= g.tj) { ja2 = g.jA; jb2 = g.jB; } }
;             const char* a1 = cA + (size_t)(t + 1) * kstep + j1;
;             const char* a2 = last ? nA : cA + (size_t)(t + 2) * kstep + ja2; const char* b2 = last ? nB : cB + (size_t)(t + 2) * kstep + jb2;
;             const char* a3 = a2 + kstep; const char* b3 = b2 + kstep;
;             PG8_LDB(B0, 0, 0); PG8_LDB(B1, 0, 1); PG8_SCHED; PG8_LDA(At, 0, 0); PG8_STAGE(PG8_SA(1, 1), a1 + hstepA, voffA);
;             PG8_WAIT_V(8); PG8_WAIT_L(0); PG8_BAR; if (do0) { PG8_MMA(0, 0, At, B0); PG8_MMA(0, 1, At, B1); } PG8_BAR; PG8_SCHED;
;             PG8_LDA(At, 0, 1); PG8_STAGE(PG8_SB(0, 0), b2, voffB); PG8_STAGE(PG8_SB(0, 1), b2 + hstepB, voffB); PG8_STAGE(PG8_SA(0, 0), a2, voffA);
;             PG8_WAIT_V(8); PG8_WAIT_L(0); PG8_BAR; if (do1) { PG8_MMA(1, 0, At, B0); PG8_MMA(1, 1, At, B1); } PG8_BAR; PG8_SCHED;
;     ...
; #pragma unroll
;         for (int a = 0; a < 2; ++a)
; #pragma unroll
;             for (int b = 0; b < 2; ++b)
; #pragma unroll
;                 for (int m = 0; m < 4; ++m)
; #pragma unroll
;                     for (int n = 0; n < 2; ++n) acc[a][b][m][n] = (f32x4){0.f, 0.f, 0.f, 0.f};
.LBB0_958:
	s_add_u32 s8, s56, 0x100
	s_addc_u32 s9, s57, 0
	s_mov_b32 s10, -2
	s_waitcnt lgkmcnt(0)
	s_cmp_lg_u32 s100, 1
	s_cbranch_scc1 .Ldefbar_skip_8
	s_mov_b32 s100, 0
	s_barrier
.Ldefbar_skip_8:
	v_add_u32_e32 v204, s22, v188
	v_add_u32_e32 v205, s22, v190
	v_add_u32_e32 v218, s22, v210
	v_add_u32_e32 v219, s22, v212
	v_add_u32_e32 v226, 0x10000, v195
	s_add_u32 s56, s52, 0x100
	s_addc_u32 s57, s53, 0
	s_add_i32 s11, 0, 0x10000
	s_cmp_eq_u32 s10, 12
	s_cselect_b32 s61, s47, s57
	s_cselect_b32 s60, s46, s56
	s_cselect_b32 s59, s51, s9
	s_cselect_b32 s58, s50, s8
	s_add_i32 s13, 0, 0x14000
	ds_read_b128 v[124:127], v226 offset:0
	ds_read_b128 v[128:131], v226 offset:1024
	ds_read_b128 v[136:139], v226 offset:2048
	ds_read_b128 v[140:143], v226 offset:3072
	ds_read_b128 v[144:147], v226 offset:16384
	ds_read_b128 v[148:151], v226 offset:17408
	ds_read_b128 v[152:155], v226 offset:18432
	ds_read_b128 v[156:159], v226 offset:19456
	s_add_i32 m0, s66, 0xc000
	ds_read_b128 v[160:163], v220
	ds_read_b128 v[164:167], v220 offset:1024
	ds_read_b128 v[168:171], v220 offset:2048
	ds_read_b128 v[172:175], v220 offset:3072
	ds_read_b128 v[176:179], v220 offset:4096
	ds_read_b128 v[180:183], v220 offset:5120
	ds_read_b128 v[184:187], v220 offset:6144
	ds_read_b128 v[222:225], v220 offset:7168
	global_load_lds_dwordx4 v214, s[52:53]
	s_add_i32 m0, s66, 0xe000
	s_nop 0
	global_load_lds_dwordx4 v216, s[52:53]
	s_waitcnt vmcnt(8)
	s_waitcnt lgkmcnt(0)
	s_setprio 1
	s_barrier
	v_mfma_f32_16x16x32_bf16 v[132:135], v[124:127], v[160:163], 0
	v_mfma_f32_16x16x32_bf16 v[120:123], v[136:139], v[160:163], 0
	v_mfma_f32_16x16x32_bf16 v[108:111], v[124:127], v[168:171], 0
	v_mfma_f32_16x16x32_bf16 v[104:107], v[136:139], v[168:171], 0
	v_mfma_f32_16x16x32_bf16 v[92:95], v[124:127], v[176:179], 0
	v_mfma_f32_16x16x32_bf16 v[88:91], v[136:139], v[176:179], 0
	v_mfma_f32_16x16x32_bf16 v[76:79], v[124:127], v[184:187], 0
	v_mfma_f32_16x16x32_bf16 v[72:75], v[136:139], v[184:187], 0
	v_mfma_f32_16x16x32_bf16 v[132:135], v[128:131], v[164:167], v[132:135]
	v_mfma_f32_16x16x32_bf16 v[120:123], v[140:143], v[164:167], v[120:123]
	v_mfma_f32_16x16x32_bf16 v[108:111], v[128:131], v[172:175], v[108:111]
	v_mfma_f32_16x16x32_bf16 v[104:107], v[140:143], v[172:175], v[104:107]
	v_mfma_f32_16x16x32_bf16 v[92:95], v[128:131], v[180:183], v[92:95]
	v_mfma_f32_16x16x32_bf16 v[88:91], v[140:143], v[180:183], v[88:91]
	v_mfma_f32_16x16x32_bf16 v[76:79], v[128:131], v[222:225], v[76:79]
	v_mfma_f32_16x16x32_bf16 v[72:75], v[140:143], v[222:225], v[72:75]
	s_setprio 0
	s_setprio 1
	v_mfma_f32_16x16x32_bf16 v[116:119], v[144:147], v[160:163], 0
	v_mfma_f32_16x16x32_bf16 v[112:115], v[152:155], v[160:163], 0
	v_mfma_f32_16x16x32_bf16 v[100:103], v[144:147], v[168:171], 0
	v_mfma_f32_16x16x32_bf16 v[96:99], v[152:155], v[168:171], 0
	v_mfma_f32_16x16x32_bf16 v[84:87], v[144:147], v[176:179], 0
	v_mfma_f32_16x16x32_bf16 v[80:83], v[152:155], v[176:179], 0
	v_mfma_f32_16x16x32_bf16 v[68:71], v[144:147], v[184:187], 0
	v_mfma_f32_16x16x32_bf16 v[64:67], v[152:155], v[184:187], 0
	v_mfma_f32_16x16x32_bf16 v[116:119], v[148:151], v[164:167], v[116:119]
	v_mfma_f32_16x16x32_bf16 v[112:115], v[156:159], v[164:167], v[112:115]
	v_mfma_f32_16x16x32_bf16 v[100:103], v[148:151], v[172:175], v[100:103]
	v_mfma_f32_16x16x32_bf16 v[96:99], v[156:159], v[172:175], v[96:99]
	v_mfma_f32_16x16x32_bf16 v[84:87], v[148:151], v[180:183], v[84:87]
	v_mfma_f32_16x16x32_bf16 v[80:83], v[156:159], v[180:183], v[80:83]
	v_mfma_f32_16x16x32_bf16 v[68:71], v[148:151], v[222:225], v[68:71]
	v_mfma_f32_16x16x32_bf16 v[64:67], v[156:159], v[222:225], v[64:67]
	s_barrier
	s_setprio 0
	s_add_i32 s11, s11, s29
	s_mov_b32 m0, s11
	ds_read_b128 v[160:163], v220 offset:16384
	ds_read_b128 v[164:167], v220 offset:17408
	ds_read_b128 v[168:171], v220 offset:18432
	ds_read_b128 v[172:175], v220 offset:19456
	ds_read_b128 v[176:179], v220 offset:20480
	ds_read_b128 v[180:183], v220 offset:21504
	ds_read_b128 v[184:187], v220 offset:22528
	ds_read_b128 v[222:225], v220 offset:23552
	global_load_lds_dwordx4 v190, s[58:59]
	s_add_i32 m0, s11, 0x2000
	s_add_u32 s52, s58, 0x40000
	s_addc_u32 s53, s59, 0
	s_add_i32 s11, s13, s29
	global_load_lds_dwordx4 v212, s[58:59]
	s_mov_b32 m0, s11
	s_nop 0
	global_load_lds_dwordx4 v190, s[52:53]
	s_add_i32 m0, s11, 0x2000
	s_nop 0
	global_load_lds_dwordx4 v212, s[52:53]
	s_mov_b32 m0, s66
	s_nop 0
	global_load_lds_dwordx4 v188, s[60:61]
	s_mov_b32 m0, s67
	s_nop 0
	global_load_lds_dwordx4 v210, s[60:61]
	s_waitcnt vmcnt(8)
	s_waitcnt lgkmcnt(0)
	s_setprio 1
	s_barrier
; #define PG8_STAGE(bufoff, gbase, voff) do { _Pragma("unroll") for (int _i = 0; _i < 2; ++_i) \
;         __builtin_amdgcn_global_load_lds((const unsigned*)((const char*)(gbase) + (voff)[_i]), (PG8_LAS unsigned*)(lds + (bufoff) + ldsw + _i * 8192), 16, 0, 0); } while (0)
; #define PG8_LDA(dst, b, h) do { _Pragma("unroll") for (int m = 0; m < 4; ++m) _Pragma("unroll") for (int k = 0; k < 2; ++k) dst[m][k] = *(const PG8_LAS bf16x8*)(lds + PG8_SA(b, h) + aoff + m * 2048 + k * 1024); } while (0)
; #define PG8_LDB(dst, b, h) do { _Pragma("unroll") for (int n = 0; n < 2; ++n) _Pragma("unroll") for (int k = 0; k < 2; ++k) dst[n][k] = *(const PG8_LAS bf16x8*)(lds + PG8_SB(b, h) + boff + n * 2048 + k * 1024); } while (0)
; #define PG8_MMA(ai, bj, At, Bt) do { __builtin_amdgcn_s_setprio(1); _Pragma("unroll") for (int m = 0; m < 4; ++m) _Pragma("unroll") for (int n = 0; n < 2; ++n) _Pragma("unroll") for (int k = 0; k < 2; ++k) \
;         acc[ai][bj][m][n] = __builtin_amdgcn_mfma_f32_16x16x32_bf16(Bt[n][k], At[m][k], acc[ai][bj][m][n], 0, 0, 0); __builtin_amdgcn_s_setprio(0); } while (0)
; #define PG8_WAIT_V(n) asm volatile("s_waitcnt vmcnt(" #n ")" ::: "memory")
; #define PG8_WAIT_L(n) asm volatile("s_waitcnt lgkmcnt(" #n ")" ::: "memory")
; #define PG8_BAR __builtin_amdgcn_s_barrier()
; #define PG8_SCHED __builtin_amdgcn_sched_barrier(0)
; template <class Epi>
; __device__ __forceinline__ void gemm_phase(PG8_LAS unsigned char* lds, PG8_LAS unsigned char* xl, const Gemm g, const Sched& S, const Epi& E, const int wid) {
;     ...
;             PG8_WAIT_V(8); PG8_WAIT_L(0); PG8_BAR; if (do1) { PG8_MMA(1, 0, At, B0); PG8_MMA(1, 1, At, B1); } PG8_BAR; PG8_SCHED;
;             PG8_LDB(B0, 1, 0); PG8_LDB(B1, 1, 1); PG8_SCHED; PG8_LDA(At, 1, 0); PG8_STAGE(PG8_SA(0, 1), a2 + hstepA, voffA);
;             PG8_WAIT_V(8); PG8_WAIT_L(0); PG8_BAR; if (do0) { PG8_MMA(0, 0, At, B0); PG8_MMA(0, 1, At, B1); } PG8_BAR; PG8_SCHED;
;             PG8_LDA(At, 1, 1); PG8_STAGE(PG8_SB(1, 0), b3, voffB); PG8_STAGE(PG8_SB(1, 1), b3 + hstepB, voffB); PG8_STAGE(PG8_SA(1, 0), a3, voffA);
;             PG8_WAIT_V(8); PG8_WAIT_L(0); PG8_BAR; if (do1) { PG8_MMA(1, 0, At, B0); PG8_MMA(1, 1, At, B1); } PG8_BAR; PG8_SCHED;
	v_mfma_f32_16x16x32_bf16 v[60:63], v[124:127], v[160:163], 0
	v_mfma_f32_16x16x32_bf16 v[56:59], v[136:139], v[160:163], 0
	v_mfma_f32_16x16x32_bf16 v[44:47], v[124:127], v[168:171], 0
	v_mfma_f32_16x16x32_bf16 v[40:43], v[136:139], v[168:171], 0
	v_mfma_f32_16x16x32_bf16 v[28:31], v[124:127], v[176:179], 0
	v_mfma_f32_16x16x32_bf16 v[24:27], v[136:139], v[176:179], 0
	v_mfma_f32_16x16x32_bf16 v[12:15], v[124:127], v[184:187], 0
	v_mfma_f32_16x16x32_bf16 v[8:11], v[136:139], v[184:187], 0
	v_mfma_f32_16x16x32_bf16 v[60:63], v[128:131], v[164:167], v[60:63]
	v_mfma_f32_16x16x32_bf16 v[56:59], v[140:143], v[164:167], v[56:59]
	v_mfma_f32_16x16x32_bf16 v[44:47], v[128:131], v[172:175], v[44:47]
	v_mfma_f32_16x16x32_bf16 v[40:43], v[140:143], v[172:175], v[40:43]
	v_mfma_f32_16x16x32_bf16 v[28:31], v[128:131], v[180:183], v[28:31]
	v_mfma_f32_16x16x32_bf16 v[24:27], v[140:143], v[180:183], v[24:27]
	v_mfma_f32_16x16x32_bf16 v[12:15], v[128:131], v[222:225], v[12:15]
	v_mfma_f32_16x16x32_bf16 v[8:11], v[140:143], v[222:225], v[8:11]
	s_setprio 0
	s_setprio 1
	v_mfma_f32_16x16x32_bf16 v[52:55], v[144:147], v[160:163], 0
	v_mfma_f32_16x16x32_bf16 v[48:51], v[152:155], v[160:163], 0
	v_mfma_f32_16x16x32_bf16 v[36:39], v[144:147], v[168:171], 0
	v_mfma_f32_16x16x32_bf16 v[32:35], v[152:155], v[168:171], 0
	v_mfma_f32_16x16x32_bf16 v[20:23], v[144:147], v[176:179], 0
	v_mfma_f32_16x16x32_bf16 v[16:19], v[152:155], v[176:179], 0
	v_mfma_f32_16x16x32_bf16 v[4:7], v[144:147], v[184:187], 0
	v_mfma_f32_16x16x32_bf16 v[0:3], v[152:155], v[184:187], 0
	v_mfma_f32_16x16x32_bf16 v[52:55], v[148:151], v[164:167], v[52:55]
	v_mfma_f32_16x16x32_bf16 v[48:51], v[156:159], v[164:167], v[48:51]
	v_mfma_f32_16x16x32_bf16 v[36:39], v[148:151], v[172:175], v[36:39]
	v_mfma_f32_16x16x32_bf16 v[32:35], v[156:159], v[172:175], v[32:35]
	v_mfma_f32_16x16x32_bf16 v[20:23], v[148:151], v[180:183], v[20:23]
	v_mfma_f32_16x16x32_bf16 v[16:19], v[156:159], v[180:183], v[16:19]
	v_mfma_f32_16x16x32_bf16 v[4:7], v[148:151], v[222:225], v[4:7]
	v_mfma_f32_16x16x32_bf16 v[0:3], v[156:159], v[222:225], v[0:3]
	s_barrier
	s_setprio 0
	s_add_i32 s11, 0, 0x18000
	s_add_i32 s13, 0, 0x1c000
	ds_read_b128 v[124:127], v226 offset:32768
	ds_read_b128 v[128:131], v226 offset:33792
	ds_read_b128 v[136:139], v226 offset:34816
	ds_read_b128 v[140:143], v226 offset:35840
	ds_read_b128 v[144:147], v226 offset:49152
	ds_read_b128 v[148:151], v226 offset:50176
	ds_read_b128 v[152:155], v226 offset:51200
	ds_read_b128 v[156:159], v226 offset:52224
	s_add_u32 s52, s60, 0x40000
	s_addc_u32 s53, s61, 0
	s_mov_b32 m0, s68
	ds_read_b128 v[160:163], v220 offset:32768
	ds_read_b128 v[164:167], v220 offset:33792
	ds_read_b128 v[168:171], v220 offset:34816
	ds_read_b128 v[172:175], v220 offset:35840
	ds_read_b128 v[176:179], v220 offset:36864
	ds_read_b128 v[180:183], v220 offset:37888
	ds_read_b128 v[184:187], v220 offset:38912
	ds_read_b128 v[222:225], v220 offset:39936
	global_load_lds_dwordx4 v188, s[52:53]
	s_mov_b32 m0, s69
	s_nop 0
	global_load_lds_dwordx4 v210, s[52:53]
	s_waitcnt vmcnt(8)
	s_waitcnt lgkmcnt(0)
	s_setprio 1
	s_barrier
	v_mfma_f32_16x16x32_bf16 v[132:135], v[124:127], v[160:163], v[132:135]
	v_mfma_f32_16x16x32_bf16 v[120:123], v[136:139], v[160:163], v[120:123]
	v_mfma_f32_16x16x32_bf16 v[108:111], v[124:127], v[168:171], v[108:111]
	v_mfma_f32_16x16x32_bf16 v[104:107], v[136:139], v[168:171], v[104:107]
	v_mfma_f32_16x16x32_bf16 v[92:95], v[124:127], v[176:179], v[92:95]
	v_mfma_f32_16x16x32_bf16 v[88:91], v[136:139], v[176:179], v[88:91]
	v_mfma_f32_16x16x32_bf16 v[76:79], v[124:127], v[184:187], v[76:79]
	v_mfma_f32_16x16x32_bf16 v[72:75], v[136:139], v[184:187], v[72:75]
	v_mfma_f32_16x16x32_bf16 v[132:135], v[128:131], v[164:167], v[132:135]
	v_mfma_f32_16x16x32_bf16 v[120:123], v[140:143], v[164:167], v[120:123]
	v_mfma_f32_16x16x32_bf16 v[108:111], v[128:131], v[172:175], v[108:111]
	v_mfma_f32_16x16x32_bf16 v[104:107], v[140:143], v[172:175], v[104:107]
	v_mfma_f32_16x16x32_bf16 v[92:95], v[128:131], v[180:183], v[92:95]
	v_mfma_f32_16x16x32_bf16 v[88:91], v[140:143], v[180:183], v[88:91]
	v_mfma_f32_16x16x32_bf16 v[76:79], v[128:131], v[222:225], v[76:79]
	v_mfma_f32_16x16x32_bf16 v[72:75], v[140:143], v[222:225], v[72:75]
	s_setprio 0
	s_setprio 1
	v_mfma_f32_16x16x32_bf16 v[116:119], v[144:147], v[160:163], v[116:119]
	v_mfma_f32_16x16x32_bf16 v[112:115], v[152:155], v[160:163], v[112:115]
	v_mfma_f32_16x16x32_bf16 v[100:103], v[144:147], v[168:171], v[100:103]
	v_mfma_f32_16x16x32_bf16 v[96:99], v[152:155], v[168:171], v[96:99]
	v_mfma_f32_16x16x32_bf16 v[84:87], v[144:147], v[176:179], v[84:87]
	v_mfma_f32_16x16x32_bf16 v[80:83], v[152:155], v[176:179], v[80:83]
	v_mfma_f32_16x16x32_bf16 v[68:71], v[144:147], v[184:187], v[68:71]
	v_mfma_f32_16x16x32_bf16 v[64:67], v[152:155], v[184:187], v[64:67]
	v_mfma_f32_16x16x32_bf16 v[116:119], v[148:151], v[164:167], v[116:119]
	v_mfma_f32_16x16x32_bf16 v[112:115], v[156:159], v[164:167], v[112:115]
	v_mfma_f32_16x16x32_bf16 v[100:103], v[148:151], v[172:175], v[100:103]
	v_mfma_f32_16x16x32_bf16 v[96:99], v[156:159], v[172:175], v[96:99]
	v_mfma_f32_16x16x32_bf16 v[84:87], v[148:151], v[180:183], v[84:87]
	v_mfma_f32_16x16x32_bf16 v[80:83], v[156:159], v[180:183], v[80:83]
	v_mfma_f32_16x16x32_bf16 v[68:71], v[148:151], v[222:225], v[68:71]
	v_mfma_f32_16x16x32_bf16 v[64:67], v[156:159], v[222:225], v[64:67]
	s_barrier
; #define PG8_STAGE(bufoff, gbase, voff) do { _Pragma("unroll") for (int _i = 0; _i < 2; ++_i) \
;         __builtin_amdgcn_global_load_lds((const unsigned*)((const char*)(gbase) + (voff)[_i]), (PG8_LAS unsigned*)(lds + (bufoff) + ldsw + _i * 8192), 16, 0, 0); } while (0)
; #define PG8_LDA(dst, b, h) do { _Pragma("unroll") for (int m = 0; m < 4; ++m) _Pragma("unroll") for (int k = 0; k < 2; ++k) dst[m][k] = *(const PG8_LAS bf16x8*)(lds + PG8_SA(b, h) + aoff + m * 2048 + k * 1024); } while (0)
; #define PG8_MMA(ai, bj, At, Bt) do { __builtin_amdgcn_s_setprio(1); _Pragma("unroll") for (int m = 0; m < 4; ++m) _Pragma("unroll") for (int n = 0; n < 2; ++n) _Pragma("unroll") for (int k = 0; k < 2; ++k) \
;         acc[ai][bj][m][n] = __builtin_amdgcn_mfma_f32_16x16x32_bf16(Bt[n][k], At[m][k], acc[ai][bj][m][n], 0, 0, 0); __builtin_amdgcn_s_setprio(0); } while (0)
; #define PG8_WAIT_V(n) asm volatile("s_waitcnt vmcnt(" #n ")" ::: "memory")
; #define PG8_WAIT_L(n) asm volatile("s_waitcnt lgkmcnt(" #n ")" ::: "memory")
; #define PG8_BAR __builtin_amdgcn_s_barrier()
; #define PG8_SCHED __builtin_amdgcn_sched_barrier(0)
; template <class Epi>
; __device__ __forceinline__ void gemm_phase(PG8_LAS unsigned char* lds, PG8_LAS unsigned char* xl, const Gemm g, const Sched& S, const Epi& E, const int wid) {
;     ...
;             PG8_LDA(At, 1, 1); PG8_STAGE(PG8_SB(1, 0), b3, voffB); PG8_STAGE(PG8_SB(1, 1), b3 + hstepB, voffB); PG8_STAGE(PG8_SA(1, 0), a3, voffA);
;             PG8_WAIT_V(8); PG8_WAIT_L(0); PG8_BAR; if (do1) { PG8_MMA(1, 0, At, B0); PG8_MMA(1, 1, At, B1); } PG8_BAR; PG8_SCHED;
;         }
	s_setprio 0
	s_add_i32 s11, s11, s29
	s_mov_b32 m0, s11
	ds_read_b128 v[160:163], v220 offset:49152
	ds_read_b128 v[164:167], v220 offset:50176
	ds_read_b128 v[168:171], v220 offset:51200
	ds_read_b128 v[172:175], v220 offset:52224
	ds_read_b128 v[176:179], v220 offset:53248
	ds_read_b128 v[180:183], v220 offset:54272
	ds_read_b128 v[184:187], v220 offset:55296
	ds_read_b128 v[222:225], v220 offset:56320
	global_load_lds_dwordx4 v205, s[58:59]
	s_add_i32 m0, s11, 0x2000
	s_add_u32 s52, s58, 0x40080
	global_load_lds_dwordx4 v219, s[58:59]
	s_addc_u32 s53, s59, 0
	s_add_i32 s11, s13, s29
	s_mov_b32 m0, s11
	s_nop 0
	global_load_lds_dwordx4 v190, s[52:53]
	s_add_i32 m0, s11, 0x2000
	s_nop 0
	global_load_lds_dwordx4 v212, s[52:53]
	s_mov_b32 m0, s87
	s_nop 0
	global_load_lds_dwordx4 v204, s[60:61]
	s_mov_b32 m0, s88
	s_nop 0
	global_load_lds_dwordx4 v218, s[60:61]
	s_waitcnt vmcnt(8)
	s_waitcnt lgkmcnt(0)
	s_setprio 1
	s_barrier
	v_mfma_f32_16x16x32_bf16 v[60:63], v[124:127], v[160:163], v[60:63]
	v_mfma_f32_16x16x32_bf16 v[56:59], v[136:139], v[160:163], v[56:59]
	v_mfma_f32_16x16x32_bf16 v[44:47], v[124:127], v[168:171], v[44:47]
	v_mfma_f32_16x16x32_bf16 v[40:43], v[136:139], v[168:171], v[40:43]
	v_mfma_f32_16x16x32_bf16 v[28:31], v[124:127], v[176:179], v[28:31]
	v_mfma_f32_16x16x32_bf16 v[24:27], v[136:139], v[176:179], v[24:27]
	v_mfma_f32_16x16x32_bf16 v[12:15], v[124:127], v[184:187], v[12:15]
	v_mfma_f32_16x16x32_bf16 v[8:11], v[136:139], v[184:187], v[8:11]
	v_mfma_f32_16x16x32_bf16 v[60:63], v[128:131], v[164:167], v[60:63]
	v_mfma_f32_16x16x32_bf16 v[56:59], v[140:143], v[164:167], v[56:59]
	v_mfma_f32_16x16x32_bf16 v[44:47], v[128:131], v[172:175], v[44:47]
	v_mfma_f32_16x16x32_bf16 v[40:43], v[140:143], v[172:175], v[40:43]
	v_mfma_f32_16x16x32_bf16 v[28:31], v[128:131], v[180:183], v[28:31]
	v_mfma_f32_16x16x32_bf16 v[24:27], v[140:143], v[180:183], v[24:27]
	v_mfma_f32_16x16x32_bf16 v[12:15], v[128:131], v[222:225], v[12:15]
	v_mfma_f32_16x16x32_bf16 v[8:11], v[140:143], v[222:225], v[8:11]
	s_setprio 0
	s_setprio 1
	v_mfma_f32_16x16x32_bf16 v[52:55], v[144:147], v[160:163], v[52:55]
	v_mfma_f32_16x16x32_bf16 v[48:51], v[152:155], v[160:163], v[48:51]
	v_mfma_f32_16x16x32_bf16 v[36:39], v[144:147], v[168:171], v[36:39]
	v_mfma_f32_16x16x32_bf16 v[32:35], v[152:155], v[168:171], v[32:35]
	v_mfma_f32_16x16x32_bf16 v[20:23], v[144:147], v[176:179], v[20:23]
	v_mfma_f32_16x16x32_bf16 v[16:19], v[152:155], v[176:179], v[16:19]
	v_mfma_f32_16x16x32_bf16 v[4:7], v[144:147], v[184:187], v[4:7]
	v_mfma_f32_16x16x32_bf16 v[0:3], v[152:155], v[184:187], v[0:3]
	v_mfma_f32_16x16x32_bf16 v[52:55], v[148:151], v[164:167], v[52:55]
	v_mfma_f32_16x16x32_bf16 v[48:51], v[156:159], v[164:167], v[48:51]
	v_mfma_f32_16x16x32_bf16 v[36:39], v[148:151], v[172:175], v[36:39]
	v_mfma_f32_16x16x32_bf16 v[32:35], v[156:159], v[172:175], v[32:35]
	v_mfma_f32_16x16x32_bf16 v[20:23], v[148:151], v[180:183], v[20:23]
	v_mfma_f32_16x16x32_bf16 v[16:19], v[156:159], v[180:183], v[16:19]
	v_mfma_f32_16x16x32_bf16 v[4:7], v[148:151], v[222:225], v[4:7]
	v_mfma_f32_16x16x32_bf16 v[0:3], v[156:159], v[222:225], v[0:3]
	s_barrier
	s_setprio 0
	s_add_i32 s10, s10, 2
	s_add_u32 s8, s8, 0x100
	s_addc_u32 s9, s9, 0
	s_cmp_gt_u32 s10, 13
	s_mov_b64 s[52:53], s[56:57]

; __device__ __forceinline__ int lane_id_opq() { int l; asm volatile("v_mbcnt_lo_u32_b32 %0, -1, 0\n\tv_mbcnt_hi_u32_b32 %0, -1, %0" : "=v"(l)); return l; }
; #define PG8_STAGE(bufoff, gbase, voff) do { _Pragma("unroll") for (int _i = 0; _i < 2; ++_i) \
;         __builtin_amdgcn_global_load_lds((const unsigned*)((const char*)(gbase) + (voff)[_i]), (PG8_LAS unsigned*)(lds + (bufoff) + ldsw + _i * 8192), 16, 0, 0); } while (0)
; #define PG8_WAIT_V(n) asm volatile("s_waitcnt vmcnt(" #n ")" ::: "memory")
; #define PG8_WAIT_L(n) asm volatile("s_waitcnt lgkmcnt(" #n ")" ::: "memory")
; template <class Epi>
; __device__ __forceinline__ void gemm_phase(PG8_LAS unsigned char* lds, PG8_LAS unsigned char* xl, const Gemm g, const Sched& S, const Epi& E, const int wid) {
;     ...
;         for (int t = 0; t < nt; t += 2) {
;             const bool last = (t == nt - 2);
;             const bool do0 = !blkdiag_v<Epi> || t == 0, do1 = !blkdiag_v<Epi> || t != 0;
;             long j1 = 0, ja2 = 0, jb2 = 0;
;             if constexpr (Epi::MID) {
;                 if (t == g.tj) { const int lnM = lane_id_opq(); E.mid(acc, cur, wr, wc, lnM & 15, lnM >> 4); }
;                 if (t >= g.tj) j1 = g.jA;
;                 if (t + 2 >= g.tj) { ja2 = g.jA; jb2 = g.jB; } }
;             const char* a1 = cA + (size_t)(t + 1) * kstep + j1;
;             const char* a2 = last ? nA : cA + (size_t)(t + 2) * kstep + ja2; const char* b2 = last ? nB : cB + (size_t)(t + 2) * kstep + jb2;
;             const char* a3 = a2 + kstep; const char* b3 = b2 + kstep;
;             PG8_LDB(B0, 0, 0); PG8_LDB(B1, 0, 1); PG8_SCHED; PG8_LDA(At, 0, 0); PG8_STAGE(PG8_SA(1, 1), a1 + hstepA, voffA);
;             PG8_WAIT_V(8); PG8_WAIT_L(0); PG8_BAR; if (do0) { PG8_MMA(0, 0, At, B0); PG8_MMA(0, 1, At, B1); } PG8_BAR; PG8_SCHED;
;             PG8_LDA(At, 0, 1); PG8_STAGE(PG8_SB(0, 0), b2, voffB); PG8_STAGE(PG8_SB(0, 1), b2 + hstepB, voffB); PG8_STAGE(PG8_SA(0, 0), a2, voffA);
;             PG8_WAIT_V(8); PG8_WAIT_L(0); PG8_BAR; if (do1) { PG8_MMA(1, 0, At, B0); PG8_MMA(1, 1, At, B1); } PG8_BAR; PG8_SCHED;
;     ...
; #pragma unroll
;         for (int a = 0; a < 2; ++a)
; #pragma unroll
;             for (int b = 0; b < 2; ++b)
; #pragma unroll
;                 for (int m = 0; m < 4; ++m)
; #pragma unroll
;                     for (int n = 0; n < 2; ++n) acc[a][b][m][n] = (f32x4){0.f, 0.f, 0.f, 0.f};
.LBB0_1303:
	s_add_u32 s36, s36, 0x160080
	s_addc_u32 s37, s37, 0
	s_add_u32 s1, s40, 0x100
	s_addc_u32 s8, s41, 0
	s_mov_b32 s9, -2
	s_waitcnt lgkmcnt(0)
	s_cmp_lg_u32 s100, 1
	s_cbranch_scc1 .Ldefbar_skip_10
	s_mov_b32 s100, 0
	s_barrier
.Ldefbar_skip_10:
	v_add_u32_e32 v204, s22, v188
	v_add_u32_e32 v205, s22, v190
	v_add_u32_e32 v218, s22, v210
	v_add_u32_e32 v219, s22, v212
	v_add_u32_e32 v226, 0x10000, v195
	s_add_u32 s4, s36, 0xffea0080
	s_addc_u32 s5, s37, -1
	s_add_i32 s13, 0, 0x10000
	s_cmpk_eq_i32 s9, 0x54
	s_cselect_b32 s11, s21, s5
	s_cselect_b32 s10, s20, s4
	s_cselect_b32 s41, s31, s8
	s_cselect_b32 s40, s30, s1
	s_add_i32 s4, 0, 0x14000
	ds_read_b128 v[120:123], v226 offset:0
	ds_read_b128 v[124:127], v226 offset:1024
	ds_read_b128 v[128:131], v226 offset:2048
	ds_read_b128 v[136:139], v226 offset:3072
	ds_read_b128 v[144:147], v226 offset:16384
	ds_read_b128 v[148:151], v226 offset:17408
	ds_read_b128 v[152:155], v226 offset:18432
	ds_read_b128 v[156:159], v226 offset:19456
	s_add_i32 m0, s51, 0xc000
	ds_read_b128 v[160:163], v220
	ds_read_b128 v[164:167], v220 offset:1024
	ds_read_b128 v[168:171], v220 offset:2048
	ds_read_b128 v[172:175], v220 offset:3072
	ds_read_b128 v[176:179], v220 offset:4096
	ds_read_b128 v[180:183], v220 offset:5120
	ds_read_b128 v[184:187], v220 offset:6144
	ds_read_b128 v[222:225], v220 offset:7168
	global_load_lds_dwordx4 v214, s[36:37]
	s_add_i32 m0, s51, 0xe000
	s_nop 0
	global_load_lds_dwordx4 v216, s[36:37]
	s_waitcnt vmcnt(8)
	s_waitcnt lgkmcnt(0)
	s_setprio 1
	s_barrier
	v_mfma_f32_16x16x32_bf16 v[140:143], v[120:123], v[160:163], 0
	v_mfma_f32_16x16x32_bf16 v[132:135], v[128:131], v[160:163], 0
	v_mfma_f32_16x16x32_bf16 v[108:111], v[120:123], v[168:171], 0
	v_mfma_f32_16x16x32_bf16 v[104:107], v[128:131], v[168:171], 0
	v_mfma_f32_16x16x32_bf16 v[92:95], v[120:123], v[176:179], 0
	v_mfma_f32_16x16x32_bf16 v[88:91], v[128:131], v[176:179], 0
	v_mfma_f32_16x16x32_bf16 v[76:79], v[120:123], v[184:187], 0
	v_mfma_f32_16x16x32_bf16 v[72:75], v[128:131], v[184:187], 0
	v_mfma_f32_16x16x32_bf16 v[140:143], v[124:127], v[164:167], v[140:143]
	v_mfma_f32_16x16x32_bf16 v[132:135], v[136:139], v[164:167], v[132:135]
	v_mfma_f32_16x16x32_bf16 v[108:111], v[124:127], v[172:175], v[108:111]
	v_mfma_f32_16x16x32_bf16 v[104:107], v[136:139], v[172:175], v[104:107]
	v_mfma_f32_16x16x32_bf16 v[92:95], v[124:127], v[180:183], v[92:95]
	v_mfma_f32_16x16x32_bf16 v[88:91], v[136:139], v[180:183], v[88:91]
	v_mfma_f32_16x16x32_bf16 v[76:79], v[124:127], v[222:225], v[76:79]
	v_mfma_f32_16x16x32_bf16 v[72:75], v[136:139], v[222:225], v[72:75]
	s_setprio 0
	s_setprio 1
	v_mfma_f32_16x16x32_bf16 v[116:119], v[144:147], v[160:163], 0
	v_mfma_f32_16x16x32_bf16 v[112:115], v[152:155], v[160:163], 0
	v_mfma_f32_16x16x32_bf16 v[100:103], v[144:147], v[168:171], 0
	v_mfma_f32_16x16x32_bf16 v[96:99], v[152:155], v[168:171], 0
	v_mfma_f32_16x16x32_bf16 v[84:87], v[144:147], v[176:179], 0
	v_mfma_f32_16x16x32_bf16 v[80:83], v[152:155], v[176:179], 0
	v_mfma_f32_16x16x32_bf16 v[68:71], v[144:147], v[184:187], 0
	v_mfma_f32_16x16x32_bf16 v[64:67], v[152:155], v[184:187], 0
	v_mfma_f32_16x16x32_bf16 v[116:119], v[148:151], v[164:167], v[116:119]
	v_mfma_f32_16x16x32_bf16 v[112:115], v[156:159], v[164:167], v[112:115]
	v_mfma_f32_16x16x32_bf16 v[100:103], v[148:151], v[172:175], v[100:103]
	v_mfma_f32_16x16x32_bf16 v[96:99], v[156:159], v[172:175], v[96:99]
	v_mfma_f32_16x16x32_bf16 v[84:87], v[148:151], v[180:183], v[84:87]
	v_mfma_f32_16x16x32_bf16 v[80:83], v[156:159], v[180:183], v[80:83]
	v_mfma_f32_16x16x32_bf16 v[68:71], v[148:151], v[222:225], v[68:71]
	v_mfma_f32_16x16x32_bf16 v[64:67], v[156:159], v[222:225], v[64:67]
	s_barrier
	s_setprio 0
	s_add_i32 s5, s13, s29
	s_mov_b32 m0, s5
	ds_read_b128 v[160:163], v220 offset:16384
	ds_read_b128 v[164:167], v220 offset:17408
	ds_read_b128 v[168:171], v220 offset:18432
	ds_read_b128 v[172:175], v220 offset:19456
	ds_read_b128 v[176:179], v220 offset:20480
	ds_read_b128 v[180:183], v220 offset:21504
	ds_read_b128 v[184:187], v220 offset:22528
	ds_read_b128 v[222:225], v220 offset:23552
	global_load_lds_dwordx4 v190, s[40:41]
	s_add_i32 m0, s5, 0x2000
	s_add_u32 s44, s40, 0x160000
	s_addc_u32 s45, s41, 0
	s_add_i32 s4, s4, s29
	global_load_lds_dwordx4 v212, s[40:41]
	s_mov_b32 m0, s4
	s_nop 0
	global_load_lds_dwordx4 v190, s[44:45]
	s_add_i32 m0, s4, 0x2000
	s_nop 0
	global_load_lds_dwordx4 v212, s[44:45]
	s_mov_b32 m0, s51
	s_nop 0
	global_load_lds_dwordx4 v188, s[10:11]
	s_mov_b32 m0, s52
	s_nop 0
	global_load_lds_dwordx4 v210, s[10:11]
	s_waitcnt vmcnt(8)
	s_waitcnt lgkmcnt(0)
	s_setprio 1
	s_barrier
; #define PG8_STAGE(bufoff, gbase, voff) do { _Pragma("unroll") for (int _i = 0; _i < 2; ++_i) \
;         __builtin_amdgcn_global_load_lds((const unsigned*)((const char*)(gbase) + (voff)[_i]), (PG8_LAS unsigned*)(lds + (bufoff) + ldsw + _i * 8192), 16, 0, 0); } while (0)
; #define PG8_LDA(dst, b, h) do { _Pragma("unroll") for (int m = 0; m < 4; ++m) _Pragma("unroll") for (int k = 0; k < 2; ++k) dst[m][k] = *(const PG8_LAS bf16x8*)(lds + PG8_SA(b, h) + aoff + m * 2048 + k * 1024); } while (0)
; #define PG8_LDB(dst, b, h) do { _Pragma("unroll") for (int n = 0; n < 2; ++n) _Pragma("unroll") for (int k = 0; k < 2; ++k) dst[n][k] = *(const PG8_LAS bf16x8*)(lds + PG8_SB(b, h) + boff + n * 2048 + k * 1024); } while (0)
; #define PG8_MMA(ai, bj, At, Bt) do { __builtin_amdgcn_s_setprio(1); _Pragma("unroll") for (int m = 0; m < 4; ++m) _Pragma("unroll") for (int n = 0; n < 2; ++n) _Pragma("unroll") for (int k = 0; k < 2; ++k) \
;         acc[ai][bj][m][n] = __builtin_amdgcn_mfma_f32_16x16x32_bf16(Bt[n][k], At[m][k], acc[ai][bj][m][n], 0, 0, 0); __builtin_amdgcn_s_setprio(0); } while (0)
; #define PG8_WAIT_V(n) asm volatile("s_waitcnt vmcnt(" #n ")" ::: "memory")
; #define PG8_WAIT_L(n) asm volatile("s_waitcnt lgkmcnt(" #n ")" ::: "memory")
; #define PG8_BAR __builtin_amdgcn_s_barrier()
; #define PG8_SCHED __builtin_amdgcn_sched_barrier(0)
; template <class Epi>
; __device__ __forceinline__ void gemm_phase(PG8_LAS unsigned char* lds, PG8_LAS unsigned char* xl, const Gemm g, const Sched& S, const Epi& E, const int wid) {
;     ...
;             PG8_WAIT_V(8); PG8_WAIT_L(0); PG8_BAR; if (do1) { PG8_MMA(1, 0, At, B0); PG8_MMA(1, 1, At, B1); } PG8_BAR; PG8_SCHED;
;             PG8_LDB(B0, 1, 0); PG8_LDB(B1, 1, 1); PG8_SCHED; PG8_LDA(At, 1, 0); PG8_STAGE(PG8_SA(0, 1), a2 + hstepA, voffA);
;             PG8_WAIT_V(8); PG8_WAIT_L(0); PG8_BAR; if (do0) { PG8_MMA(0, 0, At, B0); PG8_MMA(0, 1, At, B1); } PG8_BAR; PG8_SCHED;
;             PG8_LDA(At, 1, 1); PG8_STAGE(PG8_SB(1, 0), b3, voffB); PG8_STAGE(PG8_SB(1, 1), b3 + hstepB, voffB); PG8_STAGE(PG8_SA(1, 0), a3, voffA);
;             PG8_WAIT_V(8); PG8_WAIT_L(0); PG8_BAR; if (do1) { PG8_MMA(1, 0, At, B0); PG8_MMA(1, 1, At, B1); } PG8_BAR; PG8_SCHED;
	v_mfma_f32_16x16x32_bf16 v[60:63], v[120:123], v[160:163], 0
	v_mfma_f32_16x16x32_bf16 v[56:59], v[128:131], v[160:163], 0
	v_mfma_f32_16x16x32_bf16 v[44:47], v[120:123], v[168:171], 0
	v_mfma_f32_16x16x32_bf16 v[40:43], v[128:131], v[168:171], 0
	v_mfma_f32_16x16x32_bf16 v[28:31], v[120:123], v[176:179], 0
	v_mfma_f32_16x16x32_bf16 v[24:27], v[128:131], v[176:179], 0
	v_mfma_f32_16x16x32_bf16 v[12:15], v[120:123], v[184:187], 0
	v_mfma_f32_16x16x32_bf16 v[8:11], v[128:131], v[184:187], 0
	v_mfma_f32_16x16x32_bf16 v[60:63], v[124:127], v[164:167], v[60:63]
	v_mfma_f32_16x16x32_bf16 v[56:59], v[136:139], v[164:167], v[56:59]
	v_mfma_f32_16x16x32_bf16 v[44:47], v[124:127], v[172:175], v[44:47]
	v_mfma_f32_16x16x32_bf16 v[40:43], v[136:139], v[172:175], v[40:43]
	v_mfma_f32_16x16x32_bf16 v[28:31], v[124:127], v[180:183], v[28:31]
	v_mfma_f32_16x16x32_bf16 v[24:27], v[136:139], v[180:183], v[24:27]
	v_mfma_f32_16x16x32_bf16 v[12:15], v[124:127], v[222:225], v[12:15]
	v_mfma_f32_16x16x32_bf16 v[8:11], v[136:139], v[222:225], v[8:11]
	s_setprio 0
	s_setprio 1
	v_mfma_f32_16x16x32_bf16 v[52:55], v[144:147], v[160:163], 0
	v_mfma_f32_16x16x32_bf16 v[48:51], v[152:155], v[160:163], 0
	v_mfma_f32_16x16x32_bf16 v[36:39], v[144:147], v[168:171], 0
	v_mfma_f32_16x16x32_bf16 v[32:35], v[152:155], v[168:171], 0
	v_mfma_f32_16x16x32_bf16 v[20:23], v[144:147], v[176:179], 0
	v_mfma_f32_16x16x32_bf16 v[16:19], v[152:155], v[176:179], 0
	v_mfma_f32_16x16x32_bf16 v[4:7], v[144:147], v[184:187], 0
	v_mfma_f32_16x16x32_bf16 v[0:3], v[152:155], v[184:187], 0
	v_mfma_f32_16x16x32_bf16 v[52:55], v[148:151], v[164:167], v[52:55]
	v_mfma_f32_16x16x32_bf16 v[48:51], v[156:159], v[164:167], v[48:51]
	v_mfma_f32_16x16x32_bf16 v[36:39], v[148:151], v[172:175], v[36:39]
	v_mfma_f32_16x16x32_bf16 v[32:35], v[156:159], v[172:175], v[32:35]
	v_mfma_f32_16x16x32_bf16 v[20:23], v[148:151], v[180:183], v[20:23]
	v_mfma_f32_16x16x32_bf16 v[16:19], v[156:159], v[180:183], v[16:19]
	v_mfma_f32_16x16x32_bf16 v[4:7], v[148:151], v[222:225], v[4:7]
	v_mfma_f32_16x16x32_bf16 v[0:3], v[156:159], v[222:225], v[0:3]
	s_barrier
	s_setprio 0
	s_add_i32 s4, 0, 0x18000
	s_add_i32 s5, 0, 0x1c000
	ds_read_b128 v[120:123], v226 offset:32768
	ds_read_b128 v[124:127], v226 offset:33792
	ds_read_b128 v[128:131], v226 offset:34816
	ds_read_b128 v[136:139], v226 offset:35840
	ds_read_b128 v[144:147], v226 offset:49152
	ds_read_b128 v[148:151], v226 offset:50176
	ds_read_b128 v[152:155], v226 offset:51200
	ds_read_b128 v[156:159], v226 offset:52224
	s_add_u32 s100, s10, 0x160000
	s_addc_u32 s101, s11, 0
	s_mov_b32 m0, s53
	ds_read_b128 v[160:163], v220 offset:32768
	ds_read_b128 v[164:167], v220 offset:33792
	ds_read_b128 v[168:171], v220 offset:34816
	ds_read_b128 v[172:175], v220 offset:35840
	ds_read_b128 v[176:179], v220 offset:36864
	ds_read_b128 v[180:183], v220 offset:37888
	ds_read_b128 v[184:187], v220 offset:38912
	ds_read_b128 v[222:225], v220 offset:39936
	global_load_lds_dwordx4 v188, s[100:101]
	s_mov_b32 m0, s56
	s_nop 0
	global_load_lds_dwordx4 v210, s[100:101]
	s_waitcnt vmcnt(8)
	s_waitcnt lgkmcnt(0)
	s_setprio 1
	s_barrier
	v_mfma_f32_16x16x32_bf16 v[140:143], v[120:123], v[160:163], v[140:143]
	v_mfma_f32_16x16x32_bf16 v[132:135], v[128:131], v[160:163], v[132:135]
	v_mfma_f32_16x16x32_bf16 v[108:111], v[120:123], v[168:171], v[108:111]
	v_mfma_f32_16x16x32_bf16 v[104:107], v[128:131], v[168:171], v[104:107]
	v_mfma_f32_16x16x32_bf16 v[92:95], v[120:123], v[176:179], v[92:95]
	v_mfma_f32_16x16x32_bf16 v[88:91], v[128:131], v[176:179], v[88:91]
	v_mfma_f32_16x16x32_bf16 v[76:79], v[120:123], v[184:187], v[76:79]
	v_mfma_f32_16x16x32_bf16 v[72:75], v[128:131], v[184:187], v[72:75]
	v_mfma_f32_16x16x32_bf16 v[140:143], v[124:127], v[164:167], v[140:143]
	v_mfma_f32_16x16x32_bf16 v[132:135], v[136:139], v[164:167], v[132:135]
	v_mfma_f32_16x16x32_bf16 v[108:111], v[124:127], v[172:175], v[108:111]
	v_mfma_f32_16x16x32_bf16 v[104:107], v[136:139], v[172:175], v[104:107]
	v_mfma_f32_16x16x32_bf16 v[92:95], v[124:127], v[180:183], v[92:95]
	v_mfma_f32_16x16x32_bf16 v[88:91], v[136:139], v[180:183], v[88:91]
	v_mfma_f32_16x16x32_bf16 v[76:79], v[124:127], v[222:225], v[76:79]
	v_mfma_f32_16x16x32_bf16 v[72:75], v[136:139], v[222:225], v[72:75]
	s_setprio 0
	s_setprio 1
	v_mfma_f32_16x16x32_bf16 v[116:119], v[144:147], v[160:163], v[116:119]
	v_mfma_f32_16x16x32_bf16 v[112:115], v[152:155], v[160:163], v[112:115]
	v_mfma_f32_16x16x32_bf16 v[100:103], v[144:147], v[168:171], v[100:103]
	v_mfma_f32_16x16x32_bf16 v[96:99], v[152:155], v[168:171], v[96:99]
	v_mfma_f32_16x16x32_bf16 v[84:87], v[144:147], v[176:179], v[84:87]
	v_mfma_f32_16x16x32_bf16 v[80:83], v[152:155], v[176:179], v[80:83]
	v_mfma_f32_16x16x32_bf16 v[68:71], v[144:147], v[184:187], v[68:71]
	v_mfma_f32_16x16x32_bf16 v[64:67], v[152:155], v[184:187], v[64:67]
	v_mfma_f32_16x16x32_bf16 v[116:119], v[148:151], v[164:167], v[116:119]
	v_mfma_f32_16x16x32_bf16 v[112:115], v[156:159], v[164:167], v[112:115]
	v_mfma_f32_16x16x32_bf16 v[100:103], v[148:151], v[172:175], v[100:103]
	v_mfma_f32_16x16x32_bf16 v[96:99], v[156:159], v[172:175], v[96:99]
	v_mfma_f32_16x16x32_bf16 v[84:87], v[148:151], v[180:183], v[84:87]
	v_mfma_f32_16x16x32_bf16 v[80:83], v[156:159], v[180:183], v[80:83]
	v_mfma_f32_16x16x32_bf16 v[68:71], v[148:151], v[222:225], v[68:71]
	v_mfma_f32_16x16x32_bf16 v[64:67], v[156:159], v[222:225], v[64:67]
	s_barrier
; #define PG8_STAGE(bufoff, gbase, voff) do { _Pragma("unroll") for (int _i = 0; _i < 2; ++_i) \
;         __builtin_amdgcn_global_load_lds((const unsigned*)((const char*)(gbase) + (voff)[_i]), (PG8_LAS unsigned*)(lds + (bufoff) + ldsw + _i * 8192), 16, 0, 0); } while (0)
; #define PG8_LDA(dst, b, h) do { _Pragma("unroll") for (int m = 0; m < 4; ++m) _Pragma("unroll") for (int k = 0; k < 2; ++k) dst[m][k] = *(const PG8_LAS bf16x8*)(lds + PG8_SA(b, h) + aoff + m * 2048 + k * 1024); } while (0)
; #define PG8_MMA(ai, bj, At, Bt) do { __builtin_amdgcn_s_setprio(1); _Pragma("unroll") for (int m = 0; m < 4; ++m) _Pragma("unroll") for (int n = 0; n < 2; ++n) _Pragma("unroll") for (int k = 0; k < 2; ++k) \
;         acc[ai][bj][m][n] = __builtin_amdgcn_mfma_f32_16x16x32_bf16(Bt[n][k], At[m][k], acc[ai][bj][m][n], 0, 0, 0); __builtin_amdgcn_s_setprio(0); } while (0)
; #define PG8_WAIT_V(n) asm volatile("s_waitcnt vmcnt(" #n ")" ::: "memory")
; #define PG8_WAIT_L(n) asm volatile("s_waitcnt lgkmcnt(" #n ")" ::: "memory")
; #define PG8_BAR __builtin_amdgcn_s_barrier()
; #define PG8_SCHED __builtin_amdgcn_sched_barrier(0)
; template <class Epi>
; __device__ __forceinline__ void gemm_phase(PG8_LAS unsigned char* lds, PG8_LAS unsigned char* xl, const Gemm g, const Sched& S, const Epi& E, const int wid) {
;     ...
;             PG8_LDA(At, 1, 1); PG8_STAGE(PG8_SB(1, 0), b3, voffB); PG8_STAGE(PG8_SB(1, 1), b3 + hstepB, voffB); PG8_STAGE(PG8_SA(1, 0), a3, voffA);
;             PG8_WAIT_V(8); PG8_WAIT_L(0); PG8_BAR; if (do1) { PG8_MMA(1, 0, At, B0); PG8_MMA(1, 1, At, B1); } PG8_BAR; PG8_SCHED;
;         }
	s_setprio 0
	s_add_i32 s4, s4, s29
	s_mov_b32 m0, s4
	ds_read_b128 v[160:163], v220 offset:49152
	ds_read_b128 v[164:167], v220 offset:50176
	ds_read_b128 v[168:171], v220 offset:51200
	ds_read_b128 v[172:175], v220 offset:52224
	ds_read_b128 v[176:179], v220 offset:53248
	ds_read_b128 v[180:183], v220 offset:54272
	ds_read_b128 v[184:187], v220 offset:55296
	ds_read_b128 v[222:225], v220 offset:56320
	global_load_lds_dwordx4 v205, s[40:41]
	s_add_i32 m0, s4, 0x2000
	s_add_u32 s100, s40, 0x160080
	global_load_lds_dwordx4 v219, s[40:41]
	s_addc_u32 s101, s41, 0
	s_add_i32 s4, s5, s29
	s_mov_b32 m0, s4
	s_nop 0
	global_load_lds_dwordx4 v190, s[100:101]
	s_add_i32 m0, s4, 0x2000
	s_nop 0
	global_load_lds_dwordx4 v212, s[100:101]
	s_mov_b32 m0, s61
	s_nop 0
	global_load_lds_dwordx4 v204, s[10:11]
	s_mov_b32 m0, s62
	s_nop 0
	global_load_lds_dwordx4 v218, s[10:11]
	s_waitcnt vmcnt(8)
	s_waitcnt lgkmcnt(0)
	s_setprio 1
	s_barrier
	v_mfma_f32_16x16x32_bf16 v[60:63], v[120:123], v[160:163], v[60:63]
	v_mfma_f32_16x16x32_bf16 v[56:59], v[128:131], v[160:163], v[56:59]
	v_mfma_f32_16x16x32_bf16 v[44:47], v[120:123], v[168:171], v[44:47]
	v_mfma_f32_16x16x32_bf16 v[40:43], v[128:131], v[168:171], v[40:43]
	v_mfma_f32_16x16x32_bf16 v[28:31], v[120:123], v[176:179], v[28:31]
	v_mfma_f32_16x16x32_bf16 v[24:27], v[128:131], v[176:179], v[24:27]
	v_mfma_f32_16x16x32_bf16 v[12:15], v[120:123], v[184:187], v[12:15]
	v_mfma_f32_16x16x32_bf16 v[8:11], v[128:131], v[184:187], v[8:11]
	v_mfma_f32_16x16x32_bf16 v[60:63], v[124:127], v[164:167], v[60:63]
	v_mfma_f32_16x16x32_bf16 v[56:59], v[136:139], v[164:167], v[56:59]
	v_mfma_f32_16x16x32_bf16 v[44:47], v[124:127], v[172:175], v[44:47]
	v_mfma_f32_16x16x32_bf16 v[40:43], v[136:139], v[172:175], v[40:43]
	v_mfma_f32_16x16x32_bf16 v[28:31], v[124:127], v[180:183], v[28:31]
	v_mfma_f32_16x16x32_bf16 v[24:27], v[136:139], v[180:183], v[24:27]
	v_mfma_f32_16x16x32_bf16 v[12:15], v[124:127], v[222:225], v[12:15]
	v_mfma_f32_16x16x32_bf16 v[8:11], v[136:139], v[222:225], v[8:11]
	s_setprio 0
	s_setprio 1
	v_mfma_f32_16x16x32_bf16 v[52:55], v[144:147], v[160:163], v[52:55]
	v_mfma_f32_16x16x32_bf16 v[48:51], v[152:155], v[160:163], v[48:51]
	v_mfma_f32_16x16x32_bf16 v[36:39], v[144:147], v[168:171], v[36:39]
	v_mfma_f32_16x16x32_bf16 v[32:35], v[152:155], v[168:171], v[32:35]
	v_mfma_f32_16x16x32_bf16 v[20:23], v[144:147], v[176:179], v[20:23]
	v_mfma_f32_16x16x32_bf16 v[16:19], v[152:155], v[176:179], v[16:19]
	v_mfma_f32_16x16x32_bf16 v[4:7], v[144:147], v[184:187], v[4:7]
	v_mfma_f32_16x16x32_bf16 v[0:3], v[152:155], v[184:187], v[0:3]
	v_mfma_f32_16x16x32_bf16 v[52:55], v[148:151], v[164:167], v[52:55]
	v_mfma_f32_16x16x32_bf16 v[48:51], v[156:159], v[164:167], v[48:51]
	v_mfma_f32_16x16x32_bf16 v[36:39], v[148:151], v[172:175], v[36:39]
	v_mfma_f32_16x16x32_bf16 v[32:35], v[156:159], v[172:175], v[32:35]
	v_mfma_f32_16x16x32_bf16 v[20:23], v[148:151], v[180:183], v[20:23]
	v_mfma_f32_16x16x32_bf16 v[16:19], v[156:159], v[180:183], v[16:19]
	v_mfma_f32_16x16x32_bf16 v[4:7], v[148:151], v[222:225], v[4:7]
	v_mfma_f32_16x16x32_bf16 v[0:3], v[156:159], v[222:225], v[0:3]
	s_barrier
	s_setprio 0
	s_add_i32 s9, s9, 2
	s_add_u32 s36, s36, 0x100
	s_addc_u32 s37, s37, 0
	s_add_u32 s1, s1, 0x100
	s_addc_u32 s8, s8, 0
	s_cmpk_gt_u32 s9, 0x55
